# GEMM units: first K-loop trip peeled with C=0 MFMAs instead of 127 accumulator-zeroing moves (five GEMMs)
# speedup vs baseline: 1.0099x; 1.0058x over previous
; #define PG8_STAGE(bufoff, gbase, voff) do { _Pragma("unroll") for (int _i = 0; _i < 2; ++_i) \
;         __builtin_amdgcn_global_load_lds((const unsigned*)((const char*)(gbase) + (voff)[_i]), (LAS unsigned*)(lds + (bufoff) + ldsw + _i * 8192), 16, 0, 0); } while (0)
; #define PG8_LDA(dst, b, h) do { _Pragma("unroll") for (int m = 0; m < 4; ++m) _Pragma("unroll") for (int k = 0; k < 2; ++k) dst[m][k] = *(const LAS bf16x8*)(lds + PG8_SA(b, h) + aoff + m * 2048 + k * 1024); } while (0)
; #define PG8_LDB(dst, b, h) do { _Pragma("unroll") for (int n = 0; n < 2; ++n) _Pragma("unroll") for (int k = 0; k < 2; ++k) dst[n][k] = *(const LAS bf16x8*)(lds + PG8_SB(b, h) + boff + n * 2048 + k * 1024); } while (0)
; #define PG8_MMA(ai, bj, At, Bt) do { __builtin_amdgcn_s_setprio(1); _Pragma("unroll") for (int m = 0; m < 4; ++m) _Pragma("unroll") for (int n = 0; n < 2; ++n) _Pragma("unroll") for (int k = 0; k < 2; ++k) \
;         acc[ai][bj][m][n] = __builtin_amdgcn_mfma_f32_16x16x32_bf16(Bt[n][k], At[m][k], acc[ai][bj][m][n], 0, 0, 0); __builtin_amdgcn_s_setprio(0); } while (0)
; #define PG8_BAR __builtin_amdgcn_s_barrier()
; template <class Epi>
; DEVI void gemm_phase(const int wv, LAS unsigned char* lds, const Gemm g, const Order& S, const Epi& E) {
;     ...
;         const bool has_next = S.next(ui + 1, nxt);
;         const char* nA = has_next ? (const char*)g.A + (size_t)nxt.pb * g.a_bs + (size_t)nxt.pm * tstepA : cA;
;         const char* nB = has_next ? (const char*)g.Bt + (size_t)nxt.pb * g.b_bs + (size_t)nxt.pn * tstepB : cB;
;         for (int t = 0; t < nt; t += 2) {
;             const bool last = (t == nt - 2);
;             const char* a1 = cA + (size_t)(t + 1) * kstep;
;             const char* a2 = last ? nA : cA + (size_t)(t + 2) * kstep; const char* b2 = last ? nB : cB + (size_t)(t + 2) * kstep;
;             const char* a3 = a2 + kstep; const char* b3 = b2 + kstep;
;             PG8_LDB(B0, 0, 0); PG8_SCHED; PG8_LDA(At, 0, 0); PG8_STAGE(PG8_SA(1, 1), a1 + hstepA, voffA);
;             PG8_WAIT_L(8); PG8_BAR; PG8_WAIT_L(0); PG8_MMA(0, 0, At, B0); PG8_BAR; PG8_SCHED;
;             PG8_LDB(B1, 0, 1); PG8_STAGE(PG8_SB(0, 0), b2, voffB);
;             PG8_BAR; PG8_WAIT_L(0); PG8_MMA(0, 1, At, B1); PG8_BAR;
;             PG8_LDA(At, 0, 1); PG8_STAGE(PG8_SA(0, 0), a2, voffA);
;             PG8_BAR; PG8_WAIT_L(0); PG8_MMA(1, 0, At, B0); PG8_BAR; PG8_SCHED;
.LBB0_286:
	s_ashr_i32 s7, s6, 31
	s_xor_b64 s[10:11], s[36:37], -1
	s_lshl_b64 s[8:9], s[6:7], 19
	s_add_u32 s8, s14, s8
	s_addc_u32 s9, s15, s9
	s_and_b64 s[12:13], s[36:37], exec
	s_cselect_b32 s7, s9, s29
	s_cselect_b32 s56, s8, s28
	s_ashr_i32 s5, s4, 31
	s_lshl_b64 s[12:13], s[4:5], 19
	v_readlane_b32 s58, v250, 25
	v_readlane_b32 s59, v250, 26
	s_add_u32 s12, s58, s12
	s_addc_u32 s13, s59, s13
	s_and_b64 s[36:37], s[36:37], exec
	s_cselect_b32 s5, s13, s31
	s_cselect_b32 s57, s12, s30
	s_add_u32 s28, s28, 0x40080
	s_addc_u32 s29, s29, 0
	s_add_u32 s58, s30, 0x100
	v_mov_b32_e32 v2, 0
	s_addc_u32 s59, s31, 0
	s_mov_b32 s60, -2
	s_waitcnt lgkmcnt(0)
	s_add_u32 s30, s28, 0xfffc0080
	s_addc_u32 s31, s29, -1
	s_add_i32 s61, 0, 0x10000
	v_add_u32_e32 v156, s61, v145
	ds_read_b128 v[140:143], v156
	ds_read_b128 v[148:151], v156 offset:1024
	ds_read_b128 v[152:155], v156 offset:2048
	ds_read_b128 v[156:159], v156 offset:3072
	s_cmp_eq_u32 s60, 12
	s_cselect_b32 s37, s7, s31
	s_cselect_b32 s36, s56, s30
	s_cselect_b32 s31, s5, s59
	s_cselect_b32 s30, s57, s58
	v_lshl_add_u64 v[192:193], s[28:29], 0, v[136:137]
	s_add_i32 m0, s1, 0xc000
	ds_read_b128 v[160:163], v147
	ds_read_b128 v[164:167], v147 offset:1024
	ds_read_b128 v[168:171], v147 offset:2048
	ds_read_b128 v[172:175], v147 offset:3072
	ds_read_b128 v[176:179], v147 offset:4096
	ds_read_b128 v[180:183], v147 offset:5120
	ds_read_b128 v[184:187], v147 offset:6144
	ds_read_b128 v[188:191], v147 offset:7168
	global_load_lds_dwordx4 v[192:193], off
	v_lshl_add_u64 v[192:193], s[28:29], 0, v[138:139]
	s_add_i32 m0, s1, 0xe000
	s_nop 0
	global_load_lds_dwordx4 v[192:193], off
	s_waitcnt lgkmcnt(8)
	s_barrier
	s_waitcnt lgkmcnt(0)
	s_setprio 1
	s_waitcnt lgkmcnt(0)
	v_mfma_f32_16x16x32_bf16 v[126:129], v[140:143], v[160:163], 0
	v_mfma_f32_16x16x32_bf16 v[122:125], v[152:155], v[160:163], 0
	v_mfma_f32_16x16x32_bf16 v[118:121], v[140:143], v[168:171], 0
	v_mfma_f32_16x16x32_bf16 v[110:113], v[152:155], v[168:171], 0
	v_mfma_f32_16x16x32_bf16 v[102:105], v[140:143], v[176:179], 0
	v_mfma_f32_16x16x32_bf16 v[94:97], v[152:155], v[176:179], 0
	v_mfma_f32_16x16x32_bf16 v[86:89], v[140:143], v[184:187], 0
	v_mfma_f32_16x16x32_bf16 v[78:81], v[152:155], v[184:187], 0
	v_mfma_f32_16x16x32_bf16 v[126:129], v[148:151], v[164:167], v[126:129]
	v_mfma_f32_16x16x32_bf16 v[122:125], v[156:159], v[164:167], v[122:125]
	v_mfma_f32_16x16x32_bf16 v[118:121], v[148:151], v[172:175], v[118:121]
	v_mfma_f32_16x16x32_bf16 v[110:113], v[156:159], v[172:175], v[110:113]
	v_mfma_f32_16x16x32_bf16 v[102:105], v[148:151], v[180:183], v[102:105]
	v_mfma_f32_16x16x32_bf16 v[94:97], v[156:159], v[180:183], v[94:97]
	v_mfma_f32_16x16x32_bf16 v[86:89], v[148:151], v[188:191], v[86:89]
	v_mfma_f32_16x16x32_bf16 v[78:81], v[156:159], v[188:191], v[78:81]
	s_setprio 0
	s_barrier
	s_add_i32 s64, 0, 0x14000
	s_add_i32 s61, s61, s95
	v_add_u32_e32 v199, s64, v145
	v_lshl_add_u64 v[212:213], s[30:31], 0, v[0:1]
	s_mov_b32 m0, s61
	ds_read_b128 v[192:195], v199
	ds_read_b128 v[200:203], v199 offset:1024
	ds_read_b128 v[204:207], v199 offset:2048
	ds_read_b128 v[208:211], v199 offset:3072
	global_load_lds_dwordx4 v[212:213], off
	v_lshl_add_u64 v[214:215], s[30:31], 0, v[134:135]
	s_add_i32 m0, s61, 0x2000
	s_nop 0
	global_load_lds_dwordx4 v[214:215], off
	s_barrier
	s_waitcnt lgkmcnt(0)
	s_setprio 1
	s_waitcnt lgkmcnt(0)
	v_mfma_f32_16x16x32_bf16 v[114:117], v[192:195], v[160:163], 0
	v_mfma_f32_16x16x32_bf16 v[106:109], v[204:207], v[160:163], 0
	v_mfma_f32_16x16x32_bf16 v[98:101], v[192:195], v[168:171], 0
	v_mfma_f32_16x16x32_bf16 v[90:93], v[204:207], v[168:171], 0
	v_mfma_f32_16x16x32_bf16 v[82:85], v[192:195], v[176:179], 0
	v_mfma_f32_16x16x32_bf16 v[74:77], v[204:207], v[176:179], 0
	v_mfma_f32_16x16x32_bf16 v[70:73], v[192:195], v[184:187], 0
	v_mfma_f32_16x16x32_bf16 v[66:69], v[204:207], v[184:187], 0
	v_mfma_f32_16x16x32_bf16 v[114:117], v[200:203], v[164:167], v[114:117]
	v_mfma_f32_16x16x32_bf16 v[106:109], v[208:211], v[164:167], v[106:109]
	v_mfma_f32_16x16x32_bf16 v[98:101], v[200:203], v[172:175], v[98:101]
	v_mfma_f32_16x16x32_bf16 v[90:93], v[208:211], v[172:175], v[90:93]
	v_mfma_f32_16x16x32_bf16 v[82:85], v[200:203], v[180:183], v[82:85]
	v_mfma_f32_16x16x32_bf16 v[74:77], v[208:211], v[180:183], v[74:77]
	v_mfma_f32_16x16x32_bf16 v[70:73], v[200:203], v[188:191], v[70:73]
	v_mfma_f32_16x16x32_bf16 v[66:69], v[208:211], v[188:191], v[66:69]
	s_setprio 0
	s_mov_b32 m0, s1
	v_lshl_add_u64 v[216:217], s[36:37], 0, v[130:131]
	s_barrier
	ds_read_b128 v[160:163], v147 offset:16384
	ds_read_b128 v[164:167], v147 offset:17408
	ds_read_b128 v[168:171], v147 offset:18432
	ds_read_b128 v[172:175], v147 offset:19456
	ds_read_b128 v[176:179], v147 offset:20480
	ds_read_b128 v[180:183], v147 offset:21504
	ds_read_b128 v[184:187], v147 offset:22528
	ds_read_b128 v[188:191], v147 offset:23552
	global_load_lds_dwordx4 v[216:217], off
	v_lshl_add_u64 v[218:219], s[36:37], 0, v[132:133]
	s_mov_b32 m0, s3
	s_nop 0
	global_load_lds_dwordx4 v[218:219], off
	s_barrier
	s_waitcnt lgkmcnt(0)
	s_setprio 1
	s_waitcnt lgkmcnt(0)
	v_mfma_f32_16x16x32_bf16 v[62:65], v[140:143], v[160:163], 0
	v_mfma_f32_16x16x32_bf16 v[58:61], v[152:155], v[160:163], 0
	v_mfma_f32_16x16x32_bf16 v[54:57], v[140:143], v[168:171], 0
	v_mfma_f32_16x16x32_bf16 v[46:49], v[152:155], v[168:171], 0
	v_mfma_f32_16x16x32_bf16 v[38:41], v[140:143], v[176:179], 0
	v_mfma_f32_16x16x32_bf16 v[30:33], v[152:155], v[176:179], 0
	v_mfma_f32_16x16x32_bf16 v[22:25], v[140:143], v[184:187], 0
	v_mfma_f32_16x16x32_bf16 v[14:17], v[152:155], v[184:187], 0
	v_mfma_f32_16x16x32_bf16 v[62:65], v[148:151], v[164:167], v[62:65]
	v_mfma_f32_16x16x32_bf16 v[58:61], v[156:159], v[164:167], v[58:61]
	v_mfma_f32_16x16x32_bf16 v[54:57], v[148:151], v[172:175], v[54:57]
	v_mfma_f32_16x16x32_bf16 v[46:49], v[156:159], v[172:175], v[46:49]
	v_mfma_f32_16x16x32_bf16 v[38:41], v[148:151], v[180:183], v[38:41]
	v_mfma_f32_16x16x32_bf16 v[30:33], v[156:159], v[180:183], v[30:33]
	v_mfma_f32_16x16x32_bf16 v[22:25], v[148:151], v[188:191], v[22:25]
	v_mfma_f32_16x16x32_bf16 v[14:17], v[156:159], v[188:191], v[14:17]
	s_setprio 0
	s_barrier
; #define PG8_STAGE(bufoff, gbase, voff) do { _Pragma("unroll") for (int _i = 0; _i < 2; ++_i) \
;         __builtin_amdgcn_global_load_lds((const unsigned*)((const char*)(gbase) + (voff)[_i]), (LAS unsigned*)(lds + (bufoff) + ldsw + _i * 8192), 16, 0, 0); } while (0)
; #define PG8_LDA(dst, b, h) do { _Pragma("unroll") for (int m = 0; m < 4; ++m) _Pragma("unroll") for (int k = 0; k < 2; ++k) dst[m][k] = *(const LAS bf16x8*)(lds + PG8_SA(b, h) + aoff + m * 2048 + k * 1024); } while (0)
; #define PG8_LDB(dst, b, h) do { _Pragma("unroll") for (int n = 0; n < 2; ++n) _Pragma("unroll") for (int k = 0; k < 2; ++k) dst[n][k] = *(const LAS bf16x8*)(lds + PG8_SB(b, h) + boff + n * 2048 + k * 1024); } while (0)
; #define PG8_MMA(ai, bj, At, Bt) do { __builtin_amdgcn_s_setprio(1); _Pragma("unroll") for (int m = 0; m < 4; ++m) _Pragma("unroll") for (int n = 0; n < 2; ++n) _Pragma("unroll") for (int k = 0; k < 2; ++k) \
;         acc[ai][bj][m][n] = __builtin_amdgcn_mfma_f32_16x16x32_bf16(Bt[n][k], At[m][k], acc[ai][bj][m][n], 0, 0, 0); __builtin_amdgcn_s_setprio(0); } while (0)
; #define PG8_WAIT_V(n) asm volatile("s_waitcnt vmcnt(" #n ")" ::: "memory")
; #define PG8_WAIT_L(n) asm volatile("s_waitcnt lgkmcnt(" #n ")" ::: "memory")
; #define PG8_BAR __builtin_amdgcn_s_barrier()
; #define PG8_SCHED __builtin_amdgcn_sched_barrier(0)
; template <class Epi>
; DEVI void gemm_phase(const int wv, LAS unsigned char* lds, const Gemm g, const Order& S, const Epi& E) {
;     ...
;             PG8_STAGE(PG8_SB(0, 1), b2 + hstepB, voffB);
;             PG8_WAIT_V(6); PG8_BAR; PG8_MMA(1, 1, At, B1); PG8_BAR;
;             PG8_LDB(B0, 1, 0); PG8_SCHED; PG8_LDA(At, 1, 0); PG8_STAGE(PG8_SA(0, 1), a2 + hstepA, voffA);
;             PG8_WAIT_L(8); PG8_BAR; PG8_WAIT_L(0); PG8_MMA(0, 0, At, B0); PG8_BAR; PG8_SCHED;
;             PG8_LDB(B1, 1, 1); PG8_STAGE(PG8_SB(1, 0), b3, voffB);
;             PG8_BAR; PG8_WAIT_L(0); PG8_MMA(0, 1, At, B1); PG8_BAR;
;             PG8_LDA(At, 1, 1); PG8_STAGE(PG8_SA(1, 0), a3, voffA);
;             PG8_BAR; PG8_WAIT_L(0); PG8_MMA(1, 0, At, B0); PG8_BAR; PG8_SCHED;
	s_add_u32 s62, s30, 0x40000
	s_addc_u32 s63, s31, 0
	s_add_i32 s61, s64, s95
	v_lshl_add_u64 v[140:141], s[62:63], 0, v[0:1]
	s_mov_b32 m0, s61
	s_nop 0
	global_load_lds_dwordx4 v[140:141], off
	v_lshl_add_u64 v[140:141], s[62:63], 0, v[134:135]
	s_add_i32 m0, s61, 0x2000
	s_nop 0
	global_load_lds_dwordx4 v[140:141], off
	s_waitcnt vmcnt(6)
	s_barrier
	s_setprio 1
	v_mfma_f32_16x16x32_bf16 v[50:53], v[192:195], v[160:163], 0
	v_mfma_f32_16x16x32_bf16 v[42:45], v[204:207], v[160:163], 0
	v_mfma_f32_16x16x32_bf16 v[34:37], v[192:195], v[168:171], 0
	v_mfma_f32_16x16x32_bf16 v[26:29], v[204:207], v[168:171], 0
	v_mfma_f32_16x16x32_bf16 v[18:21], v[192:195], v[176:179], 0
	v_mfma_f32_16x16x32_bf16 v[10:13], v[204:207], v[176:179], 0
	v_mfma_f32_16x16x32_bf16 v[6:9], v[192:195], v[184:187], 0
	v_mfma_f32_16x16x32_bf16 v[2:5], v[204:207], v[184:187], 0
	v_mfma_f32_16x16x32_bf16 v[50:53], v[200:203], v[164:167], v[50:53]
	v_mfma_f32_16x16x32_bf16 v[42:45], v[208:211], v[164:167], v[42:45]
	v_mfma_f32_16x16x32_bf16 v[34:37], v[200:203], v[172:175], v[34:37]
	v_mfma_f32_16x16x32_bf16 v[26:29], v[208:211], v[172:175], v[26:29]
	v_mfma_f32_16x16x32_bf16 v[18:21], v[200:203], v[180:183], v[18:21]
	v_mfma_f32_16x16x32_bf16 v[10:13], v[208:211], v[180:183], v[10:13]
	v_mfma_f32_16x16x32_bf16 v[6:9], v[200:203], v[188:191], v[6:9]
	v_mfma_f32_16x16x32_bf16 v[2:5], v[208:211], v[188:191], v[2:5]
	s_setprio 0
	s_add_i32 s61, 0, 0x18000
	v_add_u32_e32 v156, s61, v145
	s_barrier
	ds_read_b128 v[140:143], v156
	ds_read_b128 v[148:151], v156 offset:1024
	ds_read_b128 v[152:155], v156 offset:2048
	ds_read_b128 v[156:159], v156 offset:3072
	s_add_u32 s36, s36, 0x40000
	s_addc_u32 s37, s37, 0
	s_mov_b32 m0, s41
	v_lshl_add_u64 v[192:193], s[36:37], 0, v[130:131]
	ds_read_b128 v[160:163], v147 offset:32768
	ds_read_b128 v[164:167], v147 offset:33792
	ds_read_b128 v[168:171], v147 offset:34816
	ds_read_b128 v[172:175], v147 offset:35840
	ds_read_b128 v[176:179], v147 offset:36864
	ds_read_b128 v[180:183], v147 offset:37888
	ds_read_b128 v[184:187], v147 offset:38912
	ds_read_b128 v[188:191], v147 offset:39936
	global_load_lds_dwordx4 v[192:193], off
	v_lshl_add_u64 v[192:193], s[36:37], 0, v[132:133]
	s_mov_b32 m0, s50
	s_nop 0
	global_load_lds_dwordx4 v[192:193], off
	s_waitcnt lgkmcnt(8)
	s_barrier
	s_waitcnt lgkmcnt(0)
	s_setprio 1
	s_waitcnt lgkmcnt(0)
	v_mfma_f32_16x16x32_bf16 v[126:129], v[140:143], v[160:163], v[126:129]
	v_mfma_f32_16x16x32_bf16 v[122:125], v[152:155], v[160:163], v[122:125]
	v_mfma_f32_16x16x32_bf16 v[118:121], v[140:143], v[168:171], v[118:121]
	v_mfma_f32_16x16x32_bf16 v[110:113], v[152:155], v[168:171], v[110:113]
	v_mfma_f32_16x16x32_bf16 v[102:105], v[140:143], v[176:179], v[102:105]
	v_mfma_f32_16x16x32_bf16 v[94:97], v[152:155], v[176:179], v[94:97]
	v_mfma_f32_16x16x32_bf16 v[86:89], v[140:143], v[184:187], v[86:89]
	v_mfma_f32_16x16x32_bf16 v[78:81], v[152:155], v[184:187], v[78:81]
	v_mfma_f32_16x16x32_bf16 v[126:129], v[148:151], v[164:167], v[126:129]
	v_mfma_f32_16x16x32_bf16 v[122:125], v[156:159], v[164:167], v[122:125]
	v_mfma_f32_16x16x32_bf16 v[118:121], v[148:151], v[172:175], v[118:121]
	v_mfma_f32_16x16x32_bf16 v[110:113], v[156:159], v[172:175], v[110:113]
	v_mfma_f32_16x16x32_bf16 v[102:105], v[148:151], v[180:183], v[102:105]
	v_mfma_f32_16x16x32_bf16 v[94:97], v[156:159], v[180:183], v[94:97]
	v_mfma_f32_16x16x32_bf16 v[86:89], v[148:151], v[188:191], v[86:89]
	v_mfma_f32_16x16x32_bf16 v[78:81], v[156:159], v[188:191], v[78:81]
	s_setprio 0
	s_barrier
	s_add_i32 s36, 0, 0x1c000
	s_add_i32 s37, s61, s95
	v_add_u32_e32 v199, s36, v145
	v_lshl_add_u64 v[212:213], v[212:213], 0, s[92:93]
	s_mov_b32 m0, s37
	ds_read_b128 v[192:195], v199
	ds_read_b128 v[200:203], v199 offset:1024
	ds_read_b128 v[204:207], v199 offset:2048
	ds_read_b128 v[208:211], v199 offset:3072
	global_load_lds_dwordx4 v[212:213], off
	v_lshl_add_u64 v[212:213], v[214:215], 0, s[92:93]
	s_add_i32 m0, s37, 0x2000
	s_nop 0
	global_load_lds_dwordx4 v[212:213], off
	s_barrier
; #define PG8_STAGE(bufoff, gbase, voff) do { _Pragma("unroll") for (int _i = 0; _i < 2; ++_i) \
;         __builtin_amdgcn_global_load_lds((const unsigned*)((const char*)(gbase) + (voff)[_i]), (LAS unsigned*)(lds + (bufoff) + ldsw + _i * 8192), 16, 0, 0); } while (0)
; #define PG8_LDA(dst, b, h) do { _Pragma("unroll") for (int m = 0; m < 4; ++m) _Pragma("unroll") for (int k = 0; k < 2; ++k) dst[m][k] = *(const LAS bf16x8*)(lds + PG8_SA(b, h) + aoff + m * 2048 + k * 1024); } while (0)
; #define PG8_LDB(dst, b, h) do { _Pragma("unroll") for (int n = 0; n < 2; ++n) _Pragma("unroll") for (int k = 0; k < 2; ++k) dst[n][k] = *(const LAS bf16x8*)(lds + PG8_SB(b, h) + boff + n * 2048 + k * 1024); } while (0)
; #define PG8_MMA(ai, bj, At, Bt) do { __builtin_amdgcn_s_setprio(1); _Pragma("unroll") for (int m = 0; m < 4; ++m) _Pragma("unroll") for (int n = 0; n < 2; ++n) _Pragma("unroll") for (int k = 0; k < 2; ++k) \
;         acc[ai][bj][m][n] = __builtin_amdgcn_mfma_f32_16x16x32_bf16(Bt[n][k], At[m][k], acc[ai][bj][m][n], 0, 0, 0); __builtin_amdgcn_s_setprio(0); } while (0)
; #define PG8_WAIT_V(n) asm volatile("s_waitcnt vmcnt(" #n ")" ::: "memory")
; #define PG8_WAIT_L(n) asm volatile("s_waitcnt lgkmcnt(" #n ")" ::: "memory")
; #define PG8_BAR __builtin_amdgcn_s_barrier()
; #define PG8_SCHED __builtin_amdgcn_sched_barrier(0)
; template <class Epi>
; DEVI void gemm_phase(const int wv, LAS unsigned char* lds, const Gemm g, const Order& S, const Epi& E) {
;     ...
;         for (int t = 0; t < nt; t += 2) {
;     ...
;             PG8_LDB(B0, 1, 0); PG8_SCHED; PG8_LDA(At, 1, 0); PG8_STAGE(PG8_SA(0, 1), a2 + hstepA, voffA);
;             PG8_WAIT_L(8); PG8_BAR; PG8_WAIT_L(0); PG8_MMA(0, 0, At, B0); PG8_BAR; PG8_SCHED;
;             PG8_LDB(B1, 1, 1); PG8_STAGE(PG8_SB(1, 0), b3, voffB);
;             PG8_BAR; PG8_WAIT_L(0); PG8_MMA(0, 1, At, B1); PG8_BAR;
;             PG8_LDA(At, 1, 1); PG8_STAGE(PG8_SA(1, 0), a3, voffA);
;             PG8_BAR; PG8_WAIT_L(0); PG8_MMA(1, 0, At, B0); PG8_BAR; PG8_SCHED;
;             PG8_STAGE(PG8_SB(1, 1), b3 + hstepB, voffB);
;             PG8_WAIT_V(6); PG8_BAR; PG8_MMA(1, 1, At, B1); PG8_BAR;
	s_waitcnt lgkmcnt(0)
	s_setprio 1
	s_waitcnt lgkmcnt(0)
	v_mfma_f32_16x16x32_bf16 v[114:117], v[192:195], v[160:163], v[114:117]
	v_mfma_f32_16x16x32_bf16 v[106:109], v[204:207], v[160:163], v[106:109]
	v_mfma_f32_16x16x32_bf16 v[98:101], v[192:195], v[168:171], v[98:101]
	v_mfma_f32_16x16x32_bf16 v[90:93], v[204:207], v[168:171], v[90:93]
	v_mfma_f32_16x16x32_bf16 v[82:85], v[192:195], v[176:179], v[82:85]
	v_mfma_f32_16x16x32_bf16 v[74:77], v[204:207], v[176:179], v[74:77]
	v_mfma_f32_16x16x32_bf16 v[70:73], v[192:195], v[184:187], v[70:73]
	v_mfma_f32_16x16x32_bf16 v[66:69], v[204:207], v[184:187], v[66:69]
	v_mfma_f32_16x16x32_bf16 v[114:117], v[200:203], v[164:167], v[114:117]
	v_mfma_f32_16x16x32_bf16 v[106:109], v[208:211], v[164:167], v[106:109]
	v_mfma_f32_16x16x32_bf16 v[98:101], v[200:203], v[172:175], v[98:101]
	v_mfma_f32_16x16x32_bf16 v[90:93], v[208:211], v[172:175], v[90:93]
	v_mfma_f32_16x16x32_bf16 v[82:85], v[200:203], v[180:183], v[82:85]
	v_mfma_f32_16x16x32_bf16 v[74:77], v[208:211], v[180:183], v[74:77]
	v_mfma_f32_16x16x32_bf16 v[70:73], v[200:203], v[188:191], v[70:73]
	v_mfma_f32_16x16x32_bf16 v[66:69], v[208:211], v[188:191], v[66:69]
	s_setprio 0
	s_mov_b32 m0, s51
	v_lshl_add_u64 v[212:213], v[216:217], 0, s[92:93]
	s_barrier
	ds_read_b128 v[160:163], v147 offset:49152
	ds_read_b128 v[164:167], v147 offset:50176
	ds_read_b128 v[168:171], v147 offset:51200
	ds_read_b128 v[172:175], v147 offset:52224
	ds_read_b128 v[176:179], v147 offset:53248
	ds_read_b128 v[180:183], v147 offset:54272
	ds_read_b128 v[184:187], v147 offset:55296
	ds_read_b128 v[188:191], v147 offset:56320
	global_load_lds_dwordx4 v[212:213], off
	v_lshl_add_u64 v[212:213], v[218:219], 0, s[92:93]
	s_mov_b32 m0, s52
	s_nop 0
	global_load_lds_dwordx4 v[212:213], off
	s_barrier
	s_waitcnt lgkmcnt(0)
	s_setprio 1
	s_waitcnt lgkmcnt(0)
	v_mfma_f32_16x16x32_bf16 v[62:65], v[140:143], v[160:163], v[62:65]
	v_mfma_f32_16x16x32_bf16 v[58:61], v[152:155], v[160:163], v[58:61]
	v_mfma_f32_16x16x32_bf16 v[54:57], v[140:143], v[168:171], v[54:57]
	v_mfma_f32_16x16x32_bf16 v[46:49], v[152:155], v[168:171], v[46:49]
	v_mfma_f32_16x16x32_bf16 v[38:41], v[140:143], v[176:179], v[38:41]
	v_mfma_f32_16x16x32_bf16 v[30:33], v[152:155], v[176:179], v[30:33]
	v_mfma_f32_16x16x32_bf16 v[22:25], v[140:143], v[184:187], v[22:25]
	v_mfma_f32_16x16x32_bf16 v[14:17], v[152:155], v[184:187], v[14:17]
	v_mfma_f32_16x16x32_bf16 v[62:65], v[148:151], v[164:167], v[62:65]
	v_mfma_f32_16x16x32_bf16 v[58:61], v[156:159], v[164:167], v[58:61]
	v_mfma_f32_16x16x32_bf16 v[54:57], v[148:151], v[172:175], v[54:57]
	v_mfma_f32_16x16x32_bf16 v[46:49], v[156:159], v[172:175], v[46:49]
	v_mfma_f32_16x16x32_bf16 v[38:41], v[148:151], v[180:183], v[38:41]
	v_mfma_f32_16x16x32_bf16 v[30:33], v[156:159], v[180:183], v[30:33]
	v_mfma_f32_16x16x32_bf16 v[22:25], v[148:151], v[188:191], v[22:25]
	v_mfma_f32_16x16x32_bf16 v[14:17], v[156:159], v[188:191], v[14:17]
	s_setprio 0
	s_barrier
	s_add_u32 s30, s30, 0x40080
	s_addc_u32 s31, s31, 0
	s_add_i32 s36, s36, s95
	v_lshl_add_u64 v[140:141], s[30:31], 0, v[0:1]
	s_mov_b32 m0, s36
	s_nop 0
	global_load_lds_dwordx4 v[140:141], off
	v_lshl_add_u64 v[140:141], s[30:31], 0, v[134:135]
	s_add_i32 m0, s36, 0x2000
	s_nop 0
	global_load_lds_dwordx4 v[140:141], off
	s_waitcnt vmcnt(6)
	s_barrier
	s_setprio 1
	v_mfma_f32_16x16x32_bf16 v[50:53], v[192:195], v[160:163], v[50:53]
	v_mfma_f32_16x16x32_bf16 v[42:45], v[204:207], v[160:163], v[42:45]
	v_mfma_f32_16x16x32_bf16 v[34:37], v[192:195], v[168:171], v[34:37]
	v_mfma_f32_16x16x32_bf16 v[26:29], v[204:207], v[168:171], v[26:29]
	v_mfma_f32_16x16x32_bf16 v[18:21], v[192:195], v[176:179], v[18:21]
	v_mfma_f32_16x16x32_bf16 v[10:13], v[204:207], v[176:179], v[10:13]
	v_mfma_f32_16x16x32_bf16 v[6:9], v[192:195], v[184:187], v[6:9]
	v_mfma_f32_16x16x32_bf16 v[2:5], v[204:207], v[184:187], v[2:5]
	v_mfma_f32_16x16x32_bf16 v[50:53], v[200:203], v[164:167], v[50:53]
	v_mfma_f32_16x16x32_bf16 v[42:45], v[208:211], v[164:167], v[42:45]
	v_mfma_f32_16x16x32_bf16 v[34:37], v[200:203], v[172:175], v[34:37]
	v_mfma_f32_16x16x32_bf16 v[26:29], v[208:211], v[172:175], v[26:29]
	v_mfma_f32_16x16x32_bf16 v[18:21], v[200:203], v[180:183], v[18:21]
	v_mfma_f32_16x16x32_bf16 v[10:13], v[208:211], v[180:183], v[10:13]
	v_mfma_f32_16x16x32_bf16 v[6:9], v[200:203], v[188:191], v[6:9]
	v_mfma_f32_16x16x32_bf16 v[2:5], v[208:211], v[188:191], v[2:5]
	s_setprio 0
	s_add_i32 s60, s60, 2
	s_add_u32 s28, s28, 0x100
	s_addc_u32 s29, s29, 0
	s_add_u32 s58, s58, 0x100
	s_addc_u32 s59, s59, 0
	s_cmp_gt_u32 s60, 13
	s_barrier
	s_cbranch_scc0 .LBB0_287
	s_branch .Lzp_epi_0

; DEVI unsigned cvt_pk_bf16(float lo, float hi) { unsigned r; asm volatile("v_cvt_pk_bf16_f32 %0, %1, %2" : "=v"(r) : "v"(lo), "v"(hi)); return r; }
; #define PG8_WAIT_V(n) asm volatile("s_waitcnt vmcnt(" #n ")" ::: "memory")
; #define PG8_BAR __builtin_amdgcn_s_barrier()
;     DEVI void operator()(f32x4 (&acc)[2][2][4][2], const Unit& u, int wr, int wc, int fr, int fq) const {
;     ...
;             for (int m = 0; m < 4; ++m) { bf16_t* rowp = O + (size_t)(row0 + ai * HALF + m * 16) * ldc + col0;
;                 float rstd = 1.0f; if (RS) rstd = rsqrtf(ssq[row0 + ai * HALF + m * 16] * (1.0f / 1024.0f) + EPS);
; #pragma unroll
;                 for (int bj = 0; bj < 2; ++bj) { f32x4 v0 = acc[ai][bj][m][0], v1 = acc[ai][bj][m][1];
;                     if (RS) { v0 = v0 * rstd + sh[bj][0]; v1 = v1 * rstd + sh[bj][1]; }
;                     if (ACT == 1) {
; #pragma unroll
;                         for (int j = 0; j < 4; ++j) { const float a = fmaxf(v0[j], 0.f), b = fmaxf(v1[j], 0.f); v0[j] = a * a; v1[j] = b * b; } }
;                     if (ACT == 2) {
; #pragma unroll
;                         for (int j = 0; j < 4; ++j) { v0[j] = 1.0f + __expf(-fminf(fmaxf(v0[j], -30.f), 30.f)); v1[j] = 1.0f + __expf(-fminf(fmaxf(v1[j], -30.f), 30.f)); } }
;                     u32x4 w; w.x = cvt_pk_bf16(v0[0], v0[1]); w.y = cvt_pk_bf16(v0[2], v0[3]); w.z = cvt_pk_bf16(v1[0], v1[1]); w.w = cvt_pk_bf16(v1[2], v1[3]);
;                     *(u32x4*)(rowp + bj * HALF) = w; } }
; template <class Epi>
; DEVI void gemm_phase(const int wv, LAS unsigned char* lds, const Gemm g, const Order& S, const Epi& E) {
;     ...
;         E(acc, cur, wr, wc, fr, fq);
;         if (!E.keep(cur)) {
; #pragma unroll
;             for (int a = 0; a < 2; ++a)
; #pragma unroll
;                 for (int b = 0; b < 2; ++b)
; #pragma unroll
;                     for (int m = 0; m < 4; ++m)
; #pragma unroll
;                         for (int n = 0; n < 2; ++n) acc[a][b][m][n] = (f32x4){0.f, 0.f, 0.f, 0.f};
;         }
;         if (!has_next) break;
;         cur = nxt; cA = nA; cB = nB; ++ui;
;     }
;     PG8_WAIT_V(0);
;     if (wr == 0) PG8_BAR;
;     PG8_BAR;
.Lzp_epi_0:
	v_lshl_or_b32 v142, s0, 8, v146
	v_lshl_add_u32 v150, s2, 8, v144
	v_ashrrev_i32_e32 v143, 31, v142
	v_mov_b64_e32 v[140:141], s[24:25]
	v_mad_i64_i32 v[148:149], s[28:29], v150, s46, v[140:141]
	v_lshlrev_b64 v[142:143], 1, v[142:143]
	v_lshl_add_u64 v[148:149], v[148:149], 0, v[142:143]
	v_cvt_pk_bf16_f32 v126, v126, v127
	v_cvt_pk_bf16_f32 v127, v128, v129
	v_cvt_pk_bf16_f32 v128, v122, v123
	v_cvt_pk_bf16_f32 v129, v124, v125
	global_store_dwordx4 v[148:149], v[126:129], off
	v_cvt_pk_bf16_f32 v114, v114, v115
	v_cvt_pk_bf16_f32 v115, v116, v117
	v_cvt_pk_bf16_f32 v116, v106, v107
	v_or_b32_e32 v106, 16, v150
	v_mad_i64_i32 v[106:107], s[28:29], v106, s46, v[140:141]
	v_cvt_pk_bf16_f32 v117, v108, v109
	global_store_dwordx4 v[148:149], v[114:117], off offset:256
	s_and_b64 vcc, exec, s[10:11]
	s_mov_b32 s0, s4
	v_lshl_add_u64 v[114:115], v[106:107], 0, v[142:143]
	v_cvt_pk_bf16_f32 v106, v118, v119
	v_cvt_pk_bf16_f32 v107, v120, v121
	v_cvt_pk_bf16_f32 v108, v110, v111
	v_cvt_pk_bf16_f32 v109, v112, v113
	global_store_dwordx4 v[114:115], v[106:109], off
	v_cvt_pk_bf16_f32 v98, v98, v99
	v_cvt_pk_bf16_f32 v99, v100, v101
	v_cvt_pk_bf16_f32 v100, v90, v91
	v_or_b32_e32 v90, 32, v150
	v_mad_i64_i32 v[90:91], s[28:29], v90, s46, v[140:141]
	v_cvt_pk_bf16_f32 v101, v92, v93
	global_store_dwordx4 v[114:115], v[98:101], off offset:256
	s_mov_b32 s2, s6
	s_mov_b64 s[30:31], s[12:13]
	v_lshl_add_u64 v[98:99], v[90:91], 0, v[142:143]
	v_cvt_pk_bf16_f32 v90, v102, v103
	v_cvt_pk_bf16_f32 v91, v104, v105
	v_cvt_pk_bf16_f32 v92, v94, v95
	v_cvt_pk_bf16_f32 v93, v96, v97
	global_store_dwordx4 v[98:99], v[90:93], off
	v_cvt_pk_bf16_f32 v82, v82, v83
	v_cvt_pk_bf16_f32 v83, v84, v85
	v_cvt_pk_bf16_f32 v84, v74, v75
	v_or_b32_e32 v74, 48, v150
	v_mad_i64_i32 v[74:75], s[28:29], v74, s46, v[140:141]
	v_cvt_pk_bf16_f32 v85, v76, v77
	global_store_dwordx4 v[98:99], v[82:85], off offset:256
	s_nop 1
	v_lshl_add_u64 v[82:83], v[74:75], 0, v[142:143]
	v_cvt_pk_bf16_f32 v74, v86, v87
	v_cvt_pk_bf16_f32 v75, v88, v89
	v_cvt_pk_bf16_f32 v76, v78, v79
	v_cvt_pk_bf16_f32 v77, v80, v81
	global_store_dwordx4 v[82:83], v[74:77], off
	v_cvt_pk_bf16_f32 v70, v70, v71
	v_cvt_pk_bf16_f32 v71, v72, v73
	v_cvt_pk_bf16_f32 v72, v66, v67
	v_add_u32_e32 v66, 0x80, v150
	v_mad_i64_i32 v[66:67], s[28:29], v66, s46, v[140:141]
	v_lshl_add_u64 v[66:67], v[66:67], 0, v[142:143]
	v_cvt_pk_bf16_f32 v73, v68, v69
	global_store_dwordx4 v[82:83], v[70:73], off offset:256
	v_cvt_pk_bf16_f32 v62, v62, v63
	v_cvt_pk_bf16_f32 v63, v64, v65
	v_cvt_pk_bf16_f32 v64, v58, v59
	v_cvt_pk_bf16_f32 v65, v60, v61
	global_store_dwordx4 v[66:67], v[62:65], off
	v_cvt_pk_bf16_f32 v50, v50, v51
	v_cvt_pk_bf16_f32 v51, v52, v53
	v_cvt_pk_bf16_f32 v52, v42, v43
	v_add_u32_e32 v42, 0x90, v150
	v_mad_i64_i32 v[42:43], s[28:29], v42, s46, v[140:141]
	v_cvt_pk_bf16_f32 v53, v44, v45
	global_store_dwordx4 v[66:67], v[50:53], off offset:256
	s_nop 1
	v_lshl_add_u64 v[50:51], v[42:43], 0, v[142:143]
	v_cvt_pk_bf16_f32 v42, v54, v55
	v_cvt_pk_bf16_f32 v43, v56, v57
	v_cvt_pk_bf16_f32 v44, v46, v47
	v_cvt_pk_bf16_f32 v45, v48, v49
	global_store_dwordx4 v[50:51], v[42:45], off
	v_cvt_pk_bf16_f32 v34, v34, v35
	v_cvt_pk_bf16_f32 v35, v36, v37
	v_cvt_pk_bf16_f32 v36, v26, v27
	v_add_u32_e32 v26, 0xa0, v150
	v_mad_i64_i32 v[26:27], s[28:29], v26, s46, v[140:141]
	v_cvt_pk_bf16_f32 v37, v28, v29
	global_store_dwordx4 v[50:51], v[34:37], off offset:256
	s_nop 1
	v_lshl_add_u64 v[34:35], v[26:27], 0, v[142:143]
	v_cvt_pk_bf16_f32 v26, v38, v39
	v_cvt_pk_bf16_f32 v27, v40, v41
	v_cvt_pk_bf16_f32 v28, v30, v31
	v_cvt_pk_bf16_f32 v29, v32, v33
	global_store_dwordx4 v[34:35], v[26:29], off
	v_cvt_pk_bf16_f32 v18, v18, v19
	v_cvt_pk_bf16_f32 v19, v20, v21
	v_cvt_pk_bf16_f32 v20, v10, v11
	v_add_u32_e32 v10, 0xb0, v150
	v_mad_i64_i32 v[10:11], s[28:29], v10, s46, v[140:141]
	v_cvt_pk_bf16_f32 v21, v12, v13
	global_store_dwordx4 v[34:35], v[18:21], off offset:256
	s_mov_b64 s[28:29], s[8:9]
	s_nop 0
	v_lshl_add_u64 v[18:19], v[10:11], 0, v[142:143]
	v_cvt_pk_bf16_f32 v10, v22, v23
	v_cvt_pk_bf16_f32 v11, v24, v25
	v_cvt_pk_bf16_f32 v12, v14, v15
	v_cvt_pk_bf16_f32 v13, v16, v17
	global_store_dwordx4 v[18:19], v[10:13], off
	v_cvt_pk_bf16_f32 v6, v6, v7
	v_cvt_pk_bf16_f32 v7, v8, v9
	v_cvt_pk_bf16_f32 v8, v2, v3
	v_cvt_pk_bf16_f32 v9, v4, v5
	global_store_dwordx4 v[18:19], v[6:9], off offset:256
	s_cbranch_vccz .LBB0_281
	v_readlane_b32 s0, v252, 13
	s_waitcnt vmcnt(0)
	v_readlane_b32 s1, v252, 14
	s_andn2_b64 vcc, exec, s[0:1]
	s_movk_i32 s55, 0xc00
	s_cbranch_vccnz .LBB0_291
	s_barrier

; #define PG8_STAGE(bufoff, gbase, voff) do { _Pragma("unroll") for (int _i = 0; _i < 2; ++_i) \
;         __builtin_amdgcn_global_load_lds((const unsigned*)((const char*)(gbase) + (voff)[_i]), (LAS unsigned*)(lds + (bufoff) + ldsw + _i * 8192), 16, 0, 0); } while (0)
; #define PG8_LDA(dst, b, h) do { _Pragma("unroll") for (int m = 0; m < 4; ++m) _Pragma("unroll") for (int k = 0; k < 2; ++k) dst[m][k] = *(const LAS bf16x8*)(lds + PG8_SA(b, h) + aoff + m * 2048 + k * 1024); } while (0)
; #define PG8_LDB(dst, b, h) do { _Pragma("unroll") for (int n = 0; n < 2; ++n) _Pragma("unroll") for (int k = 0; k < 2; ++k) dst[n][k] = *(const LAS bf16x8*)(lds + PG8_SB(b, h) + boff + n * 2048 + k * 1024); } while (0)
; #define PG8_MMA(ai, bj, At, Bt) do { __builtin_amdgcn_s_setprio(1); _Pragma("unroll") for (int m = 0; m < 4; ++m) _Pragma("unroll") for (int n = 0; n < 2; ++n) _Pragma("unroll") for (int k = 0; k < 2; ++k) \
;         acc[ai][bj][m][n] = __builtin_amdgcn_mfma_f32_16x16x32_bf16(Bt[n][k], At[m][k], acc[ai][bj][m][n], 0, 0, 0); __builtin_amdgcn_s_setprio(0); } while (0)
; template <class Epi>
; DEVI void gemm_phase(const int wv, LAS unsigned char* lds, const Gemm g, const Order& S, const Epi& E) {
;     ...
;     for (;;) {
;         const bool has_next = S.next(ui + 1, nxt);
;         const char* nA = has_next ? (const char*)g.A + (size_t)nxt.pb * g.a_bs + (size_t)nxt.pm * tstepA : cA;
;         const char* nB = has_next ? (const char*)g.Bt + (size_t)nxt.pb * g.b_bs + (size_t)nxt.pn * tstepB : cB;
;         for (int t = 0; t < nt; t += 2) {
;             const bool last = (t == nt - 2);
;             const char* a1 = cA + (size_t)(t + 1) * kstep;
;             const char* a2 = last ? nA : cA + (size_t)(t + 2) * kstep; const char* b2 = last ? nB : cB + (size_t)(t + 2) * kstep;
;             const char* a3 = a2 + kstep; const char* b3 = b2 + kstep;
;             PG8_LDB(B0, 0, 0); PG8_SCHED; PG8_LDA(At, 0, 0); PG8_STAGE(PG8_SA(1, 1), a1 + hstepA, voffA);
;             PG8_WAIT_L(8); PG8_BAR; PG8_WAIT_L(0); PG8_MMA(0, 0, At, B0); PG8_BAR; PG8_SCHED;
;             PG8_LDB(B1, 0, 1); PG8_STAGE(PG8_SB(0, 0), b2, voffB);
;             PG8_BAR; PG8_WAIT_L(0); PG8_MMA(0, 1, At, B1); PG8_BAR;
;             PG8_LDA(At, 0, 1); PG8_STAGE(PG8_SA(0, 0), a2, voffA);
;             PG8_BAR; PG8_WAIT_L(0); PG8_MMA(1, 0, At, B0); PG8_BAR; PG8_SCHED;
.LBB0_813:
	s_ashr_i32 s3, s2, 31
	s_xor_b64 s[6:7], s[36:37], -1
	s_lshl_b64 s[4:5], s[2:3], 19
	s_add_u32 s4, s14, s4
	s_addc_u32 s5, s15, s5
	s_and_b64 s[8:9], s[36:37], exec
	s_cselect_b32 s3, s5, s29
	s_cselect_b32 s53, s4, s28
	s_ashr_i32 s1, s0, 31
	s_lshl_b64 s[8:9], s[0:1], 19
	v_readlane_b32 s1, v252, 34
	s_add_u32 s8, s1, s8
	v_readlane_b32 s1, v252, 35
	s_addc_u32 s9, s1, s9
	s_and_b64 s[36:37], s[36:37], exec
	s_cselect_b32 s1, s9, s31
	s_cselect_b32 s54, s8, s30
	s_add_u32 s28, s28, 0x40080
	s_addc_u32 s29, s29, 0
	s_add_u32 s55, s30, 0x100
	v_mov_b32_e32 v2, 0
	s_addc_u32 s56, s31, 0
	s_mov_b32 s57, -2
	s_waitcnt lgkmcnt(0)
	s_add_u32 s30, s28, 0xfffc0080
	s_addc_u32 s31, s29, -1
	s_add_i32 s58, 0, 0x10000
	v_add_u32_e32 v156, s58, v145
	ds_read_b128 v[140:143], v156
	ds_read_b128 v[148:151], v156 offset:1024
	ds_read_b128 v[152:155], v156 offset:2048
	ds_read_b128 v[156:159], v156 offset:3072
	s_cmp_eq_u32 s57, 12
	s_cselect_b32 s37, s3, s31
	s_cselect_b32 s36, s53, s30
	s_cselect_b32 s31, s1, s56
	s_cselect_b32 s30, s54, s55
	v_lshl_add_u64 v[192:193], s[28:29], 0, v[136:137]
	s_add_i32 m0, s11, 0xc000
	ds_read_b128 v[160:163], v147
	ds_read_b128 v[164:167], v147 offset:1024
	ds_read_b128 v[168:171], v147 offset:2048
	ds_read_b128 v[172:175], v147 offset:3072
	ds_read_b128 v[176:179], v147 offset:4096
	ds_read_b128 v[180:183], v147 offset:5120
	ds_read_b128 v[184:187], v147 offset:6144
	ds_read_b128 v[188:191], v147 offset:7168
	global_load_lds_dwordx4 v[192:193], off
	v_lshl_add_u64 v[192:193], s[28:29], 0, v[138:139]
	s_add_i32 m0, s11, 0xe000
	s_nop 0
	global_load_lds_dwordx4 v[192:193], off
	s_waitcnt lgkmcnt(8)
	s_barrier
	s_waitcnt lgkmcnt(0)
	s_setprio 1
	s_waitcnt lgkmcnt(0)
	v_mfma_f32_16x16x32_bf16 v[126:129], v[140:143], v[160:163], 0
	v_mfma_f32_16x16x32_bf16 v[122:125], v[152:155], v[160:163], 0
	v_mfma_f32_16x16x32_bf16 v[110:113], v[140:143], v[168:171], 0
	v_mfma_f32_16x16x32_bf16 v[106:109], v[152:155], v[168:171], 0
	v_mfma_f32_16x16x32_bf16 v[94:97], v[140:143], v[176:179], 0
	v_mfma_f32_16x16x32_bf16 v[90:93], v[152:155], v[176:179], 0
	v_mfma_f32_16x16x32_bf16 v[78:81], v[140:143], v[184:187], 0
	v_mfma_f32_16x16x32_bf16 v[74:77], v[152:155], v[184:187], 0
	v_mfma_f32_16x16x32_bf16 v[126:129], v[148:151], v[164:167], v[126:129]
	v_mfma_f32_16x16x32_bf16 v[122:125], v[156:159], v[164:167], v[122:125]
	v_mfma_f32_16x16x32_bf16 v[110:113], v[148:151], v[172:175], v[110:113]
	v_mfma_f32_16x16x32_bf16 v[106:109], v[156:159], v[172:175], v[106:109]
	v_mfma_f32_16x16x32_bf16 v[94:97], v[148:151], v[180:183], v[94:97]
	v_mfma_f32_16x16x32_bf16 v[90:93], v[156:159], v[180:183], v[90:93]
	v_mfma_f32_16x16x32_bf16 v[78:81], v[148:151], v[188:191], v[78:81]
	v_mfma_f32_16x16x32_bf16 v[74:77], v[156:159], v[188:191], v[74:77]
	s_setprio 0
	s_barrier
	s_add_i32 s60, 0, 0x14000
	s_add_i32 s58, s58, s95
	v_add_u32_e32 v199, s60, v145
	v_lshl_add_u64 v[212:213], s[30:31], 0, v[0:1]
	s_mov_b32 m0, s58
	ds_read_b128 v[192:195], v199
	ds_read_b128 v[200:203], v199 offset:1024
	ds_read_b128 v[204:207], v199 offset:2048
	ds_read_b128 v[208:211], v199 offset:3072
	global_load_lds_dwordx4 v[212:213], off
	v_lshl_add_u64 v[214:215], s[30:31], 0, v[130:131]
	s_add_i32 m0, s58, 0x2000
	s_nop 0
	global_load_lds_dwordx4 v[214:215], off
	s_barrier
	s_waitcnt lgkmcnt(0)
	s_setprio 1
	s_waitcnt lgkmcnt(0)
	v_mfma_f32_16x16x32_bf16 v[118:121], v[192:195], v[160:163], 0
	v_mfma_f32_16x16x32_bf16 v[114:117], v[204:207], v[160:163], 0
	v_mfma_f32_16x16x32_bf16 v[102:105], v[192:195], v[168:171], 0
	v_mfma_f32_16x16x32_bf16 v[98:101], v[204:207], v[168:171], 0
	v_mfma_f32_16x16x32_bf16 v[86:89], v[192:195], v[176:179], 0
	v_mfma_f32_16x16x32_bf16 v[82:85], v[204:207], v[176:179], 0
	v_mfma_f32_16x16x32_bf16 v[70:73], v[192:195], v[184:187], 0
	v_mfma_f32_16x16x32_bf16 v[66:69], v[204:207], v[184:187], 0
	v_mfma_f32_16x16x32_bf16 v[118:121], v[200:203], v[164:167], v[118:121]
	v_mfma_f32_16x16x32_bf16 v[114:117], v[208:211], v[164:167], v[114:117]
	v_mfma_f32_16x16x32_bf16 v[102:105], v[200:203], v[172:175], v[102:105]
	v_mfma_f32_16x16x32_bf16 v[98:101], v[208:211], v[172:175], v[98:101]
	v_mfma_f32_16x16x32_bf16 v[86:89], v[200:203], v[180:183], v[86:89]
	v_mfma_f32_16x16x32_bf16 v[82:85], v[208:211], v[180:183], v[82:85]
	v_mfma_f32_16x16x32_bf16 v[70:73], v[200:203], v[188:191], v[70:73]
	v_mfma_f32_16x16x32_bf16 v[66:69], v[208:211], v[188:191], v[66:69]
	s_setprio 0
	s_mov_b32 m0, s11
	v_lshl_add_u64 v[216:217], s[36:37], 0, v[134:135]
	s_barrier
	ds_read_b128 v[160:163], v147 offset:16384
	ds_read_b128 v[164:167], v147 offset:17408
	ds_read_b128 v[168:171], v147 offset:18432
	ds_read_b128 v[172:175], v147 offset:19456
	ds_read_b128 v[176:179], v147 offset:20480
	ds_read_b128 v[180:183], v147 offset:21504
	ds_read_b128 v[184:187], v147 offset:22528
	ds_read_b128 v[188:191], v147 offset:23552
	global_load_lds_dwordx4 v[216:217], off
	v_lshl_add_u64 v[218:219], s[36:37], 0, v[132:133]
	s_mov_b32 m0, s13
	s_nop 0
	global_load_lds_dwordx4 v[218:219], off
	s_barrier
	s_waitcnt lgkmcnt(0)
	s_setprio 1
	s_waitcnt lgkmcnt(0)
	v_mfma_f32_16x16x32_bf16 v[62:65], v[140:143], v[160:163], 0
	v_mfma_f32_16x16x32_bf16 v[58:61], v[152:155], v[160:163], 0
	v_mfma_f32_16x16x32_bf16 v[46:49], v[140:143], v[168:171], 0
	v_mfma_f32_16x16x32_bf16 v[42:45], v[152:155], v[168:171], 0
	v_mfma_f32_16x16x32_bf16 v[30:33], v[140:143], v[176:179], 0
	v_mfma_f32_16x16x32_bf16 v[26:29], v[152:155], v[176:179], 0
	v_mfma_f32_16x16x32_bf16 v[14:17], v[140:143], v[184:187], 0
	v_mfma_f32_16x16x32_bf16 v[10:13], v[152:155], v[184:187], 0
	v_mfma_f32_16x16x32_bf16 v[62:65], v[148:151], v[164:167], v[62:65]
	v_mfma_f32_16x16x32_bf16 v[58:61], v[156:159], v[164:167], v[58:61]
	v_mfma_f32_16x16x32_bf16 v[46:49], v[148:151], v[172:175], v[46:49]
	v_mfma_f32_16x16x32_bf16 v[42:45], v[156:159], v[172:175], v[42:45]
	v_mfma_f32_16x16x32_bf16 v[30:33], v[148:151], v[180:183], v[30:33]
	v_mfma_f32_16x16x32_bf16 v[26:29], v[156:159], v[180:183], v[26:29]
	v_mfma_f32_16x16x32_bf16 v[14:17], v[148:151], v[188:191], v[14:17]
	v_mfma_f32_16x16x32_bf16 v[10:13], v[156:159], v[188:191], v[10:13]
	s_setprio 0
	s_barrier
; #define PG8_STAGE(bufoff, gbase, voff) do { _Pragma("unroll") for (int _i = 0; _i < 2; ++_i) \
;         __builtin_amdgcn_global_load_lds((const unsigned*)((const char*)(gbase) + (voff)[_i]), (LAS unsigned*)(lds + (bufoff) + ldsw + _i * 8192), 16, 0, 0); } while (0)
; #define PG8_LDA(dst, b, h) do { _Pragma("unroll") for (int m = 0; m < 4; ++m) _Pragma("unroll") for (int k = 0; k < 2; ++k) dst[m][k] = *(const LAS bf16x8*)(lds + PG8_SA(b, h) + aoff + m * 2048 + k * 1024); } while (0)
; #define PG8_LDB(dst, b, h) do { _Pragma("unroll") for (int n = 0; n < 2; ++n) _Pragma("unroll") for (int k = 0; k < 2; ++k) dst[n][k] = *(const LAS bf16x8*)(lds + PG8_SB(b, h) + boff + n * 2048 + k * 1024); } while (0)
; #define PG8_MMA(ai, bj, At, Bt) do { __builtin_amdgcn_s_setprio(1); _Pragma("unroll") for (int m = 0; m < 4; ++m) _Pragma("unroll") for (int n = 0; n < 2; ++n) _Pragma("unroll") for (int k = 0; k < 2; ++k) \
;         acc[ai][bj][m][n] = __builtin_amdgcn_mfma_f32_16x16x32_bf16(Bt[n][k], At[m][k], acc[ai][bj][m][n], 0, 0, 0); __builtin_amdgcn_s_setprio(0); } while (0)
; #define PG8_WAIT_V(n) asm volatile("s_waitcnt vmcnt(" #n ")" ::: "memory")
; #define PG8_WAIT_L(n) asm volatile("s_waitcnt lgkmcnt(" #n ")" ::: "memory")
; #define PG8_BAR __builtin_amdgcn_s_barrier()
; #define PG8_SCHED __builtin_amdgcn_sched_barrier(0)
; template <class Epi>
; DEVI void gemm_phase(const int wv, LAS unsigned char* lds, const Gemm g, const Order& S, const Epi& E) {
;     ...
;             PG8_STAGE(PG8_SB(0, 1), b2 + hstepB, voffB);
;             PG8_WAIT_V(6); PG8_BAR; PG8_MMA(1, 1, At, B1); PG8_BAR;
;             PG8_LDB(B0, 1, 0); PG8_SCHED; PG8_LDA(At, 1, 0); PG8_STAGE(PG8_SA(0, 1), a2 + hstepA, voffA);
;             PG8_WAIT_L(8); PG8_BAR; PG8_WAIT_L(0); PG8_MMA(0, 0, At, B0); PG8_BAR; PG8_SCHED;
;             PG8_LDB(B1, 1, 1); PG8_STAGE(PG8_SB(1, 0), b3, voffB);
;             PG8_BAR; PG8_WAIT_L(0); PG8_MMA(0, 1, At, B1); PG8_BAR;
;             PG8_LDA(At, 1, 1); PG8_STAGE(PG8_SA(1, 0), a3, voffA);
;             PG8_BAR; PG8_WAIT_L(0); PG8_MMA(1, 0, At, B0); PG8_BAR; PG8_SCHED;
	s_add_u32 s58, s30, 0x40000
	s_addc_u32 s59, s31, 0
	s_add_i32 s60, s60, s95
	v_lshl_add_u64 v[140:141], s[58:59], 0, v[0:1]
	s_mov_b32 m0, s60
	s_nop 0
	global_load_lds_dwordx4 v[140:141], off
	v_lshl_add_u64 v[140:141], s[58:59], 0, v[130:131]
	s_add_i32 m0, s60, 0x2000
	s_nop 0
	global_load_lds_dwordx4 v[140:141], off
	s_waitcnt vmcnt(6)
	s_barrier
	s_setprio 1
	v_mfma_f32_16x16x32_bf16 v[54:57], v[192:195], v[160:163], 0
	v_mfma_f32_16x16x32_bf16 v[50:53], v[204:207], v[160:163], 0
	v_mfma_f32_16x16x32_bf16 v[38:41], v[192:195], v[168:171], 0
	v_mfma_f32_16x16x32_bf16 v[34:37], v[204:207], v[168:171], 0
	v_mfma_f32_16x16x32_bf16 v[22:25], v[192:195], v[176:179], 0
	v_mfma_f32_16x16x32_bf16 v[18:21], v[204:207], v[176:179], 0
	v_mfma_f32_16x16x32_bf16 v[6:9], v[192:195], v[184:187], 0
	v_mfma_f32_16x16x32_bf16 v[2:5], v[204:207], v[184:187], 0
	v_mfma_f32_16x16x32_bf16 v[54:57], v[200:203], v[164:167], v[54:57]
	v_mfma_f32_16x16x32_bf16 v[50:53], v[208:211], v[164:167], v[50:53]
	v_mfma_f32_16x16x32_bf16 v[38:41], v[200:203], v[172:175], v[38:41]
	v_mfma_f32_16x16x32_bf16 v[34:37], v[208:211], v[172:175], v[34:37]
	v_mfma_f32_16x16x32_bf16 v[22:25], v[200:203], v[180:183], v[22:25]
	v_mfma_f32_16x16x32_bf16 v[18:21], v[208:211], v[180:183], v[18:21]
	v_mfma_f32_16x16x32_bf16 v[6:9], v[200:203], v[188:191], v[6:9]
	v_mfma_f32_16x16x32_bf16 v[2:5], v[208:211], v[188:191], v[2:5]
	s_setprio 0
	s_add_i32 s58, 0, 0x18000
	v_add_u32_e32 v156, s58, v145
	s_barrier
	ds_read_b128 v[140:143], v156
	ds_read_b128 v[148:151], v156 offset:1024
	ds_read_b128 v[152:155], v156 offset:2048
	ds_read_b128 v[156:159], v156 offset:3072
	s_add_u32 s36, s36, 0x40000
	s_addc_u32 s37, s37, 0
	s_mov_b32 m0, s40
	v_lshl_add_u64 v[192:193], s[36:37], 0, v[134:135]
	ds_read_b128 v[160:163], v147 offset:32768
	ds_read_b128 v[164:167], v147 offset:33792
	ds_read_b128 v[168:171], v147 offset:34816
	ds_read_b128 v[172:175], v147 offset:35840
	ds_read_b128 v[176:179], v147 offset:36864
	ds_read_b128 v[180:183], v147 offset:37888
	ds_read_b128 v[184:187], v147 offset:38912
	ds_read_b128 v[188:191], v147 offset:39936
	global_load_lds_dwordx4 v[192:193], off
	v_lshl_add_u64 v[192:193], s[36:37], 0, v[132:133]
	s_mov_b32 m0, s41
	s_nop 0
	global_load_lds_dwordx4 v[192:193], off
	s_waitcnt lgkmcnt(8)
	s_barrier
	s_waitcnt lgkmcnt(0)
	s_setprio 1
	s_waitcnt lgkmcnt(0)
	v_mfma_f32_16x16x32_bf16 v[126:129], v[140:143], v[160:163], v[126:129]
	v_mfma_f32_16x16x32_bf16 v[122:125], v[152:155], v[160:163], v[122:125]
	v_mfma_f32_16x16x32_bf16 v[110:113], v[140:143], v[168:171], v[110:113]
	v_mfma_f32_16x16x32_bf16 v[106:109], v[152:155], v[168:171], v[106:109]
	v_mfma_f32_16x16x32_bf16 v[94:97], v[140:143], v[176:179], v[94:97]
	v_mfma_f32_16x16x32_bf16 v[90:93], v[152:155], v[176:179], v[90:93]
	v_mfma_f32_16x16x32_bf16 v[78:81], v[140:143], v[184:187], v[78:81]
	v_mfma_f32_16x16x32_bf16 v[74:77], v[152:155], v[184:187], v[74:77]
	v_mfma_f32_16x16x32_bf16 v[126:129], v[148:151], v[164:167], v[126:129]
	v_mfma_f32_16x16x32_bf16 v[122:125], v[156:159], v[164:167], v[122:125]
	v_mfma_f32_16x16x32_bf16 v[110:113], v[148:151], v[172:175], v[110:113]
	v_mfma_f32_16x16x32_bf16 v[106:109], v[156:159], v[172:175], v[106:109]
	v_mfma_f32_16x16x32_bf16 v[94:97], v[148:151], v[180:183], v[94:97]
	v_mfma_f32_16x16x32_bf16 v[90:93], v[156:159], v[180:183], v[90:93]
	v_mfma_f32_16x16x32_bf16 v[78:81], v[148:151], v[188:191], v[78:81]
	v_mfma_f32_16x16x32_bf16 v[74:77], v[156:159], v[188:191], v[74:77]
	s_setprio 0
	s_barrier
	s_add_i32 s36, 0, 0x1c000
	s_add_i32 s37, s58, s95
	v_add_u32_e32 v199, s36, v145
	v_lshl_add_u64 v[212:213], v[212:213], 0, s[92:93]
	s_mov_b32 m0, s37
	ds_read_b128 v[192:195], v199
	ds_read_b128 v[200:203], v199 offset:1024
	ds_read_b128 v[204:207], v199 offset:2048
	ds_read_b128 v[208:211], v199 offset:3072
	global_load_lds_dwordx4 v[212:213], off
	v_lshl_add_u64 v[212:213], v[214:215], 0, s[92:93]
	s_add_i32 m0, s37, 0x2000
	s_nop 0
	global_load_lds_dwordx4 v[212:213], off
	s_barrier
; #define PG8_STAGE(bufoff, gbase, voff) do { _Pragma("unroll") for (int _i = 0; _i < 2; ++_i) \
;         __builtin_amdgcn_global_load_lds((const unsigned*)((const char*)(gbase) + (voff)[_i]), (LAS unsigned*)(lds + (bufoff) + ldsw + _i * 8192), 16, 0, 0); } while (0)
; #define PG8_MMA(ai, bj, At, Bt) do { __builtin_amdgcn_s_setprio(1); _Pragma("unroll") for (int m = 0; m < 4; ++m) _Pragma("unroll") for (int n = 0; n < 2; ++n) _Pragma("unroll") for (int k = 0; k < 2; ++k) \
;         acc[ai][bj][m][n] = __builtin_amdgcn_mfma_f32_16x16x32_bf16(Bt[n][k], At[m][k], acc[ai][bj][m][n], 0, 0, 0); __builtin_amdgcn_s_setprio(0); } while (0)
; #define PG8_WAIT_V(n) asm volatile("s_waitcnt vmcnt(" #n ")" ::: "memory")
; #define PG8_WAIT_L(n) asm volatile("s_waitcnt lgkmcnt(" #n ")" ::: "memory")
; #define PG8_BAR __builtin_amdgcn_s_barrier()
; #define PG8_SCHED __builtin_amdgcn_sched_barrier(0)
; template <class Epi>
; DEVI void gemm_phase(const int wv, LAS unsigned char* lds, const Gemm g, const Order& S, const Epi& E) {
;     ...
;             PG8_BAR; PG8_WAIT_L(0); PG8_MMA(1, 0, At, B0); PG8_BAR; PG8_SCHED;
;             PG8_STAGE(PG8_SB(1, 1), b3 + hstepB, voffB);
;             PG8_WAIT_V(6); PG8_BAR; PG8_MMA(1, 1, At, B1); PG8_BAR;
;         }
	s_waitcnt lgkmcnt(0)
	s_setprio 1
	s_waitcnt lgkmcnt(0)
	v_mfma_f32_16x16x32_bf16 v[118:121], v[192:195], v[160:163], v[118:121]
	v_mfma_f32_16x16x32_bf16 v[114:117], v[204:207], v[160:163], v[114:117]
	v_mfma_f32_16x16x32_bf16 v[102:105], v[192:195], v[168:171], v[102:105]
	v_mfma_f32_16x16x32_bf16 v[98:101], v[204:207], v[168:171], v[98:101]
	v_mfma_f32_16x16x32_bf16 v[86:89], v[192:195], v[176:179], v[86:89]
	v_mfma_f32_16x16x32_bf16 v[82:85], v[204:207], v[176:179], v[82:85]
	v_mfma_f32_16x16x32_bf16 v[70:73], v[192:195], v[184:187], v[70:73]
	v_mfma_f32_16x16x32_bf16 v[66:69], v[204:207], v[184:187], v[66:69]
	v_mfma_f32_16x16x32_bf16 v[118:121], v[200:203], v[164:167], v[118:121]
	v_mfma_f32_16x16x32_bf16 v[114:117], v[208:211], v[164:167], v[114:117]
	v_mfma_f32_16x16x32_bf16 v[102:105], v[200:203], v[172:175], v[102:105]
	v_mfma_f32_16x16x32_bf16 v[98:101], v[208:211], v[172:175], v[98:101]
	v_mfma_f32_16x16x32_bf16 v[86:89], v[200:203], v[180:183], v[86:89]
	v_mfma_f32_16x16x32_bf16 v[82:85], v[208:211], v[180:183], v[82:85]
	v_mfma_f32_16x16x32_bf16 v[70:73], v[200:203], v[188:191], v[70:73]
	v_mfma_f32_16x16x32_bf16 v[66:69], v[208:211], v[188:191], v[66:69]
	s_setprio 0
	s_mov_b32 m0, s50
	v_lshl_add_u64 v[212:213], v[216:217], 0, s[92:93]
	s_barrier
	ds_read_b128 v[160:163], v147 offset:49152
	ds_read_b128 v[164:167], v147 offset:50176
	ds_read_b128 v[168:171], v147 offset:51200
	ds_read_b128 v[172:175], v147 offset:52224
	ds_read_b128 v[176:179], v147 offset:53248
	ds_read_b128 v[180:183], v147 offset:54272
	ds_read_b128 v[184:187], v147 offset:55296
	ds_read_b128 v[188:191], v147 offset:56320
	global_load_lds_dwordx4 v[212:213], off
	v_lshl_add_u64 v[212:213], v[218:219], 0, s[92:93]
	s_mov_b32 m0, s51
	s_nop 0
	global_load_lds_dwordx4 v[212:213], off
	s_barrier
	s_waitcnt lgkmcnt(0)
	s_setprio 1
	s_waitcnt lgkmcnt(0)
	v_mfma_f32_16x16x32_bf16 v[62:65], v[140:143], v[160:163], v[62:65]
	v_mfma_f32_16x16x32_bf16 v[58:61], v[152:155], v[160:163], v[58:61]
	v_mfma_f32_16x16x32_bf16 v[46:49], v[140:143], v[168:171], v[46:49]
	v_mfma_f32_16x16x32_bf16 v[42:45], v[152:155], v[168:171], v[42:45]
	v_mfma_f32_16x16x32_bf16 v[30:33], v[140:143], v[176:179], v[30:33]
	v_mfma_f32_16x16x32_bf16 v[26:29], v[152:155], v[176:179], v[26:29]
	v_mfma_f32_16x16x32_bf16 v[14:17], v[140:143], v[184:187], v[14:17]
	v_mfma_f32_16x16x32_bf16 v[10:13], v[152:155], v[184:187], v[10:13]
	v_mfma_f32_16x16x32_bf16 v[62:65], v[148:151], v[164:167], v[62:65]
	v_mfma_f32_16x16x32_bf16 v[58:61], v[156:159], v[164:167], v[58:61]
	v_mfma_f32_16x16x32_bf16 v[46:49], v[148:151], v[172:175], v[46:49]
	v_mfma_f32_16x16x32_bf16 v[42:45], v[156:159], v[172:175], v[42:45]
	v_mfma_f32_16x16x32_bf16 v[30:33], v[148:151], v[180:183], v[30:33]
	v_mfma_f32_16x16x32_bf16 v[26:29], v[156:159], v[180:183], v[26:29]
	v_mfma_f32_16x16x32_bf16 v[14:17], v[148:151], v[188:191], v[14:17]
	v_mfma_f32_16x16x32_bf16 v[10:13], v[156:159], v[188:191], v[10:13]
	s_setprio 0
	s_barrier
	s_add_u32 s30, s30, 0x40080
	s_addc_u32 s31, s31, 0
	s_add_i32 s36, s36, s95
	v_lshl_add_u64 v[140:141], s[30:31], 0, v[0:1]
	s_mov_b32 m0, s36
	s_nop 0
	global_load_lds_dwordx4 v[140:141], off
	v_lshl_add_u64 v[140:141], s[30:31], 0, v[130:131]
	s_add_i32 m0, s36, 0x2000
	s_nop 0
	global_load_lds_dwordx4 v[140:141], off
	s_waitcnt vmcnt(6)
	s_barrier
	s_setprio 1
	v_mfma_f32_16x16x32_bf16 v[54:57], v[192:195], v[160:163], v[54:57]
	v_mfma_f32_16x16x32_bf16 v[50:53], v[204:207], v[160:163], v[50:53]
	v_mfma_f32_16x16x32_bf16 v[38:41], v[192:195], v[168:171], v[38:41]
	v_mfma_f32_16x16x32_bf16 v[34:37], v[204:207], v[168:171], v[34:37]
	v_mfma_f32_16x16x32_bf16 v[22:25], v[192:195], v[176:179], v[22:25]
	v_mfma_f32_16x16x32_bf16 v[18:21], v[204:207], v[176:179], v[18:21]
	v_mfma_f32_16x16x32_bf16 v[6:9], v[192:195], v[184:187], v[6:9]
	v_mfma_f32_16x16x32_bf16 v[2:5], v[204:207], v[184:187], v[2:5]
	v_mfma_f32_16x16x32_bf16 v[54:57], v[200:203], v[164:167], v[54:57]
	v_mfma_f32_16x16x32_bf16 v[50:53], v[208:211], v[164:167], v[50:53]
	v_mfma_f32_16x16x32_bf16 v[38:41], v[200:203], v[172:175], v[38:41]
	v_mfma_f32_16x16x32_bf16 v[34:37], v[208:211], v[172:175], v[34:37]
	v_mfma_f32_16x16x32_bf16 v[22:25], v[200:203], v[180:183], v[22:25]
	v_mfma_f32_16x16x32_bf16 v[18:21], v[208:211], v[180:183], v[18:21]
	v_mfma_f32_16x16x32_bf16 v[6:9], v[200:203], v[188:191], v[6:9]
	v_mfma_f32_16x16x32_bf16 v[2:5], v[208:211], v[188:191], v[2:5]
	s_setprio 0
	s_add_i32 s57, s57, 2
	s_add_u32 s28, s28, 0x100
	s_addc_u32 s29, s29, 0
	s_add_u32 s55, s55, 0x100
	s_addc_u32 s56, s56, 0
	s_cmp_gt_u32 s57, 13
	s_barrier
	s_cbranch_scc0 .LBB0_814
	s_branch .Lzp_epi_1

; DEVI unsigned cvt_pk_bf16(float lo, float hi) { unsigned r; asm volatile("v_cvt_pk_bf16_f32 %0, %1, %2" : "=v"(r) : "v"(lo), "v"(hi)); return r; }
;     DEVI void operator()(f32x4 (&acc)[2][2][4][2], const Unit& u, int wr, int wc, int fr, int fq) const {
;     ...
;             for (int m = 0; m < 4; ++m) { bf16_t* rowp = O + (size_t)(row0 + ai * HALF + m * 16) * ldc + col0;
;                 float rstd = 1.0f; if (RS) rstd = rsqrtf(ssq[row0 + ai * HALF + m * 16] * (1.0f / 1024.0f) + EPS);
; #pragma unroll
;                 for (int bj = 0; bj < 2; ++bj) { f32x4 v0 = acc[ai][bj][m][0], v1 = acc[ai][bj][m][1];
;                     if (RS) { v0 = v0 * rstd + sh[bj][0]; v1 = v1 * rstd + sh[bj][1]; }
;                     if (ACT == 1) {
; #pragma unroll
;                         for (int j = 0; j < 4; ++j) { const float a = fmaxf(v0[j], 0.f), b = fmaxf(v1[j], 0.f); v0[j] = a * a; v1[j] = b * b; } }
;                     if (ACT == 2) {
; #pragma unroll
;                         for (int j = 0; j < 4; ++j) { v0[j] = 1.0f + __expf(-fminf(fmaxf(v0[j], -30.f), 30.f)); v1[j] = 1.0f + __expf(-fminf(fmaxf(v1[j], -30.f), 30.f)); } }
;                     u32x4 w; w.x = cvt_pk_bf16(v0[0], v0[1]); w.y = cvt_pk_bf16(v0[2], v0[3]); w.z = cvt_pk_bf16(v1[0], v1[1]); w.w = cvt_pk_bf16(v1[2], v1[3]);
;                     *(u32x4*)(rowp + bj * HALF) = w; } }
.Lzp_epi_1:
	v_max_f32_e32 v122, v122, v122
	v_med3_f32 v122, v122, s49, v238
	v_max_f32_e32 v123, v123, v123
	v_max_f32_e32 v124, v124, v124
	v_mul_f32_e32 v122, 0xbfb8aa3b, v122
	v_med3_f32 v123, v123, s49, v238
	v_med3_f32 v124, v124, s49, v238
	v_exp_f32_e32 v122, v122
	v_mul_f32_e32 v123, 0xbfb8aa3b, v123
	v_mul_f32_e32 v124, 0xbfb8aa3b, v124
	v_exp_f32_e32 v123, v123
	v_exp_f32_e32 v124, v124
	v_add_f32_e32 v149, 1.0, v122
	v_max_f32_e32 v122, v127, v127
	v_max_f32_e32 v126, v126, v126
	v_med3_f32 v122, v122, s49, v238
	v_add_f32_e32 v127, 1.0, v123
	v_max_f32_e32 v123, v128, v128
	v_add_f32_e32 v128, 1.0, v124
	v_max_f32_e32 v124, v129, v129
	v_max_f32_e32 v125, v125, v125
	v_med3_f32 v126, v126, s49, v238
	v_mul_f32_e32 v122, 0xbfb8aa3b, v122
	v_med3_f32 v123, v123, s49, v238
	v_med3_f32 v124, v124, s49, v238
	v_med3_f32 v125, v125, s49, v238
	v_max_f32_e32 v114, v114, v114
	v_max_f32_e32 v115, v115, v115
	v_max_f32_e32 v116, v116, v116
	v_mul_f32_e32 v126, 0xbfb8aa3b, v126
	v_exp_f32_e32 v122, v122
	v_mul_f32_e32 v123, 0xbfb8aa3b, v123
	v_mul_f32_e32 v124, 0xbfb8aa3b, v124
	v_mul_f32_e32 v125, 0xbfb8aa3b, v125
	v_med3_f32 v114, v114, s49, v238
	v_med3_f32 v115, v115, s49, v238
	v_med3_f32 v116, v116, s49, v238
	v_exp_f32_e32 v126, v126
	v_exp_f32_e32 v123, v123
	v_exp_f32_e32 v124, v124
	v_exp_f32_e32 v125, v125
	v_mul_f32_e32 v114, 0xbfb8aa3b, v114
	v_mul_f32_e32 v115, 0xbfb8aa3b, v115
	v_mul_f32_e32 v116, 0xbfb8aa3b, v116
	v_lshl_or_b32 v142, s10, 8, v146
	v_exp_f32_e32 v114, v114
	v_exp_f32_e32 v115, v115
	v_exp_f32_e32 v116, v116
	v_lshl_add_u32 v148, s12, 8, v144
	v_ashrrev_i32_e32 v143, 31, v142
	v_mov_b64_e32 v[140:141], s[24:25]
	s_movk_i32 s1, 0x1800
	v_mad_i64_i32 v[150:151], s[28:29], v148, s1, v[140:141]
	v_lshlrev_b64 v[142:143], 1, v[142:143]
	v_add_f32_e32 v122, 1.0, v122
	v_lshl_add_u64 v[150:151], v[150:151], 0, v[142:143]
	v_add_f32_e32 v126, 1.0, v126
	v_add_f32_e32 v123, 1.0, v123
	v_add_f32_e32 v124, 1.0, v124
	v_add_f32_e32 v125, 1.0, v125
	v_cvt_pk_bf16_f32 v122, v126, v122
	v_cvt_pk_bf16_f32 v123, v123, v124
	v_cvt_pk_bf16_f32 v124, v149, v127
	v_cvt_pk_bf16_f32 v125, v128, v125
	global_store_dwordx4 v[150:151], v[122:125], off
	v_max_f32_e32 v118, v118, v118
	v_max_f32_e32 v117, v117, v117
	v_add_f32_e32 v122, 1.0, v114
	v_max_f32_e32 v114, v119, v119
	v_add_f32_e32 v119, 1.0, v115
	v_max_f32_e32 v115, v120, v120
	v_add_f32_e32 v120, 1.0, v116
	v_max_f32_e32 v116, v121, v121
	v_med3_f32 v114, v114, s49, v238
	v_med3_f32 v115, v115, s49, v238
	v_med3_f32 v116, v116, s49, v238
	v_med3_f32 v118, v118, s49, v238
	v_mul_f32_e32 v114, 0xbfb8aa3b, v114
	v_mul_f32_e32 v115, 0xbfb8aa3b, v115
	v_mul_f32_e32 v116, 0xbfb8aa3b, v116
	v_med3_f32 v117, v117, s49, v238
	v_max_f32_e32 v106, v106, v106
	v_mul_f32_e32 v118, 0xbfb8aa3b, v118
	v_exp_f32_e32 v114, v114
	v_exp_f32_e32 v115, v115
	v_exp_f32_e32 v116, v116
	v_mul_f32_e32 v117, 0xbfb8aa3b, v117
	v_med3_f32 v106, v106, s49, v238
	v_max_f32_e32 v107, v107, v107
	v_max_f32_e32 v108, v108, v108
	v_exp_f32_e32 v118, v118
	v_exp_f32_e32 v117, v117
	v_mul_f32_e32 v106, 0xbfb8aa3b, v106
	v_med3_f32 v107, v107, s49, v238
	v_med3_f32 v108, v108, s49, v238
	v_exp_f32_e32 v106, v106
	v_mul_f32_e32 v107, 0xbfb8aa3b, v107
	v_mul_f32_e32 v108, 0xbfb8aa3b, v108
	v_exp_f32_e32 v107, v107
	v_exp_f32_e32 v108, v108
	v_add_f32_e32 v114, 1.0, v114
	v_add_f32_e32 v115, 1.0, v115
	v_add_f32_e32 v116, 1.0, v116
	v_add_f32_e32 v118, 1.0, v118
	v_add_f32_e32 v117, 1.0, v117
	v_cvt_pk_bf16_f32 v114, v118, v114
	v_cvt_pk_bf16_f32 v115, v115, v116
	v_cvt_pk_bf16_f32 v116, v122, v119
	v_cvt_pk_bf16_f32 v117, v120, v117
	global_store_dwordx4 v[150:151], v[114:117], off offset:256
	v_max_f32_e32 v110, v110, v110
	v_max_f32_e32 v109, v109, v109
	v_add_f32_e32 v116, 1.0, v106
	v_max_f32_e32 v106, v111, v111
	v_med3_f32 v106, v106, s49, v238
	v_add_f32_e32 v111, 1.0, v107
	v_max_f32_e32 v107, v112, v112
	v_add_f32_e32 v112, 1.0, v108
	v_max_f32_e32 v108, v113, v113
	v_med3_f32 v110, v110, s49, v238
	v_mul_f32_e32 v106, 0xbfb8aa3b, v106
	v_med3_f32 v107, v107, s49, v238
	v_med3_f32 v108, v108, s49, v238
	v_med3_f32 v109, v109, s49, v238
	v_max_f32_e32 v98, v98, v98
	v_max_f32_e32 v99, v99, v99
	v_max_f32_e32 v100, v100, v100
	v_mul_f32_e32 v110, 0xbfb8aa3b, v110
	v_exp_f32_e32 v106, v106
	v_mul_f32_e32 v107, 0xbfb8aa3b, v107
	v_mul_f32_e32 v108, 0xbfb8aa3b, v108
	v_mul_f32_e32 v109, 0xbfb8aa3b, v109
	v_med3_f32 v98, v98, s49, v238
	v_med3_f32 v99, v99, s49, v238
	v_med3_f32 v100, v100, s49, v238
	v_exp_f32_e32 v110, v110
	v_exp_f32_e32 v107, v107
	v_exp_f32_e32 v108, v108
	v_exp_f32_e32 v109, v109
	v_mul_f32_e32 v98, 0xbfb8aa3b, v98
	v_mul_f32_e32 v99, 0xbfb8aa3b, v99
	v_mul_f32_e32 v100, 0xbfb8aa3b, v100
	v_exp_f32_e32 v98, v98
	v_exp_f32_e32 v99, v99
	v_exp_f32_e32 v100, v100
	v_or_b32_e32 v114, 16, v148
	v_mad_i64_i32 v[114:115], s[28:29], v114, s1, v[140:141]
	v_add_f32_e32 v106, 1.0, v106
	v_lshl_add_u64 v[114:115], v[114:115], 0, v[142:143]
	v_add_f32_e32 v110, 1.0, v110
	v_add_f32_e32 v107, 1.0, v107
	v_add_f32_e32 v108, 1.0, v108
	v_add_f32_e32 v109, 1.0, v109
	v_cvt_pk_bf16_f32 v106, v110, v106
	v_cvt_pk_bf16_f32 v107, v107, v108
	v_cvt_pk_bf16_f32 v108, v116, v111
	v_cvt_pk_bf16_f32 v109, v112, v109
	global_store_dwordx4 v[114:115], v[106:109], off
	v_max_f32_e32 v102, v102, v102
	v_max_f32_e32 v101, v101, v101
	v_add_f32_e32 v106, 1.0, v98
	v_max_f32_e32 v98, v103, v103
	v_add_f32_e32 v103, 1.0, v99
	v_max_f32_e32 v99, v104, v104
	v_add_f32_e32 v104, 1.0, v100
	v_max_f32_e32 v100, v105, v105
	v_med3_f32 v98, v98, s49, v238
	v_med3_f32 v99, v99, s49, v238
	v_med3_f32 v100, v100, s49, v238
; DEVI unsigned cvt_pk_bf16(float lo, float hi) { unsigned r; asm volatile("v_cvt_pk_bf16_f32 %0, %1, %2" : "=v"(r) : "v"(lo), "v"(hi)); return r; }
;     DEVI void operator()(f32x4 (&acc)[2][2][4][2], const Unit& u, int wr, int wc, int fr, int fq) const {
;     ...
;             for (int m = 0; m < 4; ++m) { bf16_t* rowp = O + (size_t)(row0 + ai * HALF + m * 16) * ldc + col0;
;                 float rstd = 1.0f; if (RS) rstd = rsqrtf(ssq[row0 + ai * HALF + m * 16] * (1.0f / 1024.0f) + EPS);
; #pragma unroll
;                 for (int bj = 0; bj < 2; ++bj) { f32x4 v0 = acc[ai][bj][m][0], v1 = acc[ai][bj][m][1];
;                     if (RS) { v0 = v0 * rstd + sh[bj][0]; v1 = v1 * rstd + sh[bj][1]; }
;                     if (ACT == 1) {
; #pragma unroll
;                         for (int j = 0; j < 4; ++j) { const float a = fmaxf(v0[j], 0.f), b = fmaxf(v1[j], 0.f); v0[j] = a * a; v1[j] = b * b; } }
;                     if (ACT == 2) {
; #pragma unroll
;                         for (int j = 0; j < 4; ++j) { v0[j] = 1.0f + __expf(-fminf(fmaxf(v0[j], -30.f), 30.f)); v1[j] = 1.0f + __expf(-fminf(fmaxf(v1[j], -30.f), 30.f)); } }
;                     u32x4 w; w.x = cvt_pk_bf16(v0[0], v0[1]); w.y = cvt_pk_bf16(v0[2], v0[3]); w.z = cvt_pk_bf16(v1[0], v1[1]); w.w = cvt_pk_bf16(v1[2], v1[3]);
;                     *(u32x4*)(rowp + bj * HALF) = w; } }
	v_med3_f32 v102, v102, s49, v238
	v_mul_f32_e32 v98, 0xbfb8aa3b, v98
	v_mul_f32_e32 v99, 0xbfb8aa3b, v99
	v_mul_f32_e32 v100, 0xbfb8aa3b, v100
	v_med3_f32 v101, v101, s49, v238
	v_max_f32_e32 v90, v90, v90
	v_mul_f32_e32 v102, 0xbfb8aa3b, v102
	v_exp_f32_e32 v98, v98
	v_exp_f32_e32 v99, v99
	v_exp_f32_e32 v100, v100
	v_mul_f32_e32 v101, 0xbfb8aa3b, v101
	v_med3_f32 v90, v90, s49, v238
	v_max_f32_e32 v91, v91, v91
	v_max_f32_e32 v92, v92, v92
	v_exp_f32_e32 v102, v102
	v_exp_f32_e32 v101, v101
	v_mul_f32_e32 v90, 0xbfb8aa3b, v90
	v_med3_f32 v91, v91, s49, v238
	v_med3_f32 v92, v92, s49, v238
	v_exp_f32_e32 v90, v90
	v_mul_f32_e32 v91, 0xbfb8aa3b, v91
	v_mul_f32_e32 v92, 0xbfb8aa3b, v92
	v_exp_f32_e32 v91, v91
	v_exp_f32_e32 v92, v92
	v_add_f32_e32 v98, 1.0, v98
	v_add_f32_e32 v99, 1.0, v99
	v_add_f32_e32 v100, 1.0, v100
	v_add_f32_e32 v102, 1.0, v102
	v_add_f32_e32 v101, 1.0, v101
	v_cvt_pk_bf16_f32 v98, v102, v98
	v_cvt_pk_bf16_f32 v99, v99, v100
	v_cvt_pk_bf16_f32 v100, v106, v103
	v_cvt_pk_bf16_f32 v101, v104, v101
	global_store_dwordx4 v[114:115], v[98:101], off offset:256
	v_max_f32_e32 v94, v94, v94
	v_max_f32_e32 v93, v93, v93
	v_add_f32_e32 v100, 1.0, v90
	v_max_f32_e32 v90, v95, v95
	v_med3_f32 v90, v90, s49, v238
	v_add_f32_e32 v95, 1.0, v91
	v_max_f32_e32 v91, v96, v96
	v_add_f32_e32 v96, 1.0, v92
	v_max_f32_e32 v92, v97, v97
	v_med3_f32 v94, v94, s49, v238
	v_mul_f32_e32 v90, 0xbfb8aa3b, v90
	v_med3_f32 v91, v91, s49, v238
	v_med3_f32 v92, v92, s49, v238
	v_med3_f32 v93, v93, s49, v238
	v_max_f32_e32 v82, v82, v82
	v_max_f32_e32 v83, v83, v83
	v_max_f32_e32 v84, v84, v84
	v_mul_f32_e32 v94, 0xbfb8aa3b, v94
	v_exp_f32_e32 v90, v90
	v_mul_f32_e32 v91, 0xbfb8aa3b, v91
	v_mul_f32_e32 v92, 0xbfb8aa3b, v92
	v_mul_f32_e32 v93, 0xbfb8aa3b, v93
	v_med3_f32 v82, v82, s49, v238
	v_med3_f32 v83, v83, s49, v238
	v_med3_f32 v84, v84, s49, v238
	v_exp_f32_e32 v94, v94
	v_exp_f32_e32 v91, v91
	v_exp_f32_e32 v92, v92
	v_exp_f32_e32 v93, v93
	v_mul_f32_e32 v82, 0xbfb8aa3b, v82
	v_mul_f32_e32 v83, 0xbfb8aa3b, v83
	v_mul_f32_e32 v84, 0xbfb8aa3b, v84
	v_exp_f32_e32 v82, v82
	v_exp_f32_e32 v83, v83
	v_exp_f32_e32 v84, v84
	v_or_b32_e32 v98, 32, v148
	v_mad_i64_i32 v[98:99], s[28:29], v98, s1, v[140:141]
	v_add_f32_e32 v90, 1.0, v90
	v_lshl_add_u64 v[98:99], v[98:99], 0, v[142:143]
	v_add_f32_e32 v94, 1.0, v94
	v_add_f32_e32 v91, 1.0, v91
	v_add_f32_e32 v92, 1.0, v92
	v_add_f32_e32 v93, 1.0, v93
	v_cvt_pk_bf16_f32 v90, v94, v90
	v_cvt_pk_bf16_f32 v91, v91, v92
	v_cvt_pk_bf16_f32 v92, v100, v95
	v_cvt_pk_bf16_f32 v93, v96, v93
	global_store_dwordx4 v[98:99], v[90:93], off
	v_max_f32_e32 v86, v86, v86
	v_max_f32_e32 v85, v85, v85
	v_add_f32_e32 v90, 1.0, v82
	v_max_f32_e32 v82, v87, v87
	v_add_f32_e32 v87, 1.0, v83
	v_max_f32_e32 v83, v88, v88
	v_add_f32_e32 v88, 1.0, v84
	v_max_f32_e32 v84, v89, v89
	v_med3_f32 v82, v82, s49, v238
	v_med3_f32 v83, v83, s49, v238
	v_med3_f32 v84, v84, s49, v238
	v_med3_f32 v86, v86, s49, v238
	v_mul_f32_e32 v82, 0xbfb8aa3b, v82
	v_mul_f32_e32 v83, 0xbfb8aa3b, v83
	v_mul_f32_e32 v84, 0xbfb8aa3b, v84
	v_med3_f32 v85, v85, s49, v238
	v_max_f32_e32 v74, v74, v74
	v_mul_f32_e32 v86, 0xbfb8aa3b, v86
	v_exp_f32_e32 v82, v82
	v_exp_f32_e32 v83, v83
	v_exp_f32_e32 v84, v84
	v_mul_f32_e32 v85, 0xbfb8aa3b, v85
	v_med3_f32 v74, v74, s49, v238
	v_max_f32_e32 v75, v75, v75
	v_max_f32_e32 v76, v76, v76
	v_exp_f32_e32 v86, v86
	v_exp_f32_e32 v85, v85
	v_mul_f32_e32 v74, 0xbfb8aa3b, v74
	v_med3_f32 v75, v75, s49, v238
	v_med3_f32 v76, v76, s49, v238
	v_exp_f32_e32 v74, v74
	v_mul_f32_e32 v75, 0xbfb8aa3b, v75
	v_mul_f32_e32 v76, 0xbfb8aa3b, v76
	v_exp_f32_e32 v75, v75
	v_exp_f32_e32 v76, v76
	v_add_f32_e32 v82, 1.0, v82
	v_add_f32_e32 v83, 1.0, v83
	v_add_f32_e32 v84, 1.0, v84
	v_add_f32_e32 v86, 1.0, v86
	v_add_f32_e32 v85, 1.0, v85
	v_cvt_pk_bf16_f32 v82, v86, v82
	v_cvt_pk_bf16_f32 v83, v83, v84
	v_cvt_pk_bf16_f32 v84, v90, v87
	v_cvt_pk_bf16_f32 v85, v88, v85
	global_store_dwordx4 v[98:99], v[82:85], off offset:256
	v_max_f32_e32 v78, v78, v78
	v_max_f32_e32 v77, v77, v77
	v_add_f32_e32 v84, 1.0, v74
	v_max_f32_e32 v74, v79, v79
	v_med3_f32 v74, v74, s49, v238
	v_add_f32_e32 v79, 1.0, v75
	v_max_f32_e32 v75, v80, v80
	v_add_f32_e32 v80, 1.0, v76
	v_max_f32_e32 v76, v81, v81
	v_med3_f32 v78, v78, s49, v238
	v_mul_f32_e32 v74, 0xbfb8aa3b, v74
	v_med3_f32 v75, v75, s49, v238
	v_med3_f32 v76, v76, s49, v238
	v_med3_f32 v77, v77, s49, v238
	v_max_f32_e32 v66, v66, v66
	v_max_f32_e32 v67, v67, v67
	v_max_f32_e32 v68, v68, v68
	v_mul_f32_e32 v78, 0xbfb8aa3b, v78
	v_exp_f32_e32 v74, v74
	v_mul_f32_e32 v75, 0xbfb8aa3b, v75
	v_mul_f32_e32 v76, 0xbfb8aa3b, v76
	v_mul_f32_e32 v77, 0xbfb8aa3b, v77
	v_med3_f32 v66, v66, s49, v238
	v_med3_f32 v67, v67, s49, v238
	v_med3_f32 v68, v68, s49, v238
	v_exp_f32_e32 v78, v78
	v_exp_f32_e32 v75, v75
	v_exp_f32_e32 v76, v76
	v_exp_f32_e32 v77, v77
	v_mul_f32_e32 v66, 0xbfb8aa3b, v66
	v_mul_f32_e32 v67, 0xbfb8aa3b, v67
	v_mul_f32_e32 v68, 0xbfb8aa3b, v68
	v_exp_f32_e32 v66, v66
	v_exp_f32_e32 v67, v67
	v_exp_f32_e32 v68, v68
	v_or_b32_e32 v82, 48, v148
	v_mad_i64_i32 v[82:83], s[28:29], v82, s1, v[140:141]
	v_add_f32_e32 v74, 1.0, v74
	v_lshl_add_u64 v[82:83], v[82:83], 0, v[142:143]
	v_add_f32_e32 v78, 1.0, v78
	v_add_f32_e32 v75, 1.0, v75
	v_add_f32_e32 v76, 1.0, v76
	v_add_f32_e32 v77, 1.0, v77
	v_cvt_pk_bf16_f32 v74, v78, v74
	v_cvt_pk_bf16_f32 v75, v75, v76
	v_cvt_pk_bf16_f32 v76, v84, v79
	v_cvt_pk_bf16_f32 v77, v80, v77
	global_store_dwordx4 v[82:83], v[74:77], off
	v_max_f32_e32 v70, v70, v70
	v_max_f32_e32 v69, v69, v69
	v_add_f32_e32 v74, 1.0, v66
	v_max_f32_e32 v66, v71, v71
	v_add_f32_e32 v71, 1.0, v67
; DEVI unsigned cvt_pk_bf16(float lo, float hi) { unsigned r; asm volatile("v_cvt_pk_bf16_f32 %0, %1, %2" : "=v"(r) : "v"(lo), "v"(hi)); return r; }
;     DEVI void operator()(f32x4 (&acc)[2][2][4][2], const Unit& u, int wr, int wc, int fr, int fq) const {
;     ...
;             for (int m = 0; m < 4; ++m) { bf16_t* rowp = O + (size_t)(row0 + ai * HALF + m * 16) * ldc + col0;
;                 float rstd = 1.0f; if (RS) rstd = rsqrtf(ssq[row0 + ai * HALF + m * 16] * (1.0f / 1024.0f) + EPS);
; #pragma unroll
;                 for (int bj = 0; bj < 2; ++bj) { f32x4 v0 = acc[ai][bj][m][0], v1 = acc[ai][bj][m][1];
;                     if (RS) { v0 = v0 * rstd + sh[bj][0]; v1 = v1 * rstd + sh[bj][1]; }
;                     if (ACT == 1) {
; #pragma unroll
;                         for (int j = 0; j < 4; ++j) { const float a = fmaxf(v0[j], 0.f), b = fmaxf(v1[j], 0.f); v0[j] = a * a; v1[j] = b * b; } }
;                     if (ACT == 2) {
; #pragma unroll
;                         for (int j = 0; j < 4; ++j) { v0[j] = 1.0f + __expf(-fminf(fmaxf(v0[j], -30.f), 30.f)); v1[j] = 1.0f + __expf(-fminf(fmaxf(v1[j], -30.f), 30.f)); } }
;                     u32x4 w; w.x = cvt_pk_bf16(v0[0], v0[1]); w.y = cvt_pk_bf16(v0[2], v0[3]); w.z = cvt_pk_bf16(v1[0], v1[1]); w.w = cvt_pk_bf16(v1[2], v1[3]);
;                     *(u32x4*)(rowp + bj * HALF) = w; } }
	v_max_f32_e32 v67, v72, v72
	v_add_f32_e32 v72, 1.0, v68
	v_max_f32_e32 v68, v73, v73
	v_med3_f32 v66, v66, s49, v238
	v_med3_f32 v67, v67, s49, v238
	v_med3_f32 v68, v68, s49, v238
	v_med3_f32 v70, v70, s49, v238
	v_mul_f32_e32 v66, 0xbfb8aa3b, v66
	v_mul_f32_e32 v67, 0xbfb8aa3b, v67
	v_mul_f32_e32 v68, 0xbfb8aa3b, v68
	v_med3_f32 v69, v69, s49, v238
	v_max_f32_e32 v58, v58, v58
	v_mul_f32_e32 v70, 0xbfb8aa3b, v70
	v_exp_f32_e32 v66, v66
	v_exp_f32_e32 v67, v67
	v_exp_f32_e32 v68, v68
	v_mul_f32_e32 v69, 0xbfb8aa3b, v69
	v_med3_f32 v58, v58, s49, v238
	v_max_f32_e32 v59, v59, v59
	v_max_f32_e32 v60, v60, v60
	v_exp_f32_e32 v70, v70
	v_exp_f32_e32 v69, v69
	v_mul_f32_e32 v58, 0xbfb8aa3b, v58
	v_med3_f32 v59, v59, s49, v238
	v_med3_f32 v60, v60, s49, v238
	v_exp_f32_e32 v58, v58
	v_mul_f32_e32 v59, 0xbfb8aa3b, v59
	v_mul_f32_e32 v60, 0xbfb8aa3b, v60
	v_exp_f32_e32 v59, v59
	v_exp_f32_e32 v60, v60
	v_add_f32_e32 v66, 1.0, v66
	v_add_f32_e32 v67, 1.0, v67
	v_add_f32_e32 v68, 1.0, v68
	v_add_f32_e32 v70, 1.0, v70
	v_add_f32_e32 v69, 1.0, v69
	v_cvt_pk_bf16_f32 v66, v70, v66
	v_cvt_pk_bf16_f32 v67, v67, v68
	v_cvt_pk_bf16_f32 v68, v74, v71
	v_cvt_pk_bf16_f32 v69, v72, v69
	global_store_dwordx4 v[82:83], v[66:69], off offset:256
	v_max_f32_e32 v62, v62, v62
	v_max_f32_e32 v61, v61, v61
	v_add_f32_e32 v68, 1.0, v58
	v_max_f32_e32 v58, v63, v63
	v_med3_f32 v58, v58, s49, v238
	v_add_f32_e32 v63, 1.0, v59
	v_max_f32_e32 v59, v64, v64
	v_add_f32_e32 v64, 1.0, v60
	v_max_f32_e32 v60, v65, v65
	v_med3_f32 v62, v62, s49, v238
	v_mul_f32_e32 v58, 0xbfb8aa3b, v58
	v_med3_f32 v59, v59, s49, v238
	v_med3_f32 v60, v60, s49, v238
	v_med3_f32 v61, v61, s49, v238
	v_max_f32_e32 v50, v50, v50
	v_max_f32_e32 v51, v51, v51
	v_max_f32_e32 v52, v52, v52
	v_mul_f32_e32 v62, 0xbfb8aa3b, v62
	v_exp_f32_e32 v58, v58
	v_mul_f32_e32 v59, 0xbfb8aa3b, v59
	v_mul_f32_e32 v60, 0xbfb8aa3b, v60
	v_mul_f32_e32 v61, 0xbfb8aa3b, v61
	v_med3_f32 v50, v50, s49, v238
	v_med3_f32 v51, v51, s49, v238
	v_med3_f32 v52, v52, s49, v238
	v_exp_f32_e32 v62, v62
	v_exp_f32_e32 v59, v59
	v_exp_f32_e32 v60, v60
	v_exp_f32_e32 v61, v61
	v_mul_f32_e32 v50, 0xbfb8aa3b, v50
	v_mul_f32_e32 v51, 0xbfb8aa3b, v51
	v_mul_f32_e32 v52, 0xbfb8aa3b, v52
	v_exp_f32_e32 v50, v50
	v_exp_f32_e32 v51, v51
	v_exp_f32_e32 v52, v52
	v_add_u32_e32 v66, 0x80, v148
	v_mad_i64_i32 v[66:67], s[28:29], v66, s1, v[140:141]
	v_add_f32_e32 v58, 1.0, v58
	v_lshl_add_u64 v[66:67], v[66:67], 0, v[142:143]
	v_add_f32_e32 v62, 1.0, v62
	v_add_f32_e32 v59, 1.0, v59
	v_add_f32_e32 v60, 1.0, v60
	v_add_f32_e32 v61, 1.0, v61
	v_cvt_pk_bf16_f32 v58, v62, v58
	v_cvt_pk_bf16_f32 v59, v59, v60
	v_cvt_pk_bf16_f32 v60, v68, v63
	v_cvt_pk_bf16_f32 v61, v64, v61
	global_store_dwordx4 v[66:67], v[58:61], off
	v_max_f32_e32 v54, v54, v54
	v_max_f32_e32 v53, v53, v53
	v_add_f32_e32 v58, 1.0, v50
	v_max_f32_e32 v50, v55, v55
	v_add_f32_e32 v55, 1.0, v51
	v_max_f32_e32 v51, v56, v56
	v_add_f32_e32 v56, 1.0, v52
	v_max_f32_e32 v52, v57, v57
	v_med3_f32 v50, v50, s49, v238
	v_med3_f32 v51, v51, s49, v238
	v_med3_f32 v52, v52, s49, v238
	v_med3_f32 v54, v54, s49, v238
	v_mul_f32_e32 v50, 0xbfb8aa3b, v50
	v_mul_f32_e32 v51, 0xbfb8aa3b, v51
	v_mul_f32_e32 v52, 0xbfb8aa3b, v52
	v_med3_f32 v53, v53, s49, v238
	v_max_f32_e32 v42, v42, v42
	v_mul_f32_e32 v54, 0xbfb8aa3b, v54
	v_exp_f32_e32 v50, v50
	v_exp_f32_e32 v51, v51
	v_exp_f32_e32 v52, v52
	v_mul_f32_e32 v53, 0xbfb8aa3b, v53
	v_med3_f32 v42, v42, s49, v238
	v_max_f32_e32 v43, v43, v43
	v_max_f32_e32 v44, v44, v44
	v_exp_f32_e32 v54, v54
	v_exp_f32_e32 v53, v53
	v_mul_f32_e32 v42, 0xbfb8aa3b, v42
	v_med3_f32 v43, v43, s49, v238
	v_med3_f32 v44, v44, s49, v238
	v_exp_f32_e32 v42, v42
	v_mul_f32_e32 v43, 0xbfb8aa3b, v43
	v_mul_f32_e32 v44, 0xbfb8aa3b, v44
	v_exp_f32_e32 v43, v43
	v_exp_f32_e32 v44, v44
	v_add_f32_e32 v50, 1.0, v50
	v_add_f32_e32 v51, 1.0, v51
	v_add_f32_e32 v52, 1.0, v52
	v_add_f32_e32 v54, 1.0, v54
	v_add_f32_e32 v53, 1.0, v53
	v_cvt_pk_bf16_f32 v50, v54, v50
	v_cvt_pk_bf16_f32 v51, v51, v52
	v_cvt_pk_bf16_f32 v52, v58, v55
	v_cvt_pk_bf16_f32 v53, v56, v53
	global_store_dwordx4 v[66:67], v[50:53], off offset:256
	v_max_f32_e32 v46, v46, v46
	v_max_f32_e32 v45, v45, v45
	v_add_f32_e32 v52, 1.0, v42
	v_max_f32_e32 v42, v47, v47
	v_med3_f32 v42, v42, s49, v238
	v_add_f32_e32 v47, 1.0, v43
	v_max_f32_e32 v43, v48, v48
	v_add_f32_e32 v48, 1.0, v44
	v_max_f32_e32 v44, v49, v49
	v_med3_f32 v46, v46, s49, v238
	v_mul_f32_e32 v42, 0xbfb8aa3b, v42
	v_med3_f32 v43, v43, s49, v238
	v_med3_f32 v44, v44, s49, v238
	v_med3_f32 v45, v45, s49, v238
	v_max_f32_e32 v34, v34, v34
	v_max_f32_e32 v35, v35, v35
	v_max_f32_e32 v36, v36, v36
	v_mul_f32_e32 v46, 0xbfb8aa3b, v46
	v_exp_f32_e32 v42, v42
	v_mul_f32_e32 v43, 0xbfb8aa3b, v43
	v_mul_f32_e32 v44, 0xbfb8aa3b, v44
	v_mul_f32_e32 v45, 0xbfb8aa3b, v45
	v_med3_f32 v34, v34, s49, v238
	v_med3_f32 v35, v35, s49, v238
	v_med3_f32 v36, v36, s49, v238
	v_exp_f32_e32 v46, v46
	v_exp_f32_e32 v43, v43
	v_exp_f32_e32 v44, v44
	v_exp_f32_e32 v45, v45
	v_mul_f32_e32 v34, 0xbfb8aa3b, v34
	v_mul_f32_e32 v35, 0xbfb8aa3b, v35
	v_mul_f32_e32 v36, 0xbfb8aa3b, v36
	v_exp_f32_e32 v34, v34
	v_exp_f32_e32 v35, v35
	v_exp_f32_e32 v36, v36
	v_add_u32_e32 v50, 0x90, v148
	v_mad_i64_i32 v[50:51], s[28:29], v50, s1, v[140:141]
	v_add_f32_e32 v42, 1.0, v42
	v_lshl_add_u64 v[50:51], v[50:51], 0, v[142:143]
	v_add_f32_e32 v46, 1.0, v46
	v_add_f32_e32 v43, 1.0, v43
	v_add_f32_e32 v44, 1.0, v44
	v_add_f32_e32 v45, 1.0, v45
	v_cvt_pk_bf16_f32 v42, v46, v42
	v_cvt_pk_bf16_f32 v43, v43, v44
	v_cvt_pk_bf16_f32 v44, v52, v47
	v_cvt_pk_bf16_f32 v45, v48, v45
	global_store_dwordx4 v[50:51], v[42:45], off
; DEVI unsigned cvt_pk_bf16(float lo, float hi) { unsigned r; asm volatile("v_cvt_pk_bf16_f32 %0, %1, %2" : "=v"(r) : "v"(lo), "v"(hi)); return r; }
;     DEVI void operator()(f32x4 (&acc)[2][2][4][2], const Unit& u, int wr, int wc, int fr, int fq) const {
;     ...
;             for (int m = 0; m < 4; ++m) { bf16_t* rowp = O + (size_t)(row0 + ai * HALF + m * 16) * ldc + col0;
;                 float rstd = 1.0f; if (RS) rstd = rsqrtf(ssq[row0 + ai * HALF + m * 16] * (1.0f / 1024.0f) + EPS);
; #pragma unroll
;                 for (int bj = 0; bj < 2; ++bj) { f32x4 v0 = acc[ai][bj][m][0], v1 = acc[ai][bj][m][1];
;                     if (RS) { v0 = v0 * rstd + sh[bj][0]; v1 = v1 * rstd + sh[bj][1]; }
;                     if (ACT == 1) {
; #pragma unroll
;                         for (int j = 0; j < 4; ++j) { const float a = fmaxf(v0[j], 0.f), b = fmaxf(v1[j], 0.f); v0[j] = a * a; v1[j] = b * b; } }
;                     if (ACT == 2) {
; #pragma unroll
;                         for (int j = 0; j < 4; ++j) { v0[j] = 1.0f + __expf(-fminf(fmaxf(v0[j], -30.f), 30.f)); v1[j] = 1.0f + __expf(-fminf(fmaxf(v1[j], -30.f), 30.f)); } }
;                     u32x4 w; w.x = cvt_pk_bf16(v0[0], v0[1]); w.y = cvt_pk_bf16(v0[2], v0[3]); w.z = cvt_pk_bf16(v1[0], v1[1]); w.w = cvt_pk_bf16(v1[2], v1[3]);
;                     *(u32x4*)(rowp + bj * HALF) = w; } }
; template <class Epi>
; DEVI void gemm_phase(const int wv, LAS unsigned char* lds, const Gemm g, const Order& S, const Epi& E) {
;     ...
;         if (!has_next) break;
;         cur = nxt; cA = nA; cB = nB; ++ui;
	v_max_f32_e32 v38, v38, v38
	v_max_f32_e32 v37, v37, v37
	v_add_f32_e32 v42, 1.0, v34
	v_max_f32_e32 v34, v39, v39
	v_add_f32_e32 v39, 1.0, v35
	v_max_f32_e32 v35, v40, v40
	v_add_f32_e32 v40, 1.0, v36
	v_max_f32_e32 v36, v41, v41
	v_med3_f32 v34, v34, s49, v238
	v_med3_f32 v35, v35, s49, v238
	v_med3_f32 v36, v36, s49, v238
	v_med3_f32 v38, v38, s49, v238
	v_mul_f32_e32 v34, 0xbfb8aa3b, v34
	v_mul_f32_e32 v35, 0xbfb8aa3b, v35
	v_mul_f32_e32 v36, 0xbfb8aa3b, v36
	v_med3_f32 v37, v37, s49, v238
	v_max_f32_e32 v26, v26, v26
	v_mul_f32_e32 v38, 0xbfb8aa3b, v38
	v_exp_f32_e32 v34, v34
	v_exp_f32_e32 v35, v35
	v_exp_f32_e32 v36, v36
	v_mul_f32_e32 v37, 0xbfb8aa3b, v37
	v_med3_f32 v26, v26, s49, v238
	v_max_f32_e32 v27, v27, v27
	v_max_f32_e32 v28, v28, v28
	v_exp_f32_e32 v38, v38
	v_exp_f32_e32 v37, v37
	v_mul_f32_e32 v26, 0xbfb8aa3b, v26
	v_med3_f32 v27, v27, s49, v238
	v_med3_f32 v28, v28, s49, v238
	v_exp_f32_e32 v26, v26
	v_mul_f32_e32 v27, 0xbfb8aa3b, v27
	v_mul_f32_e32 v28, 0xbfb8aa3b, v28
	v_exp_f32_e32 v27, v27
	v_exp_f32_e32 v28, v28
	v_add_f32_e32 v34, 1.0, v34
	v_add_f32_e32 v35, 1.0, v35
	v_add_f32_e32 v36, 1.0, v36
	v_add_f32_e32 v38, 1.0, v38
	v_add_f32_e32 v37, 1.0, v37
	v_cvt_pk_bf16_f32 v34, v38, v34
	v_cvt_pk_bf16_f32 v35, v35, v36
	v_cvt_pk_bf16_f32 v36, v42, v39
	v_cvt_pk_bf16_f32 v37, v40, v37
	global_store_dwordx4 v[50:51], v[34:37], off offset:256
	v_max_f32_e32 v30, v30, v30
	v_max_f32_e32 v29, v29, v29
	v_add_f32_e32 v36, 1.0, v26
	v_max_f32_e32 v26, v31, v31
	v_med3_f32 v26, v26, s49, v238
	v_add_f32_e32 v31, 1.0, v27
	v_max_f32_e32 v27, v32, v32
	v_add_f32_e32 v32, 1.0, v28
	v_max_f32_e32 v28, v33, v33
	v_med3_f32 v30, v30, s49, v238
	v_mul_f32_e32 v26, 0xbfb8aa3b, v26
	v_med3_f32 v27, v27, s49, v238
	v_med3_f32 v28, v28, s49, v238
	v_med3_f32 v29, v29, s49, v238
	v_max_f32_e32 v18, v18, v18
	v_max_f32_e32 v19, v19, v19
	v_max_f32_e32 v20, v20, v20
	v_mul_f32_e32 v30, 0xbfb8aa3b, v30
	v_exp_f32_e32 v26, v26
	v_mul_f32_e32 v27, 0xbfb8aa3b, v27
	v_mul_f32_e32 v28, 0xbfb8aa3b, v28
	v_mul_f32_e32 v29, 0xbfb8aa3b, v29
	v_med3_f32 v18, v18, s49, v238
	v_med3_f32 v19, v19, s49, v238
	v_med3_f32 v20, v20, s49, v238
	v_exp_f32_e32 v30, v30
	v_exp_f32_e32 v27, v27
	v_exp_f32_e32 v28, v28
	v_exp_f32_e32 v29, v29
	v_mul_f32_e32 v18, 0xbfb8aa3b, v18
	v_mul_f32_e32 v19, 0xbfb8aa3b, v19
	v_mul_f32_e32 v20, 0xbfb8aa3b, v20
	v_exp_f32_e32 v18, v18
	v_exp_f32_e32 v19, v19
	v_exp_f32_e32 v20, v20
	v_add_u32_e32 v34, 0xa0, v148
	v_mad_i64_i32 v[34:35], s[28:29], v34, s1, v[140:141]
	v_add_f32_e32 v26, 1.0, v26
	v_lshl_add_u64 v[34:35], v[34:35], 0, v[142:143]
	v_add_f32_e32 v30, 1.0, v30
	v_add_f32_e32 v27, 1.0, v27
	v_add_f32_e32 v28, 1.0, v28
	v_add_f32_e32 v29, 1.0, v29
	v_cvt_pk_bf16_f32 v26, v30, v26
	v_cvt_pk_bf16_f32 v27, v27, v28
	v_cvt_pk_bf16_f32 v28, v36, v31
	v_cvt_pk_bf16_f32 v29, v32, v29
	global_store_dwordx4 v[34:35], v[26:29], off
	v_max_f32_e32 v22, v22, v22
	v_max_f32_e32 v21, v21, v21
	v_add_f32_e32 v26, 1.0, v18
	v_max_f32_e32 v18, v23, v23
	v_add_f32_e32 v23, 1.0, v19
	v_max_f32_e32 v19, v24, v24
	v_add_f32_e32 v24, 1.0, v20
	v_max_f32_e32 v20, v25, v25
	v_med3_f32 v18, v18, s49, v238
	v_med3_f32 v19, v19, s49, v238
	v_med3_f32 v20, v20, s49, v238
	v_med3_f32 v22, v22, s49, v238
	v_mul_f32_e32 v18, 0xbfb8aa3b, v18
	v_mul_f32_e32 v19, 0xbfb8aa3b, v19
	v_mul_f32_e32 v20, 0xbfb8aa3b, v20
	v_med3_f32 v21, v21, s49, v238
	v_max_f32_e32 v10, v10, v10
	v_mul_f32_e32 v22, 0xbfb8aa3b, v22
	v_exp_f32_e32 v18, v18
	v_exp_f32_e32 v19, v19
	v_exp_f32_e32 v20, v20
	v_mul_f32_e32 v21, 0xbfb8aa3b, v21
	v_med3_f32 v10, v10, s49, v238
	v_max_f32_e32 v11, v11, v11
	v_max_f32_e32 v12, v12, v12
	v_exp_f32_e32 v22, v22
	v_exp_f32_e32 v21, v21
	v_mul_f32_e32 v10, 0xbfb8aa3b, v10
	v_med3_f32 v11, v11, s49, v238
	v_med3_f32 v12, v12, s49, v238
	v_exp_f32_e32 v10, v10
	v_mul_f32_e32 v11, 0xbfb8aa3b, v11
	v_mul_f32_e32 v12, 0xbfb8aa3b, v12
	v_exp_f32_e32 v11, v11
	v_exp_f32_e32 v12, v12
	v_add_f32_e32 v18, 1.0, v18
	v_add_f32_e32 v19, 1.0, v19
	v_add_f32_e32 v20, 1.0, v20
	v_add_f32_e32 v22, 1.0, v22
	v_add_f32_e32 v21, 1.0, v21
	v_cvt_pk_bf16_f32 v18, v22, v18
	v_cvt_pk_bf16_f32 v19, v19, v20
	v_cvt_pk_bf16_f32 v20, v26, v23
	v_cvt_pk_bf16_f32 v21, v24, v21
	global_store_dwordx4 v[34:35], v[18:21], off offset:256
	v_max_f32_e32 v14, v14, v14
	v_max_f32_e32 v13, v13, v13
	v_add_f32_e32 v20, 1.0, v10
	v_max_f32_e32 v10, v15, v15
	v_med3_f32 v10, v10, s49, v238
	v_add_f32_e32 v15, 1.0, v11
	v_max_f32_e32 v11, v16, v16
	v_add_f32_e32 v16, 1.0, v12
	v_max_f32_e32 v12, v17, v17
	v_med3_f32 v14, v14, s49, v238
	v_mul_f32_e32 v10, 0xbfb8aa3b, v10
	v_med3_f32 v11, v11, s49, v238
	v_med3_f32 v12, v12, s49, v238
	v_med3_f32 v13, v13, s49, v238
	v_max_f32_e32 v2, v2, v2
	v_max_f32_e32 v3, v3, v3
	v_max_f32_e32 v4, v4, v4
	v_mul_f32_e32 v14, 0xbfb8aa3b, v14
	v_exp_f32_e32 v10, v10
	v_mul_f32_e32 v11, 0xbfb8aa3b, v11
	v_mul_f32_e32 v12, 0xbfb8aa3b, v12
	v_mul_f32_e32 v13, 0xbfb8aa3b, v13
	v_med3_f32 v2, v2, s49, v238
	v_med3_f32 v3, v3, s49, v238
	v_med3_f32 v4, v4, s49, v238
	v_exp_f32_e32 v14, v14
	v_exp_f32_e32 v11, v11
	v_exp_f32_e32 v12, v12
	v_exp_f32_e32 v13, v13
	v_mul_f32_e32 v2, 0xbfb8aa3b, v2
	v_mul_f32_e32 v3, 0xbfb8aa3b, v3
	v_mul_f32_e32 v4, 0xbfb8aa3b, v4
	v_exp_f32_e32 v2, v2
	v_exp_f32_e32 v3, v3
	v_exp_f32_e32 v4, v4
	v_add_u32_e32 v18, 0xb0, v148
	v_mad_i64_i32 v[18:19], s[28:29], v18, s1, v[140:141]
	v_add_f32_e32 v10, 1.0, v10
	v_lshl_add_u64 v[18:19], v[18:19], 0, v[142:143]
	v_add_f32_e32 v14, 1.0, v14
	v_add_f32_e32 v11, 1.0, v11
	v_add_f32_e32 v12, 1.0, v12
	v_add_f32_e32 v13, 1.0, v13
	v_cvt_pk_bf16_f32 v10, v14, v10
	v_cvt_pk_bf16_f32 v11, v11, v12
	v_cvt_pk_bf16_f32 v12, v20, v15
	v_cvt_pk_bf16_f32 v13, v16, v13
	global_store_dwordx4 v[18:19], v[10:13], off
	v_max_f32_e32 v5, v5, v5
	v_max_f32_e32 v6, v6, v6
	v_add_f32_e32 v10, 1.0, v2
	v_max_f32_e32 v2, v7, v7
	v_add_f32_e32 v7, 1.0, v3
	v_max_f32_e32 v3, v8, v8
	v_add_f32_e32 v8, 1.0, v4
	v_max_f32_e32 v4, v9, v9
	v_med3_f32 v2, v2, s49, v238
	v_med3_f32 v3, v3, s49, v238
	v_med3_f32 v4, v4, s49, v238
	v_med3_f32 v5, v5, s49, v238
	v_med3_f32 v6, v6, s49, v238
	v_mul_f32_e32 v2, 0xbfb8aa3b, v2
	v_mul_f32_e32 v3, 0xbfb8aa3b, v3
	v_mul_f32_e32 v4, 0xbfb8aa3b, v4
	v_mul_f32_e32 v5, 0xbfb8aa3b, v5
	v_mul_f32_e32 v6, 0xbfb8aa3b, v6
	v_exp_f32_e32 v2, v2
	v_exp_f32_e32 v3, v3
	v_exp_f32_e32 v4, v4
	v_exp_f32_e32 v5, v5
	v_exp_f32_e32 v6, v6
	s_movk_i32 s47, 0x1800
	v_add_f32_e32 v2, 1.0, v2
	v_add_f32_e32 v3, 1.0, v3
	v_add_f32_e32 v4, 1.0, v4
	v_add_f32_e32 v5, 1.0, v5
	s_and_b64 vcc, exec, s[6:7]
	s_mov_b32 s10, s0
	s_mov_b32 s12, s2
	s_mov_b64 s[30:31], s[8:9]
	s_mov_b64 s[28:29], s[4:5]
	s_movk_i32 s55, 0xc00
	v_add_f32_e32 v6, 1.0, v6
	v_cvt_pk_bf16_f32 v2, v6, v2
	v_cvt_pk_bf16_f32 v3, v3, v4
	v_cvt_pk_bf16_f32 v4, v10, v7
	v_cvt_pk_bf16_f32 v5, v8, v5
	global_store_dwordx4 v[18:19], v[2:5], off offset:256
	s_cbranch_vccz .LBB0_809
	s_branch .LBB0_817

; #define PG8_STAGE(bufoff, gbase, voff) do { _Pragma("unroll") for (int _i = 0; _i < 2; ++_i) \
;         __builtin_amdgcn_global_load_lds((const unsigned*)((const char*)(gbase) + (voff)[_i]), (LAS unsigned*)(lds + (bufoff) + ldsw + _i * 8192), 16, 0, 0); } while (0)
; #define PG8_LDA(dst, b, h) do { _Pragma("unroll") for (int m = 0; m < 4; ++m) _Pragma("unroll") for (int k = 0; k < 2; ++k) dst[m][k] = *(const LAS bf16x8*)(lds + PG8_SA(b, h) + aoff + m * 2048 + k * 1024); } while (0)
; #define PG8_LDB(dst, b, h) do { _Pragma("unroll") for (int n = 0; n < 2; ++n) _Pragma("unroll") for (int k = 0; k < 2; ++k) dst[n][k] = *(const LAS bf16x8*)(lds + PG8_SB(b, h) + boff + n * 2048 + k * 1024); } while (0)
; #define PG8_MMA(ai, bj, At, Bt) do { __builtin_amdgcn_s_setprio(1); _Pragma("unroll") for (int m = 0; m < 4; ++m) _Pragma("unroll") for (int n = 0; n < 2; ++n) _Pragma("unroll") for (int k = 0; k < 2; ++k) \
;         acc[ai][bj][m][n] = __builtin_amdgcn_mfma_f32_16x16x32_bf16(Bt[n][k], At[m][k], acc[ai][bj][m][n], 0, 0, 0); __builtin_amdgcn_s_setprio(0); } while (0)
; template <class Epi>
; DEVI void gemm_phase(const int wv, LAS unsigned char* lds, const Gemm g, const Order& S, const Epi& E) {
;     ...
;     for (;;) {
;         const bool has_next = S.next(ui + 1, nxt);
;         const char* nA = has_next ? (const char*)g.A + (size_t)nxt.pb * g.a_bs + (size_t)nxt.pm * tstepA : cA;
;         const char* nB = has_next ? (const char*)g.Bt + (size_t)nxt.pb * g.b_bs + (size_t)nxt.pn * tstepB : cB;
;         for (int t = 0; t < nt; t += 2) {
;             const bool last = (t == nt - 2);
;             const char* a1 = cA + (size_t)(t + 1) * kstep;
;             const char* a2 = last ? nA : cA + (size_t)(t + 2) * kstep; const char* b2 = last ? nB : cB + (size_t)(t + 2) * kstep;
;             const char* a3 = a2 + kstep; const char* b3 = b2 + kstep;
;             PG8_LDB(B0, 0, 0); PG8_SCHED; PG8_LDA(At, 0, 0); PG8_STAGE(PG8_SA(1, 1), a1 + hstepA, voffA);
;             PG8_WAIT_L(8); PG8_BAR; PG8_WAIT_L(0); PG8_MMA(0, 0, At, B0); PG8_BAR; PG8_SCHED;
;             PG8_LDB(B1, 0, 1); PG8_STAGE(PG8_SB(0, 0), b2, voffB);
;             PG8_BAR; PG8_WAIT_L(0); PG8_MMA(0, 1, At, B1); PG8_BAR;
;             PG8_LDA(At, 0, 1); PG8_STAGE(PG8_SA(0, 0), a2, voffA);
;             PG8_BAR; PG8_WAIT_L(0); PG8_MMA(1, 0, At, B0); PG8_BAR; PG8_SCHED;
.LBB0_1072:
	s_ashr_i32 s13, s12, 31
	s_xor_b64 s[30:31], s[40:41], -1
	s_lshl_b64 s[28:29], s[12:13], 19
	s_add_u32 s28, s14, s28
	s_addc_u32 s29, s15, s29
	s_and_b64 s[36:37], s[40:41], exec
	s_cselect_b32 s3, s29, s7
	s_cselect_b32 s5, s28, s6
	s_ashr_i32 s11, s10, 31
	s_lshl_b64 s[36:37], s[10:11], 19
	v_readlane_b32 s60, v250, 35
	v_readlane_b32 s61, v250, 36
	s_add_u32 s36, s60, s36
	s_addc_u32 s37, s61, s37
	s_and_b64 s[40:41], s[40:41], exec
	s_cselect_b32 s11, s37, s39
	s_cselect_b32 s13, s36, s38
	s_add_u32 s6, s6, 0x40080
	s_addc_u32 s7, s7, 0
	s_add_u32 s60, s38, 0x100
	v_mov_b32_e32 v2, 0
	s_addc_u32 s61, s39, 0
	s_mov_b32 s62, -2
	s_waitcnt lgkmcnt(0)
	s_add_u32 s38, s6, 0xfffc0080
	s_addc_u32 s39, s7, -1
	s_add_i32 s63, 0, 0x10000
	v_add_u32_e32 v0, s63, v214
	ds_read_b128 v[54:57], v0
	ds_read_b128 v[58:61], v0 offset:1024
	ds_read_b128 v[66:69], v0 offset:2048
	ds_read_b128 v[70:73], v0 offset:3072
	s_cmp_eq_u32 s62, 12
	s_cselect_b32 s41, s3, s39
	s_cselect_b32 s40, s5, s38
	s_cselect_b32 s39, s11, s61
	s_cselect_b32 s38, s13, s60
	v_lshl_add_u64 v[178:179], s[6:7], 0, v[202:203]
	s_add_i32 m0, s51, 0xc000
	ds_read_b128 v[74:77], v216
	ds_read_b128 v[78:81], v216 offset:1024
	ds_read_b128 v[86:89], v216 offset:2048
	ds_read_b128 v[90:93], v216 offset:3072
	ds_read_b128 v[162:165], v216 offset:4096
	ds_read_b128 v[166:169], v216 offset:5120
	ds_read_b128 v[170:173], v216 offset:6144
	ds_read_b128 v[174:177], v216 offset:7168
	global_load_lds_dwordx4 v[178:179], off
	v_lshl_add_u64 v[178:179], s[6:7], 0, v[204:205]
	s_add_i32 m0, s51, 0xe000
	s_nop 0
	global_load_lds_dwordx4 v[178:179], off
	s_waitcnt lgkmcnt(8)
	s_barrier
	s_waitcnt lgkmcnt(0)
	s_setprio 1
	s_waitcnt lgkmcnt(0)
	v_mfma_f32_16x16x32_bf16 v[158:161], v[54:57], v[74:77], 0
	v_mfma_f32_16x16x32_bf16 v[154:157], v[66:69], v[74:77], 0
	v_mfma_f32_16x16x32_bf16 v[142:145], v[54:57], v[86:89], 0
	v_mfma_f32_16x16x32_bf16 v[138:141], v[66:69], v[86:89], 0
	v_mfma_f32_16x16x32_bf16 v[126:129], v[54:57], v[162:165], 0
	v_mfma_f32_16x16x32_bf16 v[122:125], v[66:69], v[162:165], 0
	v_mfma_f32_16x16x32_bf16 v[110:113], v[54:57], v[170:173], 0
	v_mfma_f32_16x16x32_bf16 v[106:109], v[66:69], v[170:173], 0
	v_mfma_f32_16x16x32_bf16 v[158:161], v[58:61], v[78:81], v[158:161]
	v_mfma_f32_16x16x32_bf16 v[154:157], v[70:73], v[78:81], v[154:157]
	v_mfma_f32_16x16x32_bf16 v[142:145], v[58:61], v[90:93], v[142:145]
	v_mfma_f32_16x16x32_bf16 v[138:141], v[70:73], v[90:93], v[138:141]
	v_mfma_f32_16x16x32_bf16 v[126:129], v[58:61], v[166:169], v[126:129]
	v_mfma_f32_16x16x32_bf16 v[122:125], v[70:73], v[166:169], v[122:125]
	v_mfma_f32_16x16x32_bf16 v[110:113], v[58:61], v[174:177], v[110:113]
	v_mfma_f32_16x16x32_bf16 v[106:109], v[70:73], v[174:177], v[106:109]
	s_setprio 0
	s_barrier
	s_add_i32 s66, 0, 0x14000
	s_add_i32 s63, s63, s95
	v_add_u32_e32 v0, s66, v214
	v_lshl_add_u64 v[218:219], s[38:39], 0, v[194:195]
	s_mov_b32 m0, s63
	ds_read_b128 v[178:181], v0
	ds_read_b128 v[182:185], v0 offset:1024
	ds_read_b128 v[186:189], v0 offset:2048
	ds_read_b128 v[190:193], v0 offset:3072
	global_load_lds_dwordx4 v[218:219], off
	v_lshl_add_u64 v[220:221], s[38:39], 0, v[200:201]
	s_add_i32 m0, s63, 0x2000
	s_nop 0
	global_load_lds_dwordx4 v[220:221], off
	s_barrier
	s_waitcnt lgkmcnt(0)
	s_setprio 1
	s_waitcnt lgkmcnt(0)
	v_mfma_f32_16x16x32_bf16 v[150:153], v[178:181], v[74:77], 0
	v_mfma_f32_16x16x32_bf16 v[74:77], v[186:189], v[74:77], 0
	v_mfma_f32_16x16x32_bf16 v[150:153], v[182:185], v[78:81], v[150:153]
	v_mfma_f32_16x16x32_bf16 v[74:77], v[190:193], v[78:81], v[74:77]
	v_mfma_f32_16x16x32_bf16 v[78:81], v[178:181], v[86:89], 0
	v_mfma_f32_16x16x32_bf16 v[86:89], v[186:189], v[86:89], 0
	v_mfma_f32_16x16x32_bf16 v[114:117], v[186:189], v[162:165], 0
	v_mfma_f32_16x16x32_bf16 v[102:105], v[178:181], v[170:173], 0
	v_mfma_f32_16x16x32_bf16 v[98:101], v[186:189], v[170:173], 0
	v_mfma_f32_16x16x32_bf16 v[78:81], v[182:185], v[90:93], v[78:81]
	v_mfma_f32_16x16x32_bf16 v[86:89], v[190:193], v[90:93], v[86:89]
	v_mfma_f32_16x16x32_bf16 v[90:93], v[178:181], v[162:165], 0
	v_mfma_f32_16x16x32_bf16 v[114:117], v[190:193], v[166:169], v[114:117]
	v_mfma_f32_16x16x32_bf16 v[102:105], v[182:185], v[174:177], v[102:105]
	v_mfma_f32_16x16x32_bf16 v[98:101], v[190:193], v[174:177], v[98:101]
	v_mfma_f32_16x16x32_bf16 v[90:93], v[182:185], v[166:169], v[90:93]
	s_setprio 0
	s_mov_b32 m0, s51
	v_lshl_add_u64 v[222:223], s[40:41], 0, v[194:195]
	s_barrier
	ds_read_b128 v[118:121], v216 offset:16384
	ds_read_b128 v[130:133], v216 offset:17408
	ds_read_b128 v[134:137], v216 offset:18432
	ds_read_b128 v[146:149], v216 offset:19456
	ds_read_b128 v[162:165], v216 offset:20480
	ds_read_b128 v[166:169], v216 offset:21504
	ds_read_b128 v[170:173], v216 offset:22528
	ds_read_b128 v[174:177], v216 offset:23552
	global_load_lds_dwordx4 v[222:223], off
	v_lshl_add_u64 v[240:241], s[40:41], 0, v[200:201]
	s_mov_b32 m0, s52
	s_nop 0
	global_load_lds_dwordx4 v[240:241], off
	s_barrier
	s_waitcnt lgkmcnt(0)
	s_setprio 1
	s_waitcnt lgkmcnt(0)
	v_mfma_f32_16x16x32_bf16 v[94:97], v[54:57], v[118:121], 0
	v_mfma_f32_16x16x32_bf16 v[82:85], v[66:69], v[118:121], 0
	v_mfma_f32_16x16x32_bf16 v[46:49], v[54:57], v[134:137], 0
	v_mfma_f32_16x16x32_bf16 v[42:45], v[66:69], v[134:137], 0
	v_mfma_f32_16x16x32_bf16 v[30:33], v[54:57], v[162:165], 0
	v_mfma_f32_16x16x32_bf16 v[26:29], v[66:69], v[162:165], 0
	v_mfma_f32_16x16x32_bf16 v[14:17], v[54:57], v[170:173], 0
	v_mfma_f32_16x16x32_bf16 v[10:13], v[66:69], v[170:173], 0
	v_mfma_f32_16x16x32_bf16 v[94:97], v[58:61], v[130:133], v[94:97]
	v_mfma_f32_16x16x32_bf16 v[82:85], v[70:73], v[130:133], v[82:85]
	v_mfma_f32_16x16x32_bf16 v[46:49], v[58:61], v[146:149], v[46:49]
	v_mfma_f32_16x16x32_bf16 v[42:45], v[70:73], v[146:149], v[42:45]
	v_mfma_f32_16x16x32_bf16 v[30:33], v[58:61], v[166:169], v[30:33]
	v_mfma_f32_16x16x32_bf16 v[26:29], v[70:73], v[166:169], v[26:29]
	v_mfma_f32_16x16x32_bf16 v[14:17], v[58:61], v[174:177], v[14:17]
	v_mfma_f32_16x16x32_bf16 v[10:13], v[70:73], v[174:177], v[10:13]
	s_setprio 0
	s_barrier
; #define PG8_STAGE(bufoff, gbase, voff) do { _Pragma("unroll") for (int _i = 0; _i < 2; ++_i) \
;         __builtin_amdgcn_global_load_lds((const unsigned*)((const char*)(gbase) + (voff)[_i]), (LAS unsigned*)(lds + (bufoff) + ldsw + _i * 8192), 16, 0, 0); } while (0)
; #define PG8_LDA(dst, b, h) do { _Pragma("unroll") for (int m = 0; m < 4; ++m) _Pragma("unroll") for (int k = 0; k < 2; ++k) dst[m][k] = *(const LAS bf16x8*)(lds + PG8_SA(b, h) + aoff + m * 2048 + k * 1024); } while (0)
; #define PG8_LDB(dst, b, h) do { _Pragma("unroll") for (int n = 0; n < 2; ++n) _Pragma("unroll") for (int k = 0; k < 2; ++k) dst[n][k] = *(const LAS bf16x8*)(lds + PG8_SB(b, h) + boff + n * 2048 + k * 1024); } while (0)
; #define PG8_MMA(ai, bj, At, Bt) do { __builtin_amdgcn_s_setprio(1); _Pragma("unroll") for (int m = 0; m < 4; ++m) _Pragma("unroll") for (int n = 0; n < 2; ++n) _Pragma("unroll") for (int k = 0; k < 2; ++k) \
;         acc[ai][bj][m][n] = __builtin_amdgcn_mfma_f32_16x16x32_bf16(Bt[n][k], At[m][k], acc[ai][bj][m][n], 0, 0, 0); __builtin_amdgcn_s_setprio(0); } while (0)
; #define PG8_WAIT_V(n) asm volatile("s_waitcnt vmcnt(" #n ")" ::: "memory")
; #define PG8_WAIT_L(n) asm volatile("s_waitcnt lgkmcnt(" #n ")" ::: "memory")
; #define PG8_BAR __builtin_amdgcn_s_barrier()
; #define PG8_SCHED __builtin_amdgcn_sched_barrier(0)
; template <class Epi>
; DEVI void gemm_phase(const int wv, LAS unsigned char* lds, const Gemm g, const Order& S, const Epi& E) {
;     ...
;             PG8_STAGE(PG8_SB(0, 1), b2 + hstepB, voffB);
;             PG8_WAIT_V(6); PG8_BAR; PG8_MMA(1, 1, At, B1); PG8_BAR;
;             PG8_LDB(B0, 1, 0); PG8_SCHED; PG8_LDA(At, 1, 0); PG8_STAGE(PG8_SA(0, 1), a2 + hstepA, voffA);
;             PG8_WAIT_L(8); PG8_BAR; PG8_WAIT_L(0); PG8_MMA(0, 0, At, B0); PG8_BAR; PG8_SCHED;
;             PG8_LDB(B1, 1, 1); PG8_STAGE(PG8_SB(1, 0), b3, voffB);
;             PG8_BAR; PG8_WAIT_L(0); PG8_MMA(0, 1, At, B1); PG8_BAR;
;             PG8_LDA(At, 1, 1); PG8_STAGE(PG8_SA(1, 0), a3, voffA);
;             PG8_BAR; PG8_WAIT_L(0); PG8_MMA(1, 0, At, B0); PG8_BAR; PG8_SCHED;
	s_add_u32 s64, s38, 0x40000
	s_addc_u32 s65, s39, 0
	s_add_i32 s63, s66, s95
	v_lshl_add_u64 v[54:55], s[64:65], 0, v[194:195]
	s_mov_b32 m0, s63
	s_nop 0
	global_load_lds_dwordx4 v[54:55], off
	v_lshl_add_u64 v[54:55], s[64:65], 0, v[200:201]
	s_add_i32 m0, s63, 0x2000
	s_nop 0
	global_load_lds_dwordx4 v[54:55], off
	s_waitcnt vmcnt(6)
	s_barrier
	s_setprio 1
	v_mfma_f32_16x16x32_bf16 v[50:53], v[186:189], v[118:121], 0
	v_mfma_f32_16x16x32_bf16 v[38:41], v[178:181], v[134:137], 0
	v_mfma_f32_16x16x32_bf16 v[34:37], v[186:189], v[134:137], 0
	v_mfma_f32_16x16x32_bf16 v[22:25], v[178:181], v[162:165], 0
	v_mfma_f32_16x16x32_bf16 v[18:21], v[186:189], v[162:165], 0
	v_mfma_f32_16x16x32_bf16 v[6:9], v[178:181], v[170:173], 0
	v_mfma_f32_16x16x32_bf16 v[2:5], v[186:189], v[170:173], 0
	v_mfma_f32_16x16x32_bf16 v[54:57], v[178:181], v[118:121], 0
	v_mfma_f32_16x16x32_bf16 v[50:53], v[190:193], v[130:133], v[50:53]
	v_mfma_f32_16x16x32_bf16 v[38:41], v[182:185], v[146:149], v[38:41]
	v_mfma_f32_16x16x32_bf16 v[34:37], v[190:193], v[146:149], v[34:37]
	v_mfma_f32_16x16x32_bf16 v[22:25], v[182:185], v[166:169], v[22:25]
	v_mfma_f32_16x16x32_bf16 v[18:21], v[190:193], v[166:169], v[18:21]
	v_mfma_f32_16x16x32_bf16 v[6:9], v[182:185], v[174:177], v[6:9]
	v_mfma_f32_16x16x32_bf16 v[2:5], v[190:193], v[174:177], v[2:5]
	v_mfma_f32_16x16x32_bf16 v[54:57], v[182:185], v[130:133], v[54:57]
	s_setprio 0
	s_add_i32 s63, 0, 0x18000
	v_add_u32_e32 v0, s63, v214
	s_barrier
	ds_read_b128 v[58:61], v0
	ds_read_b128 v[62:65], v0 offset:1024
	ds_read_b128 v[66:69], v0 offset:2048
	ds_read_b128 v[70:73], v0 offset:3072
	s_add_u32 s40, s40, 0x40000
	s_addc_u32 s41, s41, 0
	s_mov_b32 m0, s53
	v_lshl_add_u64 v[134:135], s[40:41], 0, v[194:195]
	ds_read_b128 v[118:121], v216 offset:32768
	ds_read_b128 v[130:133], v216 offset:33792
	ds_read_b128 v[162:165], v216 offset:34816
	ds_read_b128 v[166:169], v216 offset:35840
	ds_read_b128 v[170:173], v216 offset:36864
	ds_read_b128 v[174:177], v216 offset:37888
	ds_read_b128 v[178:181], v216 offset:38912
	ds_read_b128 v[182:185], v216 offset:39936
	global_load_lds_dwordx4 v[134:135], off
	v_lshl_add_u64 v[134:135], s[40:41], 0, v[200:201]
	s_mov_b32 m0, s54
	s_nop 0
	global_load_lds_dwordx4 v[134:135], off
	s_waitcnt lgkmcnt(8)
	s_barrier
	s_waitcnt lgkmcnt(0)
	s_setprio 1
	s_waitcnt lgkmcnt(0)
	v_mfma_f32_16x16x32_bf16 v[134:137], v[58:61], v[118:121], v[158:161]
	v_mfma_f32_16x16x32_bf16 v[158:161], v[62:65], v[130:133], v[134:137]
	v_mfma_f32_16x16x32_bf16 v[134:137], v[66:69], v[118:121], v[154:157]
	v_mfma_f32_16x16x32_bf16 v[154:157], v[70:73], v[130:133], v[134:137]
	v_mfma_f32_16x16x32_bf16 v[134:137], v[58:61], v[162:165], v[142:145]
	v_mfma_f32_16x16x32_bf16 v[142:145], v[62:65], v[166:169], v[134:137]
	v_mfma_f32_16x16x32_bf16 v[134:137], v[66:69], v[162:165], v[138:141]
	v_mfma_f32_16x16x32_bf16 v[126:129], v[58:61], v[170:173], v[126:129]
	v_mfma_f32_16x16x32_bf16 v[122:125], v[66:69], v[170:173], v[122:125]
	v_mfma_f32_16x16x32_bf16 v[110:113], v[58:61], v[178:181], v[110:113]
	v_mfma_f32_16x16x32_bf16 v[106:109], v[66:69], v[178:181], v[106:109]
	v_mfma_f32_16x16x32_bf16 v[138:141], v[70:73], v[166:169], v[134:137]
	v_mfma_f32_16x16x32_bf16 v[126:129], v[62:65], v[174:177], v[126:129]
	v_mfma_f32_16x16x32_bf16 v[122:125], v[70:73], v[174:177], v[122:125]
	v_mfma_f32_16x16x32_bf16 v[110:113], v[62:65], v[182:185], v[110:113]
	v_mfma_f32_16x16x32_bf16 v[106:109], v[70:73], v[182:185], v[106:109]
	s_setprio 0
	s_barrier
	s_add_i32 s40, 0, 0x1c000
	s_add_i32 s41, s63, s95
	v_add_u32_e32 v0, s40, v214
	v_lshl_add_u64 v[134:135], v[218:219], 0, s[92:93]
	s_mov_b32 m0, s41
	ds_read_b128 v[186:189], v0
	ds_read_b128 v[190:193], v0 offset:1024
	ds_read_b128 v[206:209], v0 offset:2048
	ds_read_b128 v[210:213], v0 offset:3072
	global_load_lds_dwordx4 v[134:135], off
	v_lshl_add_u64 v[134:135], v[220:221], 0, s[92:93]
	s_add_i32 m0, s41, 0x2000
	s_nop 0
	global_load_lds_dwordx4 v[134:135], off
	s_barrier
; #define PG8_STAGE(bufoff, gbase, voff) do { _Pragma("unroll") for (int _i = 0; _i < 2; ++_i) \
;         __builtin_amdgcn_global_load_lds((const unsigned*)((const char*)(gbase) + (voff)[_i]), (LAS unsigned*)(lds + (bufoff) + ldsw + _i * 8192), 16, 0, 0); } while (0)
; #define PG8_MMA(ai, bj, At, Bt) do { __builtin_amdgcn_s_setprio(1); _Pragma("unroll") for (int m = 0; m < 4; ++m) _Pragma("unroll") for (int n = 0; n < 2; ++n) _Pragma("unroll") for (int k = 0; k < 2; ++k) \
;         acc[ai][bj][m][n] = __builtin_amdgcn_mfma_f32_16x16x32_bf16(Bt[n][k], At[m][k], acc[ai][bj][m][n], 0, 0, 0); __builtin_amdgcn_s_setprio(0); } while (0)
; #define PG8_WAIT_V(n) asm volatile("s_waitcnt vmcnt(" #n ")" ::: "memory")
; #define PG8_WAIT_L(n) asm volatile("s_waitcnt lgkmcnt(" #n ")" ::: "memory")
; #define PG8_BAR __builtin_amdgcn_s_barrier()
; #define PG8_SCHED __builtin_amdgcn_sched_barrier(0)
; template <class Epi>
; DEVI void gemm_phase(const int wv, LAS unsigned char* lds, const Gemm g, const Order& S, const Epi& E) {
;     ...
;             PG8_BAR; PG8_WAIT_L(0); PG8_MMA(1, 0, At, B0); PG8_BAR; PG8_SCHED;
;             PG8_STAGE(PG8_SB(1, 1), b3 + hstepB, voffB);
;             PG8_WAIT_V(6); PG8_BAR; PG8_MMA(1, 1, At, B1); PG8_BAR;
;         }
	s_waitcnt lgkmcnt(0)
	s_setprio 1
	s_waitcnt lgkmcnt(0)
	v_mfma_f32_16x16x32_bf16 v[74:77], v[206:209], v[118:121], v[74:77]
	v_mfma_f32_16x16x32_bf16 v[134:137], v[186:189], v[118:121], v[150:153]
	v_mfma_f32_16x16x32_bf16 v[146:149], v[210:213], v[130:133], v[74:77]
	v_mfma_f32_16x16x32_bf16 v[74:77], v[186:189], v[162:165], v[78:81]
	v_mfma_f32_16x16x32_bf16 v[150:153], v[190:193], v[130:133], v[134:137]
	v_mfma_f32_16x16x32_bf16 v[134:137], v[190:193], v[166:169], v[74:77]
	v_mfma_f32_16x16x32_bf16 v[74:77], v[206:209], v[162:165], v[86:89]
	v_mfma_f32_16x16x32_bf16 v[130:133], v[210:213], v[166:169], v[74:77]
	v_mfma_f32_16x16x32_bf16 v[74:77], v[186:189], v[170:173], v[90:93]
	v_mfma_f32_16x16x32_bf16 v[118:121], v[190:193], v[174:177], v[74:77]
	v_mfma_f32_16x16x32_bf16 v[74:77], v[206:209], v[170:173], v[114:117]
	v_mfma_f32_16x16x32_bf16 v[114:117], v[210:213], v[174:177], v[74:77]
	v_mfma_f32_16x16x32_bf16 v[74:77], v[186:189], v[178:181], v[102:105]
	v_mfma_f32_16x16x32_bf16 v[102:105], v[190:193], v[182:185], v[74:77]
	v_mfma_f32_16x16x32_bf16 v[74:77], v[206:209], v[178:181], v[98:101]
	v_mfma_f32_16x16x32_bf16 v[98:101], v[210:213], v[182:185], v[74:77]
	s_setprio 0
	s_mov_b32 m0, s55
	v_lshl_add_u64 v[178:179], v[222:223], 0, s[92:93]
	s_barrier
	s_nop 2
	ds_read_b128 v[74:77], v216 offset:49152
	ds_read_b128 v[78:81], v216 offset:50176
	ds_read_b128 v[86:89], v216 offset:51200
	ds_read_b128 v[90:93], v216 offset:52224
	ds_read_b128 v[162:165], v216 offset:53248
	ds_read_b128 v[166:169], v216 offset:54272
	ds_read_b128 v[170:173], v216 offset:55296
	ds_read_b128 v[174:177], v216 offset:56320
	global_load_lds_dwordx4 v[178:179], off
	v_lshl_add_u64 v[178:179], v[240:241], 0, s[92:93]
	s_mov_b32 m0, s56
	s_nop 0
	global_load_lds_dwordx4 v[178:179], off
	s_barrier
	s_waitcnt lgkmcnt(0)
	s_setprio 1
	s_waitcnt lgkmcnt(0)
	v_mfma_f32_16x16x32_bf16 v[94:97], v[58:61], v[74:77], v[94:97]
	v_mfma_f32_16x16x32_bf16 v[82:85], v[66:69], v[74:77], v[82:85]
	v_mfma_f32_16x16x32_bf16 v[46:49], v[58:61], v[86:89], v[46:49]
	v_mfma_f32_16x16x32_bf16 v[42:45], v[66:69], v[86:89], v[42:45]
	v_mfma_f32_16x16x32_bf16 v[30:33], v[58:61], v[162:165], v[30:33]
	v_mfma_f32_16x16x32_bf16 v[26:29], v[66:69], v[162:165], v[26:29]
	v_mfma_f32_16x16x32_bf16 v[14:17], v[58:61], v[170:173], v[14:17]
	v_mfma_f32_16x16x32_bf16 v[10:13], v[66:69], v[170:173], v[10:13]
	v_mfma_f32_16x16x32_bf16 v[94:97], v[62:65], v[78:81], v[94:97]
	v_mfma_f32_16x16x32_bf16 v[82:85], v[70:73], v[78:81], v[82:85]
	v_mfma_f32_16x16x32_bf16 v[46:49], v[62:65], v[90:93], v[46:49]
	v_mfma_f32_16x16x32_bf16 v[42:45], v[70:73], v[90:93], v[42:45]
	v_mfma_f32_16x16x32_bf16 v[30:33], v[62:65], v[166:169], v[30:33]
	v_mfma_f32_16x16x32_bf16 v[26:29], v[70:73], v[166:169], v[26:29]
	v_mfma_f32_16x16x32_bf16 v[14:17], v[62:65], v[174:177], v[14:17]
	v_mfma_f32_16x16x32_bf16 v[10:13], v[70:73], v[174:177], v[10:13]
	s_setprio 0
	s_barrier
	s_add_u32 s38, s38, 0x40080
	s_addc_u32 s39, s39, 0
	s_add_i32 s40, s40, s95
	v_lshl_add_u64 v[58:59], s[38:39], 0, v[194:195]
	s_mov_b32 m0, s40
	s_nop 0
	global_load_lds_dwordx4 v[58:59], off
	v_lshl_add_u64 v[58:59], s[38:39], 0, v[200:201]
	s_add_i32 m0, s40, 0x2000
	s_nop 0
	global_load_lds_dwordx4 v[58:59], off
	s_waitcnt vmcnt(6)
	s_barrier
	s_setprio 1
	v_mfma_f32_16x16x32_bf16 v[54:57], v[186:189], v[74:77], v[54:57]
	v_mfma_f32_16x16x32_bf16 v[50:53], v[206:209], v[74:77], v[50:53]
	v_mfma_f32_16x16x32_bf16 v[38:41], v[186:189], v[86:89], v[38:41]
	v_mfma_f32_16x16x32_bf16 v[34:37], v[206:209], v[86:89], v[34:37]
	v_mfma_f32_16x16x32_bf16 v[22:25], v[186:189], v[162:165], v[22:25]
	v_mfma_f32_16x16x32_bf16 v[18:21], v[206:209], v[162:165], v[18:21]
	v_mfma_f32_16x16x32_bf16 v[6:9], v[186:189], v[170:173], v[6:9]
	v_mfma_f32_16x16x32_bf16 v[2:5], v[206:209], v[170:173], v[2:5]
	v_mfma_f32_16x16x32_bf16 v[62:65], v[190:193], v[78:81], v[54:57]
	v_mfma_f32_16x16x32_bf16 v[50:53], v[210:213], v[78:81], v[50:53]
	v_mfma_f32_16x16x32_bf16 v[38:41], v[190:193], v[90:93], v[38:41]
	v_mfma_f32_16x16x32_bf16 v[34:37], v[210:213], v[90:93], v[34:37]
	v_mfma_f32_16x16x32_bf16 v[22:25], v[190:193], v[166:169], v[22:25]
	v_mfma_f32_16x16x32_bf16 v[18:21], v[210:213], v[166:169], v[18:21]
	v_mfma_f32_16x16x32_bf16 v[6:9], v[190:193], v[174:177], v[6:9]
	v_mfma_f32_16x16x32_bf16 v[2:5], v[210:213], v[174:177], v[2:5]
	s_setprio 0
	s_add_i32 s62, s62, 2
	s_add_u32 s6, s6, 0x100
	s_addc_u32 s7, s7, 0
	s_add_u32 s60, s60, 0x100
	s_addc_u32 s61, s61, 0
	s_cmp_gt_u32 s62, 13
	s_barrier
	s_cbranch_scc0 .LBB0_1073
	s_branch .Lzp_epi_2

; DEVI const float* modrow(const Params& p, int l, int row) { const int bi = row < NLAT ? (row >> 11) : 16; return (const float*)(p.ws + OFF_MOD) + (size_t)(l * 17 + bi) * 6144; }
;     DEVI void operator()(f32x4 (&acc)[2][2][4][2], const Unit& u, int wr, int wc, int fr, int fq) const {
;         const int row0 = u.pm * BM + wr * 64 + fr, col0 = u.pn * BM + wc * 32 + 4 * fq;
;         const float* gr = modrow(p, l, u.pm * BM) + goff + col0;
;         f32x4 gv[2][2];
; #pragma unroll
;         for (int bj = 0; bj < 2; ++bj)
; #pragma unroll
;             for (int n = 0; n < 2; ++n) gv[bj][n] = *(const f32x4*)(gr + bj * HALF + n * 16);
;         f32x4 av[2][2];
;         if (emit) { const int bi = u.pm * BM < NLAT ? (u.pm * BM) >> 11 : 16; const float* ar = (const float*)(p.ws + OFF_A2) + (size_t)(l * 17 + bi) * 1024 + col0;
; #pragma unroll
;             for (int bj = 0; bj < 2; ++bj)
; #pragma unroll
;                 for (int n = 0; n < 2; ++n) av[bj][n] = *(const f32x4*)(ar + bj * HALF + n * 16); }
; #pragma unroll
;         for (int am = 0; am < 4; ++am) {
;             const int ai = am >> 1, mb = (am & 1) * 2;
;             f32x4 xv[2][2][2];
; #pragma unroll
;             for (int mm = 0; mm < 2; ++mm) { const int r = row0 + ai * HALF + (mb + mm) * 16;
;                 const float* xi = (in_is_stream ? (const float*)xrow_out(p, r) : xrow_in(p, l, r)) + col0;
.Lzp_epi_2:
	s_lshl_b32 s6, s2, 8
	s_min_i32 s3, s6, 0x8000
	s_ashr_i32 s3, s3, 11
	s_add_i32 s3, s3, s59
	s_mul_hi_i32 s5, s3, 0x6000
	s_mulk_i32 s3, 0x6000
	v_lshl_or_b32 v206, s4, 8, v215
	s_add_u32 s4, s24, s3
	s_addc_u32 s5, s25, s5
	v_ashrrev_i32_e32 v207, 31, v206
	s_min_i32 s2, s2, 0x80
	v_lshlrev_b64 v[210:211], 2, v[206:207]
	s_ashr_i32 s2, s2, 3
	v_lshl_add_u64 v[54:55], s[4:5], 0, v[210:211]
	s_mov_b64 s[4:5], 0x1e082000
	s_mov_b32 s3, 0x1e082000
	s_add_i32 s2, s2, s59
	v_lshl_add_u64 v[56:57], v[54:55], 0, s[4:5]
	v_add_co_u32_e32 v54, vcc, s3, v54
	s_ashr_i32 s3, s2, 31
	s_lshl_b64 s[2:3], s[2:3], 12
	v_readlane_b32 s4, v252, 40
	v_readlane_b32 s5, v252, 41
	s_add_u32 s2, s4, s2
	v_addc_co_u32_e32 v55, vcc, 0, v55, vcc
	s_addc_u32 s3, s5, s3
	global_load_dwordx4 v[74:77], v[56:57], off offset:64
	global_load_dwordx4 v[66:69], v[56:57], off offset:512
	global_load_dwordx4 v[86:89], v[54:55], off
	global_load_dwordx4 v[58:61], v[56:57], off offset:576
	v_lshl_add_u64 v[54:55], s[2:3], 0, v[210:211]
	global_load_dwordx4 v[90:93], v[54:55], off
	global_load_dwordx4 v[78:81], v[54:55], off offset:64
	global_load_dwordx4 v[70:73], v[54:55], off offset:512
	s_nop 0
	global_load_dwordx4 v[54:57], v[54:55], off offset:576
	v_add_u32_e32 v208, s6, v199
	s_mov_b32 s2, 0x8000
	v_readlane_b32 s38, v253, 33
	v_cmp_gt_i32_e64 s[4:5], s2, v208
	s_movk_i32 s2, 0x7fff
	v_readlane_b32 s39, v253, 34
	v_cmp_lt_i32_e64 s[2:3], s2, v208
	s_mov_b64 s[6:7], -1
	s_and_b64 vcc, exec, s[38:39]
	s_cbranch_vccz .LBB0_1080
	v_mov_b64_e32 v[162:163], s[22:23]
	s_and_saveexec_b64 s[6:7], s[2:3]
	s_xor_b64 s[6:7], exec, s[6:7]
	v_add_u32_e32 v0, 0xffff8000, v208
	v_mov_b64_e32 v[162:163], s[16:17]
	v_mov_b64_e32 v[164:165], v[0:1]
	s_andn2_saveexec_b64 s[6:7], s[6:7]
	v_ashrrev_i32_e32 v209, 31, v208
	v_mov_b64_e32 v[164:165], v[208:209]
	s_or_b64 exec, exec, s[6:7]
	s_mov_b64 s[6:7], 0

; #define PG8_STAGE(bufoff, gbase, voff) do { _Pragma("unroll") for (int _i = 0; _i < 2; ++_i) \
;         __builtin_amdgcn_global_load_lds((const unsigned*)((const char*)(gbase) + (voff)[_i]), (LAS unsigned*)(lds + (bufoff) + ldsw + _i * 8192), 16, 0, 0); } while (0)
; #define PG8_LDA(dst, b, h) do { _Pragma("unroll") for (int m = 0; m < 4; ++m) _Pragma("unroll") for (int k = 0; k < 2; ++k) dst[m][k] = *(const LAS bf16x8*)(lds + PG8_SA(b, h) + aoff + m * 2048 + k * 1024); } while (0)
; #define PG8_LDB(dst, b, h) do { _Pragma("unroll") for (int n = 0; n < 2; ++n) _Pragma("unroll") for (int k = 0; k < 2; ++k) dst[n][k] = *(const LAS bf16x8*)(lds + PG8_SB(b, h) + boff + n * 2048 + k * 1024); } while (0)
; #define PG8_MMA(ai, bj, At, Bt) do { __builtin_amdgcn_s_setprio(1); _Pragma("unroll") for (int m = 0; m < 4; ++m) _Pragma("unroll") for (int n = 0; n < 2; ++n) _Pragma("unroll") for (int k = 0; k < 2; ++k) \
;         acc[ai][bj][m][n] = __builtin_amdgcn_mfma_f32_16x16x32_bf16(Bt[n][k], At[m][k], acc[ai][bj][m][n], 0, 0, 0); __builtin_amdgcn_s_setprio(0); } while (0)
; template <class Epi>
; DEVI void gemm_phase(const int wv, LAS unsigned char* lds, const Gemm g, const Order& S, const Epi& E) {
;     ...
;     for (;;) {
;         const bool has_next = S.next(ui + 1, nxt);
;         const char* nA = has_next ? (const char*)g.A + (size_t)nxt.pb * g.a_bs + (size_t)nxt.pm * tstepA : cA;
;         const char* nB = has_next ? (const char*)g.Bt + (size_t)nxt.pb * g.b_bs + (size_t)nxt.pn * tstepB : cB;
;         for (int t = 0; t < nt; t += 2) {
;             const bool last = (t == nt - 2);
;             const char* a1 = cA + (size_t)(t + 1) * kstep;
;             const char* a2 = last ? nA : cA + (size_t)(t + 2) * kstep; const char* b2 = last ? nB : cB + (size_t)(t + 2) * kstep;
;             const char* a3 = a2 + kstep; const char* b3 = b2 + kstep;
;             PG8_LDB(B0, 0, 0); PG8_SCHED; PG8_LDA(At, 0, 0); PG8_STAGE(PG8_SA(1, 1), a1 + hstepA, voffA);
;             PG8_WAIT_L(8); PG8_BAR; PG8_WAIT_L(0); PG8_MMA(0, 0, At, B0); PG8_BAR; PG8_SCHED;
;             PG8_LDB(B1, 0, 1); PG8_STAGE(PG8_SB(0, 0), b2, voffB);
;             PG8_BAR; PG8_WAIT_L(0); PG8_MMA(0, 1, At, B1); PG8_BAR;
;             PG8_LDA(At, 0, 1); PG8_STAGE(PG8_SA(0, 0), a2, voffA);
;             PG8_BAR; PG8_WAIT_L(0); PG8_MMA(1, 0, At, B0); PG8_BAR; PG8_SCHED;
.LBB0_1282:
	s_ashr_i32 s5, s4, 31
	s_xor_b64 s[10:11], s[36:37], -1
	s_lshl_b64 s[6:7], s[4:5], 19
	s_add_u32 s6, s24, s6
	s_addc_u32 s7, s25, s7
	s_and_b64 s[8:9], s[36:37], exec
	s_cselect_b32 s5, s7, s31
	s_cselect_b32 s55, s6, s30
	s_ashr_i32 s3, s2, 31
	s_lshl_b64 s[8:9], s[2:3], 19
	v_readlane_b32 s56, v250, 33
	v_readlane_b32 s57, v250, 34
	s_add_u32 s8, s56, s8
	s_addc_u32 s9, s57, s9
	s_and_b64 s[36:37], s[36:37], exec
	s_cselect_b32 s3, s9, s35
	s_cselect_b32 s56, s8, s34
	s_add_u32 s30, s30, 0x40080
	s_addc_u32 s31, s31, 0
	s_add_u32 s57, s34, 0x100
	v_mov_b32_e32 v2, 0
	s_addc_u32 s58, s35, 0
	s_mov_b32 s59, -2
	s_add_u32 s34, s30, 0xfffc0080
	s_addc_u32 s35, s31, -1
	s_add_i32 s60, 0, 0x10000
	v_add_u32_e32 v62, s60, v165
	ds_read_b128 v[42:45], v62
	ds_read_b128 v[46:49], v62 offset:1024
	ds_read_b128 v[58:61], v62 offset:2048
	ds_read_b128 v[62:65], v62 offset:3072
	s_cmp_eq_u32 s59, 12
	s_cselect_b32 s37, s5, s35
	s_cselect_b32 s36, s55, s34
	s_cselect_b32 s35, s3, s58
	s_cselect_b32 s34, s56, s57
	v_lshl_add_u64 v[192:193], s[30:31], 0, v[152:153]
	s_add_i32 m0, s13, 0xc000
	ds_read_b128 v[156:159], v167
	ds_read_b128 v[160:163], v167 offset:1024
	ds_read_b128 v[168:171], v167 offset:2048
	ds_read_b128 v[172:175], v167 offset:3072
	ds_read_b128 v[176:179], v167 offset:4096
	ds_read_b128 v[180:183], v167 offset:5120
	ds_read_b128 v[184:187], v167 offset:6144
	ds_read_b128 v[188:191], v167 offset:7168
	global_load_lds_dwordx4 v[192:193], off
	v_lshl_add_u64 v[192:193], s[30:31], 0, v[154:155]
	s_add_i32 m0, s13, 0xe000
	s_nop 0
	global_load_lds_dwordx4 v[192:193], off
	s_waitcnt lgkmcnt(8)
	s_barrier
	s_waitcnt lgkmcnt(0)
	s_setprio 1
	s_waitcnt lgkmcnt(0)
	v_mfma_f32_16x16x32_bf16 v[142:145], v[42:45], v[156:159], 0
	v_mfma_f32_16x16x32_bf16 v[138:141], v[58:61], v[156:159], 0
	v_mfma_f32_16x16x32_bf16 v[126:129], v[42:45], v[168:171], 0
	v_mfma_f32_16x16x32_bf16 v[122:125], v[58:61], v[168:171], 0
	v_mfma_f32_16x16x32_bf16 v[110:113], v[42:45], v[176:179], 0
	v_mfma_f32_16x16x32_bf16 v[106:109], v[58:61], v[176:179], 0
	v_mfma_f32_16x16x32_bf16 v[94:97], v[42:45], v[184:187], 0
	v_mfma_f32_16x16x32_bf16 v[90:93], v[58:61], v[184:187], 0
	v_mfma_f32_16x16x32_bf16 v[142:145], v[46:49], v[160:163], v[142:145]
	v_mfma_f32_16x16x32_bf16 v[138:141], v[62:65], v[160:163], v[138:141]
	v_mfma_f32_16x16x32_bf16 v[126:129], v[46:49], v[172:175], v[126:129]
	v_mfma_f32_16x16x32_bf16 v[122:125], v[62:65], v[172:175], v[122:125]
	v_mfma_f32_16x16x32_bf16 v[110:113], v[46:49], v[180:183], v[110:113]
	v_mfma_f32_16x16x32_bf16 v[106:109], v[62:65], v[180:183], v[106:109]
	v_mfma_f32_16x16x32_bf16 v[94:97], v[46:49], v[188:191], v[94:97]
	v_mfma_f32_16x16x32_bf16 v[90:93], v[62:65], v[188:191], v[90:93]
	s_setprio 0
	s_barrier
	s_add_i32 s62, 0, 0x14000
	s_add_i32 s60, s60, s95
	v_add_u32_e32 v199, s62, v165
	v_lshl_add_u64 v[212:213], s[34:35], 0, v[0:1]
	s_mov_b32 m0, s60
	ds_read_b128 v[192:195], v199
	ds_read_b128 v[200:203], v199 offset:1024
	ds_read_b128 v[204:207], v199 offset:2048
	ds_read_b128 v[208:211], v199 offset:3072
	global_load_lds_dwordx4 v[212:213], off
	v_lshl_add_u64 v[214:215], s[34:35], 0, v[146:147]
	s_add_i32 m0, s60, 0x2000
	s_nop 0
	global_load_lds_dwordx4 v[214:215], off
	s_barrier
	s_waitcnt lgkmcnt(0)
	s_setprio 1
	s_waitcnt lgkmcnt(0)
	v_mfma_f32_16x16x32_bf16 v[134:137], v[192:195], v[156:159], 0
	v_mfma_f32_16x16x32_bf16 v[130:133], v[204:207], v[156:159], 0
	v_mfma_f32_16x16x32_bf16 v[118:121], v[192:195], v[168:171], 0
	v_mfma_f32_16x16x32_bf16 v[114:117], v[204:207], v[168:171], 0
	v_mfma_f32_16x16x32_bf16 v[102:105], v[192:195], v[176:179], 0
	v_mfma_f32_16x16x32_bf16 v[98:101], v[204:207], v[176:179], 0
	v_mfma_f32_16x16x32_bf16 v[86:89], v[192:195], v[184:187], 0
	v_mfma_f32_16x16x32_bf16 v[82:85], v[204:207], v[184:187], 0
	v_mfma_f32_16x16x32_bf16 v[134:137], v[200:203], v[160:163], v[134:137]
	v_mfma_f32_16x16x32_bf16 v[130:133], v[208:211], v[160:163], v[130:133]
	v_mfma_f32_16x16x32_bf16 v[118:121], v[200:203], v[172:175], v[118:121]
	v_mfma_f32_16x16x32_bf16 v[114:117], v[208:211], v[172:175], v[114:117]
	v_mfma_f32_16x16x32_bf16 v[102:105], v[200:203], v[180:183], v[102:105]
	v_mfma_f32_16x16x32_bf16 v[98:101], v[208:211], v[180:183], v[98:101]
	v_mfma_f32_16x16x32_bf16 v[86:89], v[200:203], v[188:191], v[86:89]
	v_mfma_f32_16x16x32_bf16 v[82:85], v[208:211], v[188:191], v[82:85]
	s_setprio 0
	s_mov_b32 m0, s13
	v_lshl_add_u64 v[216:217], s[36:37], 0, v[150:151]
	s_barrier
	ds_read_b128 v[156:159], v167 offset:16384
	ds_read_b128 v[160:163], v167 offset:17408
	ds_read_b128 v[168:171], v167 offset:18432
	ds_read_b128 v[172:175], v167 offset:19456
	ds_read_b128 v[176:179], v167 offset:20480
	ds_read_b128 v[180:183], v167 offset:21504
	ds_read_b128 v[184:187], v167 offset:22528
	ds_read_b128 v[188:191], v167 offset:23552
	global_load_lds_dwordx4 v[216:217], off
	v_lshl_add_u64 v[218:219], s[36:37], 0, v[148:149]
	s_mov_b32 m0, s29
	s_nop 0
	global_load_lds_dwordx4 v[218:219], off
	s_barrier
	s_waitcnt lgkmcnt(0)
	s_setprio 1
	s_waitcnt lgkmcnt(0)
	v_mfma_f32_16x16x32_bf16 v[78:81], v[42:45], v[156:159], 0
	v_mfma_f32_16x16x32_bf16 v[74:77], v[58:61], v[156:159], 0
	v_mfma_f32_16x16x32_bf16 v[54:57], v[42:45], v[168:171], 0
	v_mfma_f32_16x16x32_bf16 v[50:53], v[58:61], v[168:171], 0
	v_mfma_f32_16x16x32_bf16 v[30:33], v[42:45], v[176:179], 0
	v_mfma_f32_16x16x32_bf16 v[26:29], v[58:61], v[176:179], 0
	v_mfma_f32_16x16x32_bf16 v[14:17], v[42:45], v[184:187], 0
	v_mfma_f32_16x16x32_bf16 v[10:13], v[58:61], v[184:187], 0
	v_mfma_f32_16x16x32_bf16 v[78:81], v[46:49], v[160:163], v[78:81]
	v_mfma_f32_16x16x32_bf16 v[74:77], v[62:65], v[160:163], v[74:77]
	v_mfma_f32_16x16x32_bf16 v[54:57], v[46:49], v[172:175], v[54:57]
	v_mfma_f32_16x16x32_bf16 v[50:53], v[62:65], v[172:175], v[50:53]
	v_mfma_f32_16x16x32_bf16 v[30:33], v[46:49], v[180:183], v[30:33]
	v_mfma_f32_16x16x32_bf16 v[26:29], v[62:65], v[180:183], v[26:29]
	v_mfma_f32_16x16x32_bf16 v[14:17], v[46:49], v[188:191], v[14:17]
	v_mfma_f32_16x16x32_bf16 v[10:13], v[62:65], v[188:191], v[10:13]
	s_setprio 0
	s_barrier
; #define PG8_STAGE(bufoff, gbase, voff) do { _Pragma("unroll") for (int _i = 0; _i < 2; ++_i) \
;         __builtin_amdgcn_global_load_lds((const unsigned*)((const char*)(gbase) + (voff)[_i]), (LAS unsigned*)(lds + (bufoff) + ldsw + _i * 8192), 16, 0, 0); } while (0)
; #define PG8_LDA(dst, b, h) do { _Pragma("unroll") for (int m = 0; m < 4; ++m) _Pragma("unroll") for (int k = 0; k < 2; ++k) dst[m][k] = *(const LAS bf16x8*)(lds + PG8_SA(b, h) + aoff + m * 2048 + k * 1024); } while (0)
; #define PG8_LDB(dst, b, h) do { _Pragma("unroll") for (int n = 0; n < 2; ++n) _Pragma("unroll") for (int k = 0; k < 2; ++k) dst[n][k] = *(const LAS bf16x8*)(lds + PG8_SB(b, h) + boff + n * 2048 + k * 1024); } while (0)
; #define PG8_MMA(ai, bj, At, Bt) do { __builtin_amdgcn_s_setprio(1); _Pragma("unroll") for (int m = 0; m < 4; ++m) _Pragma("unroll") for (int n = 0; n < 2; ++n) _Pragma("unroll") for (int k = 0; k < 2; ++k) \
;         acc[ai][bj][m][n] = __builtin_amdgcn_mfma_f32_16x16x32_bf16(Bt[n][k], At[m][k], acc[ai][bj][m][n], 0, 0, 0); __builtin_amdgcn_s_setprio(0); } while (0)
; #define PG8_WAIT_V(n) asm volatile("s_waitcnt vmcnt(" #n ")" ::: "memory")
; #define PG8_WAIT_L(n) asm volatile("s_waitcnt lgkmcnt(" #n ")" ::: "memory")
; #define PG8_BAR __builtin_amdgcn_s_barrier()
; #define PG8_SCHED __builtin_amdgcn_sched_barrier(0)
; template <class Epi>
; DEVI void gemm_phase(const int wv, LAS unsigned char* lds, const Gemm g, const Order& S, const Epi& E) {
;     ...
;             PG8_STAGE(PG8_SB(0, 1), b2 + hstepB, voffB);
;             PG8_WAIT_V(6); PG8_BAR; PG8_MMA(1, 1, At, B1); PG8_BAR;
;             PG8_LDB(B0, 1, 0); PG8_SCHED; PG8_LDA(At, 1, 0); PG8_STAGE(PG8_SA(0, 1), a2 + hstepA, voffA);
;             PG8_WAIT_L(8); PG8_BAR; PG8_WAIT_L(0); PG8_MMA(0, 0, At, B0); PG8_BAR; PG8_SCHED;
;             PG8_LDB(B1, 1, 1); PG8_STAGE(PG8_SB(1, 0), b3, voffB);
;             PG8_BAR; PG8_WAIT_L(0); PG8_MMA(0, 1, At, B1); PG8_BAR;
;             PG8_LDA(At, 1, 1); PG8_STAGE(PG8_SA(1, 0), a3, voffA);
;             PG8_BAR; PG8_WAIT_L(0); PG8_MMA(1, 0, At, B0); PG8_BAR; PG8_SCHED;
	s_add_u32 s60, s34, 0x40000
	s_addc_u32 s61, s35, 0
	s_add_i32 s62, s62, s95
	v_lshl_add_u64 v[42:43], s[60:61], 0, v[0:1]
	s_mov_b32 m0, s62
	s_nop 0
	global_load_lds_dwordx4 v[42:43], off
	v_lshl_add_u64 v[42:43], s[60:61], 0, v[146:147]
	s_add_i32 m0, s62, 0x2000
	s_nop 0
	global_load_lds_dwordx4 v[42:43], off
	s_waitcnt vmcnt(6)
	s_barrier
	s_setprio 1
	v_mfma_f32_16x16x32_bf16 v[38:41], v[192:195], v[168:171], 0
	v_mfma_f32_16x16x32_bf16 v[34:37], v[204:207], v[168:171], 0
	v_mfma_f32_16x16x32_bf16 v[22:25], v[192:195], v[176:179], 0
	v_mfma_f32_16x16x32_bf16 v[18:21], v[204:207], v[176:179], 0
	v_mfma_f32_16x16x32_bf16 v[6:9], v[192:195], v[184:187], 0
	v_mfma_f32_16x16x32_bf16 v[2:5], v[204:207], v[184:187], 0
	v_mfma_f32_16x16x32_bf16 v[42:45], v[192:195], v[156:159], 0
	v_mfma_f32_16x16x32_bf16 v[46:49], v[204:207], v[156:159], 0
	v_mfma_f32_16x16x32_bf16 v[38:41], v[200:203], v[172:175], v[38:41]
	v_mfma_f32_16x16x32_bf16 v[34:37], v[208:211], v[172:175], v[34:37]
	v_mfma_f32_16x16x32_bf16 v[22:25], v[200:203], v[180:183], v[22:25]
	v_mfma_f32_16x16x32_bf16 v[18:21], v[208:211], v[180:183], v[18:21]
	v_mfma_f32_16x16x32_bf16 v[6:9], v[200:203], v[188:191], v[6:9]
	v_mfma_f32_16x16x32_bf16 v[2:5], v[208:211], v[188:191], v[2:5]
	v_mfma_f32_16x16x32_bf16 v[42:45], v[200:203], v[160:163], v[42:45]
	v_mfma_f32_16x16x32_bf16 v[46:49], v[208:211], v[160:163], v[46:49]
	s_setprio 0
	s_add_i32 s60, 0, 0x18000
	v_add_u32_e32 v70, s60, v165
	s_barrier
	ds_read_b128 v[58:61], v70
	ds_read_b128 v[62:65], v70 offset:1024
	ds_read_b128 v[66:69], v70 offset:2048
	ds_read_b128 v[70:73], v70 offset:3072
	s_add_u32 s36, s36, 0x40000
	s_addc_u32 s37, s37, 0
	s_mov_b32 m0, s40
	v_lshl_add_u64 v[192:193], s[36:37], 0, v[150:151]
	ds_read_b128 v[156:159], v167 offset:32768
	ds_read_b128 v[160:163], v167 offset:33792
	ds_read_b128 v[168:171], v167 offset:34816
	ds_read_b128 v[172:175], v167 offset:35840
	ds_read_b128 v[176:179], v167 offset:36864
	ds_read_b128 v[180:183], v167 offset:37888
	ds_read_b128 v[184:187], v167 offset:38912
	ds_read_b128 v[188:191], v167 offset:39936
	global_load_lds_dwordx4 v[192:193], off
	v_lshl_add_u64 v[192:193], s[36:37], 0, v[148:149]
	s_mov_b32 m0, s41
	s_nop 0
	global_load_lds_dwordx4 v[192:193], off
	s_waitcnt lgkmcnt(8)
	s_barrier
	s_waitcnt lgkmcnt(0)
	s_setprio 1
	s_waitcnt lgkmcnt(0)
	v_mfma_f32_16x16x32_bf16 v[142:145], v[58:61], v[156:159], v[142:145]
	v_mfma_f32_16x16x32_bf16 v[138:141], v[66:69], v[156:159], v[138:141]
	v_mfma_f32_16x16x32_bf16 v[126:129], v[58:61], v[168:171], v[126:129]
	v_mfma_f32_16x16x32_bf16 v[122:125], v[66:69], v[168:171], v[122:125]
	v_mfma_f32_16x16x32_bf16 v[110:113], v[58:61], v[176:179], v[110:113]
	v_mfma_f32_16x16x32_bf16 v[106:109], v[66:69], v[176:179], v[106:109]
	v_mfma_f32_16x16x32_bf16 v[94:97], v[58:61], v[184:187], v[94:97]
	v_mfma_f32_16x16x32_bf16 v[90:93], v[66:69], v[184:187], v[90:93]
	v_mfma_f32_16x16x32_bf16 v[142:145], v[62:65], v[160:163], v[142:145]
	v_mfma_f32_16x16x32_bf16 v[138:141], v[70:73], v[160:163], v[138:141]
	v_mfma_f32_16x16x32_bf16 v[126:129], v[62:65], v[172:175], v[126:129]
	v_mfma_f32_16x16x32_bf16 v[122:125], v[70:73], v[172:175], v[122:125]
	v_mfma_f32_16x16x32_bf16 v[110:113], v[62:65], v[180:183], v[110:113]
	v_mfma_f32_16x16x32_bf16 v[106:109], v[70:73], v[180:183], v[106:109]
	v_mfma_f32_16x16x32_bf16 v[94:97], v[62:65], v[188:191], v[94:97]
	v_mfma_f32_16x16x32_bf16 v[90:93], v[70:73], v[188:191], v[90:93]
	s_setprio 0
	s_barrier
	s_add_i32 s36, 0, 0x1c000
	s_add_i32 s37, s60, s95
	v_add_u32_e32 v199, s36, v165
	v_lshl_add_u64 v[212:213], v[212:213], 0, s[92:93]
	s_mov_b32 m0, s37
	ds_read_b128 v[192:195], v199
	ds_read_b128 v[200:203], v199 offset:1024
	ds_read_b128 v[204:207], v199 offset:2048
	ds_read_b128 v[208:211], v199 offset:3072
	global_load_lds_dwordx4 v[212:213], off
	v_lshl_add_u64 v[212:213], v[214:215], 0, s[92:93]
	s_add_i32 m0, s37, 0x2000
	s_nop 0
	global_load_lds_dwordx4 v[212:213], off
	s_barrier
; #define PG8_STAGE(bufoff, gbase, voff) do { _Pragma("unroll") for (int _i = 0; _i < 2; ++_i) \
;         __builtin_amdgcn_global_load_lds((const unsigned*)((const char*)(gbase) + (voff)[_i]), (LAS unsigned*)(lds + (bufoff) + ldsw + _i * 8192), 16, 0, 0); } while (0)
; #define PG8_MMA(ai, bj, At, Bt) do { __builtin_amdgcn_s_setprio(1); _Pragma("unroll") for (int m = 0; m < 4; ++m) _Pragma("unroll") for (int n = 0; n < 2; ++n) _Pragma("unroll") for (int k = 0; k < 2; ++k) \
;         acc[ai][bj][m][n] = __builtin_amdgcn_mfma_f32_16x16x32_bf16(Bt[n][k], At[m][k], acc[ai][bj][m][n], 0, 0, 0); __builtin_amdgcn_s_setprio(0); } while (0)
; #define PG8_WAIT_V(n) asm volatile("s_waitcnt vmcnt(" #n ")" ::: "memory")
; #define PG8_WAIT_L(n) asm volatile("s_waitcnt lgkmcnt(" #n ")" ::: "memory")
; #define PG8_BAR __builtin_amdgcn_s_barrier()
; #define PG8_SCHED __builtin_amdgcn_sched_barrier(0)
; template <class Epi>
; DEVI void gemm_phase(const int wv, LAS unsigned char* lds, const Gemm g, const Order& S, const Epi& E) {
;     ...
;             PG8_BAR; PG8_WAIT_L(0); PG8_MMA(1, 0, At, B0); PG8_BAR; PG8_SCHED;
;             PG8_STAGE(PG8_SB(1, 1), b3 + hstepB, voffB);
;             PG8_WAIT_V(6); PG8_BAR; PG8_MMA(1, 1, At, B1); PG8_BAR;
;         }
	s_waitcnt lgkmcnt(0)
	s_setprio 1
	s_waitcnt lgkmcnt(0)
	v_mfma_f32_16x16x32_bf16 v[134:137], v[192:195], v[156:159], v[134:137]
	v_mfma_f32_16x16x32_bf16 v[130:133], v[204:207], v[156:159], v[130:133]
	v_mfma_f32_16x16x32_bf16 v[118:121], v[192:195], v[168:171], v[118:121]
	v_mfma_f32_16x16x32_bf16 v[114:117], v[204:207], v[168:171], v[114:117]
	v_mfma_f32_16x16x32_bf16 v[102:105], v[192:195], v[176:179], v[102:105]
	v_mfma_f32_16x16x32_bf16 v[98:101], v[204:207], v[176:179], v[98:101]
	v_mfma_f32_16x16x32_bf16 v[86:89], v[192:195], v[184:187], v[86:89]
	v_mfma_f32_16x16x32_bf16 v[82:85], v[204:207], v[184:187], v[82:85]
	v_mfma_f32_16x16x32_bf16 v[134:137], v[200:203], v[160:163], v[134:137]
	v_mfma_f32_16x16x32_bf16 v[130:133], v[208:211], v[160:163], v[130:133]
	v_mfma_f32_16x16x32_bf16 v[118:121], v[200:203], v[172:175], v[118:121]
	v_mfma_f32_16x16x32_bf16 v[114:117], v[208:211], v[172:175], v[114:117]
	v_mfma_f32_16x16x32_bf16 v[102:105], v[200:203], v[180:183], v[102:105]
	v_mfma_f32_16x16x32_bf16 v[98:101], v[208:211], v[180:183], v[98:101]
	v_mfma_f32_16x16x32_bf16 v[86:89], v[200:203], v[188:191], v[86:89]
	v_mfma_f32_16x16x32_bf16 v[82:85], v[208:211], v[188:191], v[82:85]
	s_setprio 0
	s_mov_b32 m0, s52
	v_lshl_add_u64 v[212:213], v[216:217], 0, s[92:93]
	s_barrier
	ds_read_b128 v[156:159], v167 offset:49152
	ds_read_b128 v[160:163], v167 offset:50176
	ds_read_b128 v[168:171], v167 offset:51200
	ds_read_b128 v[172:175], v167 offset:52224
	ds_read_b128 v[176:179], v167 offset:53248
	ds_read_b128 v[180:183], v167 offset:54272
	ds_read_b128 v[184:187], v167 offset:55296
	ds_read_b128 v[188:191], v167 offset:56320
	global_load_lds_dwordx4 v[212:213], off
	v_lshl_add_u64 v[212:213], v[218:219], 0, s[92:93]
	s_mov_b32 m0, s53
	s_nop 0
	global_load_lds_dwordx4 v[212:213], off
	s_barrier
	s_waitcnt lgkmcnt(0)
	s_setprio 1
	s_waitcnt lgkmcnt(0)
	v_mfma_f32_16x16x32_bf16 v[78:81], v[58:61], v[156:159], v[78:81]
	v_mfma_f32_16x16x32_bf16 v[74:77], v[66:69], v[156:159], v[74:77]
	v_mfma_f32_16x16x32_bf16 v[54:57], v[58:61], v[168:171], v[54:57]
	v_mfma_f32_16x16x32_bf16 v[50:53], v[66:69], v[168:171], v[50:53]
	v_mfma_f32_16x16x32_bf16 v[30:33], v[58:61], v[176:179], v[30:33]
	v_mfma_f32_16x16x32_bf16 v[26:29], v[66:69], v[176:179], v[26:29]
	v_mfma_f32_16x16x32_bf16 v[14:17], v[58:61], v[184:187], v[14:17]
	v_mfma_f32_16x16x32_bf16 v[10:13], v[66:69], v[184:187], v[10:13]
	v_mfma_f32_16x16x32_bf16 v[78:81], v[62:65], v[160:163], v[78:81]
	v_mfma_f32_16x16x32_bf16 v[74:77], v[70:73], v[160:163], v[74:77]
	v_mfma_f32_16x16x32_bf16 v[54:57], v[62:65], v[172:175], v[54:57]
	v_mfma_f32_16x16x32_bf16 v[50:53], v[70:73], v[172:175], v[50:53]
	v_mfma_f32_16x16x32_bf16 v[30:33], v[62:65], v[180:183], v[30:33]
	v_mfma_f32_16x16x32_bf16 v[26:29], v[70:73], v[180:183], v[26:29]
	v_mfma_f32_16x16x32_bf16 v[14:17], v[62:65], v[188:191], v[14:17]
	v_mfma_f32_16x16x32_bf16 v[10:13], v[70:73], v[188:191], v[10:13]
	s_setprio 0
	s_barrier
	s_add_u32 s34, s34, 0x40080
	s_addc_u32 s35, s35, 0
	s_add_i32 s36, s36, s95
	v_lshl_add_u64 v[58:59], s[34:35], 0, v[0:1]
	s_mov_b32 m0, s36
	s_nop 0
	global_load_lds_dwordx4 v[58:59], off
	v_lshl_add_u64 v[58:59], s[34:35], 0, v[146:147]
	s_add_i32 m0, s36, 0x2000
	s_nop 0
	global_load_lds_dwordx4 v[58:59], off
	s_waitcnt vmcnt(6)
	s_barrier
	s_setprio 1
	v_mfma_f32_16x16x32_bf16 v[42:45], v[192:195], v[156:159], v[42:45]
	v_mfma_f32_16x16x32_bf16 v[70:73], v[200:203], v[160:163], v[42:45]
	v_mfma_f32_16x16x32_bf16 v[42:45], v[204:207], v[156:159], v[46:49]
	v_mfma_f32_16x16x32_bf16 v[38:41], v[192:195], v[168:171], v[38:41]
	v_mfma_f32_16x16x32_bf16 v[34:37], v[204:207], v[168:171], v[34:37]
	v_mfma_f32_16x16x32_bf16 v[22:25], v[192:195], v[176:179], v[22:25]
	v_mfma_f32_16x16x32_bf16 v[18:21], v[204:207], v[176:179], v[18:21]
	v_mfma_f32_16x16x32_bf16 v[6:9], v[192:195], v[184:187], v[6:9]
	v_mfma_f32_16x16x32_bf16 v[2:5], v[204:207], v[184:187], v[2:5]
	v_mfma_f32_16x16x32_bf16 v[66:69], v[208:211], v[160:163], v[42:45]
	v_mfma_f32_16x16x32_bf16 v[38:41], v[200:203], v[172:175], v[38:41]
	v_mfma_f32_16x16x32_bf16 v[34:37], v[208:211], v[172:175], v[34:37]
	v_mfma_f32_16x16x32_bf16 v[22:25], v[200:203], v[180:183], v[22:25]
	v_mfma_f32_16x16x32_bf16 v[18:21], v[208:211], v[180:183], v[18:21]
	v_mfma_f32_16x16x32_bf16 v[6:9], v[200:203], v[188:191], v[6:9]
	v_mfma_f32_16x16x32_bf16 v[2:5], v[208:211], v[188:191], v[2:5]
	s_setprio 0
	s_add_i32 s59, s59, 2
	s_add_u32 s30, s30, 0x100
	s_addc_u32 s31, s31, 0
	s_add_u32 s57, s57, 0x100
	s_addc_u32 s58, s58, 0
	s_cmp_gt_u32 s59, 13
	s_barrier
	s_cbranch_scc0 .LBB0_1283
	s_branch .Lzp_epi_3

; DEVI unsigned cvt_pk_bf16(float lo, float hi) { unsigned r; asm volatile("v_cvt_pk_bf16_f32 %0, %1, %2" : "=v"(r) : "v"(lo), "v"(hi)); return r; }
;     DEVI void operator()(f32x4 (&acc)[2][2][4][2], const Unit& u, int wr, int wc, int fr, int fq) const {
;         const int row0 = u.pm * BM + wr * 64 + fr, col0 = u.pn * BM + wc * 32 + 8 * fq;
;         f32x4 sh[2][2];
;         if (RS) { const int bi = u.pm * BM < NLAT ? (u.pm * BM) >> 11 : 16;
; #pragma unroll
;             for (int bj = 0; bj < 2; ++bj) { sh[bj][0] = *(const f32x4*)(shw + (size_t)bi * ldshw + col0 + bj * HALF); sh[bj][1] = *(const f32x4*)(shw + (size_t)bi * ldshw + col0 + bj * HALF + 4); } }
; #pragma unroll
;         for (int ai = 0; ai < 2; ++ai)
; #pragma unroll
;             for (int m = 0; m < 4; ++m) { bf16_t* rowp = O + (size_t)(row0 + ai * HALF + m * 16) * ldc + col0;
;                 float rstd = 1.0f; if (RS) rstd = rsqrtf(ssq[row0 + ai * HALF + m * 16] * (1.0f / 1024.0f) + EPS);
; #pragma unroll
;                 for (int bj = 0; bj < 2; ++bj) { f32x4 v0 = acc[ai][bj][m][0], v1 = acc[ai][bj][m][1];
;                     if (RS) { v0 = v0 * rstd + sh[bj][0]; v1 = v1 * rstd + sh[bj][1]; }
;                     if (ACT == 1) {
; #pragma unroll
;                         for (int j = 0; j < 4; ++j) { const float a = fmaxf(v0[j], 0.f), b = fmaxf(v1[j], 0.f); v0[j] = a * a; v1[j] = b * b; } }
;                     if (ACT == 2) {
; #pragma unroll
;                         for (int j = 0; j < 4; ++j) { v0[j] = 1.0f + __expf(-fminf(fmaxf(v0[j], -30.f), 30.f)); v1[j] = 1.0f + __expf(-fminf(fmaxf(v1[j], -30.f), 30.f)); } }
;                     u32x4 w; w.x = cvt_pk_bf16(v0[0], v0[1]); w.y = cvt_pk_bf16(v0[2], v0[3]); w.z = cvt_pk_bf16(v1[0], v1[1]); w.w = cvt_pk_bf16(v1[2], v1[3]);
;                     *(u32x4*)(rowp + bj * HALF) = w; } }
.Lzp_epi_3:
	s_min_i32 s3, s12, 0x80
	s_ashr_i32 s30, s3, 3
	s_ashr_i32 s31, s30, 31
	s_lshl_b64 s[30:31], s[30:31], 14
	v_lshl_or_b32 v156, s28, 8, v166
	s_add_u32 s30, s50, s30
	s_addc_u32 s31, s51, s31
	v_ashrrev_i32_e32 v157, 31, v156
	v_lshl_add_u32 v160, s12, 8, v164
	v_lshl_add_u64 v[46:47], v[156:157], 2, s[30:31]
	v_ashrrev_i32_e32 v161, 31, v160
	v_readlane_b32 s30, v252, 51
	v_lshlrev_b64 v[158:159], 13, v[160:161]
	v_readlane_b32 s31, v252, 52
	v_lshlrev_b64 v[162:163], 1, v[156:157]
	global_load_dwordx4 v[58:61], v[46:47], off offset:16
	global_load_dwordx4 v[62:65], v[46:47], off
	global_load_dwordx4 v[42:45], v[46:47], off offset:528
	s_nop 0
	global_load_dwordx4 v[46:49], v[46:47], off offset:512
	v_lshl_add_u64 v[158:159], s[30:31], 0, v[158:159]
	v_lshl_add_u64 v[156:157], v[158:159], 0, v[162:163]
	v_lshl_add_u64 v[158:159], v[160:161], 2, s[0:1]
	global_load_dword v161, v[158:159], off
	s_mov_b32 s5, 0x800000
	s_mov_b32 s3, 0x100000
	s_mov_b32 s28, s2
	s_mov_b32 s12, s4
	s_mov_b64 s[34:35], s[8:9]
	s_movk_i32 s55, 0xc00
	s_waitcnt vmcnt(0)
	v_fmamk_f32 v161, v161, 0x3a800000, v196
	v_cmp_gt_f32_e32 vcc, s5, v161
	v_mul_f32_e32 v168, 0x4b800000, v161
	s_nop 0
	v_cndmask_b32_e32 v161, v161, v168, vcc
	v_rsq_f32_e32 v161, v161
	s_nop 0
	v_mul_f32_e32 v168, 0x45800000, v161
	v_cndmask_b32_e32 v168, v161, v168, vcc
	v_pk_fma_f32 v[138:139], v[138:139], v[168:169], v[58:59] op_sel_hi:[1,0,1]
	v_pk_fma_f32 v[142:143], v[142:143], v[168:169], v[62:63] op_sel_hi:[1,0,1]
	v_pk_fma_f32 v[140:141], v[140:141], v[168:169], v[60:61] op_sel_hi:[1,0,1]
	v_max_f32_e32 v138, 0, v138
	v_pk_fma_f32 v[144:145], v[144:145], v[168:169], v[64:65] op_sel_hi:[1,0,1]
	v_mul_f32_e32 v161, v138, v138
	v_max_f32_e32 v138, 0, v143
	v_max_f32_e32 v139, 0, v139
	v_max_f32_e32 v140, 0, v140
	v_max_f32_e32 v142, 0, v142
	v_mul_f32_e32 v138, v138, v138
	v_mul_f32_e32 v143, v139, v139
	v_max_f32_e32 v139, 0, v144
	v_mul_f32_e32 v144, v140, v140
	v_max_f32_e32 v140, 0, v145
	v_max_f32_e32 v141, 0, v141
	v_pk_fma_f32 v[132:133], v[132:133], v[168:169], v[44:45] op_sel_hi:[1,0,1]
	v_pk_fma_f32 v[130:131], v[130:131], v[168:169], v[42:43] op_sel_hi:[1,0,1]
	v_mul_f32_e32 v142, v142, v142
	v_mul_f32_e32 v139, v139, v139
	v_mul_f32_e32 v140, v140, v140
	v_mul_f32_e32 v141, v141, v141
	v_cvt_pk_bf16_f32 v138, v142, v138
	v_pk_fma_f32 v[136:137], v[136:137], v[168:169], v[48:49] op_sel_hi:[1,0,1]
	v_pk_fma_f32 v[134:135], v[134:135], v[168:169], v[46:47] op_sel_hi:[1,0,1]
	v_max_f32_e32 v130, 0, v130
	v_max_f32_e32 v131, 0, v131
	v_max_f32_e32 v132, 0, v132
	v_cvt_pk_bf16_f32 v139, v139, v140
	v_cvt_pk_bf16_f32 v140, v161, v143
	v_cvt_pk_bf16_f32 v141, v144, v141
	global_store_dwordx4 v[156:157], v[138:141], off
	v_max_f32_e32 v133, 0, v133
	v_max_f32_e32 v134, 0, v134
	v_mul_f32_e32 v138, v130, v130
	v_max_f32_e32 v130, 0, v135
	v_mul_f32_e32 v135, v131, v131
	v_max_f32_e32 v131, 0, v136
	v_mul_f32_e32 v136, v132, v132
	v_max_f32_e32 v132, 0, v137
	v_mul_f32_e32 v130, v130, v130
	v_mul_f32_e32 v131, v131, v131
	v_mul_f32_e32 v132, v132, v132
	v_mul_f32_e32 v133, v133, v133
	v_mul_f32_e32 v134, v134, v134
	v_cvt_pk_bf16_f32 v130, v134, v130
	v_cvt_pk_bf16_f32 v131, v131, v132
	v_cvt_pk_bf16_f32 v132, v138, v135
	v_cvt_pk_bf16_f32 v133, v136, v133
	global_store_dwordx4 v[156:157], v[130:133], off offset:256
	global_load_dword v132, v[158:159], off offset:64
	s_nop 0
	v_or_b32_e32 v130, 16, v160
	v_ashrrev_i32_e32 v131, 31, v130
	v_lshlrev_b64 v[130:131], 13, v[130:131]
	v_lshl_add_u64 v[130:131], s[30:31], 0, v[130:131]
	v_lshl_add_u64 v[130:131], v[130:131], 0, v[162:163]
	s_waitcnt vmcnt(0)
	v_fmamk_f32 v132, v132, 0x3a800000, v196
	v_cmp_gt_f32_e32 vcc, s5, v132
	v_mul_f32_e32 v133, 0x4b800000, v132
	s_nop 0
	v_cndmask_b32_e32 v132, v132, v133, vcc
	v_rsq_f32_e32 v132, v132
	s_nop 0
	v_mul_f32_e32 v133, 0x45800000, v132
	v_cndmask_b32_e32 v132, v132, v133, vcc
	v_pk_fma_f32 v[122:123], v[122:123], v[132:133], v[58:59] op_sel_hi:[1,0,1]
	v_pk_fma_f32 v[126:127], v[126:127], v[132:133], v[62:63] op_sel_hi:[1,0,1]
	v_pk_fma_f32 v[124:125], v[124:125], v[132:133], v[60:61] op_sel_hi:[1,0,1]
	v_max_f32_e32 v122, 0, v122
	v_pk_fma_f32 v[128:129], v[128:129], v[132:133], v[64:65] op_sel_hi:[1,0,1]
	v_mul_f32_e32 v133, v122, v122
	v_max_f32_e32 v122, 0, v127
	v_max_f32_e32 v123, 0, v123
	v_max_f32_e32 v124, 0, v124
	v_max_f32_e32 v126, 0, v126
	v_mul_f32_e32 v122, v122, v122
	v_mul_f32_e32 v127, v123, v123
	v_max_f32_e32 v123, 0, v128
	v_mul_f32_e32 v128, v124, v124
	v_max_f32_e32 v124, 0, v129
	v_max_f32_e32 v125, 0, v125
	v_pk_fma_f32 v[116:117], v[116:117], v[132:133], v[44:45] op_sel_hi:[1,0,1]
	v_pk_fma_f32 v[114:115], v[114:115], v[132:133], v[42:43] op_sel_hi:[1,0,1]
	v_mul_f32_e32 v126, v126, v126
	v_mul_f32_e32 v123, v123, v123
	v_mul_f32_e32 v124, v124, v124
	v_mul_f32_e32 v125, v125, v125
	v_cvt_pk_bf16_f32 v122, v126, v122
	v_pk_fma_f32 v[120:121], v[120:121], v[132:133], v[48:49] op_sel_hi:[1,0,1]
	v_pk_fma_f32 v[118:119], v[118:119], v[132:133], v[46:47] op_sel_hi:[1,0,1]
	v_max_f32_e32 v114, 0, v114
	v_max_f32_e32 v115, 0, v115
	v_max_f32_e32 v116, 0, v116
	v_cvt_pk_bf16_f32 v123, v123, v124
	v_cvt_pk_bf16_f32 v124, v133, v127
	v_cvt_pk_bf16_f32 v125, v128, v125
	global_store_dwordx4 v[130:131], v[122:125], off
	v_max_f32_e32 v117, 0, v117
	v_max_f32_e32 v118, 0, v118
	v_mul_f32_e32 v122, v114, v114
	v_max_f32_e32 v114, 0, v119
	v_mul_f32_e32 v119, v115, v115
	v_max_f32_e32 v115, 0, v120
	v_mul_f32_e32 v120, v116, v116
	v_max_f32_e32 v116, 0, v121
	v_mul_f32_e32 v114, v114, v114
	v_mul_f32_e32 v115, v115, v115
	v_mul_f32_e32 v116, v116, v116
	v_mul_f32_e32 v117, v117, v117
	v_mul_f32_e32 v118, v118, v118
	v_cvt_pk_bf16_f32 v114, v118, v114
	v_cvt_pk_bf16_f32 v115, v115, v116
	v_cvt_pk_bf16_f32 v116, v122, v119
	v_cvt_pk_bf16_f32 v117, v120, v117
	global_store_dwordx4 v[130:131], v[114:117], off offset:256
	global_load_dword v116, v[158:159], off offset:128
	s_nop 0
	v_or_b32_e32 v114, 32, v160
	v_ashrrev_i32_e32 v115, 31, v114
	v_lshlrev_b64 v[114:115], 13, v[114:115]
	v_lshl_add_u64 v[114:115], s[30:31], 0, v[114:115]
	v_lshl_add_u64 v[114:115], v[114:115], 0, v[162:163]
	s_waitcnt vmcnt(0)
; DEVI unsigned cvt_pk_bf16(float lo, float hi) { unsigned r; asm volatile("v_cvt_pk_bf16_f32 %0, %1, %2" : "=v"(r) : "v"(lo), "v"(hi)); return r; }
;     DEVI void operator()(f32x4 (&acc)[2][2][4][2], const Unit& u, int wr, int wc, int fr, int fq) const {
;     ...
;             for (int m = 0; m < 4; ++m) { bf16_t* rowp = O + (size_t)(row0 + ai * HALF + m * 16) * ldc + col0;
;                 float rstd = 1.0f; if (RS) rstd = rsqrtf(ssq[row0 + ai * HALF + m * 16] * (1.0f / 1024.0f) + EPS);
; #pragma unroll
;                 for (int bj = 0; bj < 2; ++bj) { f32x4 v0 = acc[ai][bj][m][0], v1 = acc[ai][bj][m][1];
;                     if (RS) { v0 = v0 * rstd + sh[bj][0]; v1 = v1 * rstd + sh[bj][1]; }
;                     if (ACT == 1) {
; #pragma unroll
;                         for (int j = 0; j < 4; ++j) { const float a = fmaxf(v0[j], 0.f), b = fmaxf(v1[j], 0.f); v0[j] = a * a; v1[j] = b * b; } }
;                     if (ACT == 2) {
; #pragma unroll
;                         for (int j = 0; j < 4; ++j) { v0[j] = 1.0f + __expf(-fminf(fmaxf(v0[j], -30.f), 30.f)); v1[j] = 1.0f + __expf(-fminf(fmaxf(v1[j], -30.f), 30.f)); } }
;                     u32x4 w; w.x = cvt_pk_bf16(v0[0], v0[1]); w.y = cvt_pk_bf16(v0[2], v0[3]); w.z = cvt_pk_bf16(v1[0], v1[1]); w.w = cvt_pk_bf16(v1[2], v1[3]);
;                     *(u32x4*)(rowp + bj * HALF) = w; } }
	v_fmamk_f32 v116, v116, 0x3a800000, v196
	v_cmp_gt_f32_e32 vcc, s5, v116
	v_mul_f32_e32 v117, 0x4b800000, v116
	s_nop 0
	v_cndmask_b32_e32 v116, v116, v117, vcc
	v_rsq_f32_e32 v116, v116
	s_nop 0
	v_mul_f32_e32 v117, 0x45800000, v116
	v_cndmask_b32_e32 v116, v116, v117, vcc
	v_pk_fma_f32 v[106:107], v[106:107], v[116:117], v[58:59] op_sel_hi:[1,0,1]
	v_pk_fma_f32 v[110:111], v[110:111], v[116:117], v[62:63] op_sel_hi:[1,0,1]
	v_pk_fma_f32 v[108:109], v[108:109], v[116:117], v[60:61] op_sel_hi:[1,0,1]
	v_max_f32_e32 v106, 0, v106
	v_pk_fma_f32 v[112:113], v[112:113], v[116:117], v[64:65] op_sel_hi:[1,0,1]
	v_mul_f32_e32 v117, v106, v106
	v_max_f32_e32 v106, 0, v111
	v_max_f32_e32 v107, 0, v107
	v_max_f32_e32 v108, 0, v108
	v_max_f32_e32 v110, 0, v110
	v_mul_f32_e32 v106, v106, v106
	v_mul_f32_e32 v111, v107, v107
	v_max_f32_e32 v107, 0, v112
	v_mul_f32_e32 v112, v108, v108
	v_max_f32_e32 v108, 0, v113
	v_max_f32_e32 v109, 0, v109
	v_pk_fma_f32 v[100:101], v[100:101], v[116:117], v[44:45] op_sel_hi:[1,0,1]
	v_pk_fma_f32 v[98:99], v[98:99], v[116:117], v[42:43] op_sel_hi:[1,0,1]
	v_mul_f32_e32 v110, v110, v110
	v_mul_f32_e32 v107, v107, v107
	v_mul_f32_e32 v108, v108, v108
	v_mul_f32_e32 v109, v109, v109
	v_cvt_pk_bf16_f32 v106, v110, v106
	v_pk_fma_f32 v[104:105], v[104:105], v[116:117], v[48:49] op_sel_hi:[1,0,1]
	v_pk_fma_f32 v[102:103], v[102:103], v[116:117], v[46:47] op_sel_hi:[1,0,1]
	v_max_f32_e32 v98, 0, v98
	v_max_f32_e32 v99, 0, v99
	v_max_f32_e32 v100, 0, v100
	v_cvt_pk_bf16_f32 v107, v107, v108
	v_cvt_pk_bf16_f32 v108, v117, v111
	v_cvt_pk_bf16_f32 v109, v112, v109
	global_store_dwordx4 v[114:115], v[106:109], off
	v_max_f32_e32 v101, 0, v101
	v_max_f32_e32 v102, 0, v102
	v_mul_f32_e32 v106, v98, v98
	v_max_f32_e32 v98, 0, v103
	v_mul_f32_e32 v103, v99, v99
	v_max_f32_e32 v99, 0, v104
	v_mul_f32_e32 v104, v100, v100
	v_max_f32_e32 v100, 0, v105
	v_mul_f32_e32 v98, v98, v98
	v_mul_f32_e32 v99, v99, v99
	v_mul_f32_e32 v100, v100, v100
	v_mul_f32_e32 v101, v101, v101
	v_mul_f32_e32 v102, v102, v102
	v_cvt_pk_bf16_f32 v98, v102, v98
	v_cvt_pk_bf16_f32 v99, v99, v100
	v_cvt_pk_bf16_f32 v100, v106, v103
	v_cvt_pk_bf16_f32 v101, v104, v101
	global_store_dwordx4 v[114:115], v[98:101], off offset:256
	global_load_dword v100, v[158:159], off offset:192
	s_nop 0
	v_or_b32_e32 v98, 48, v160
	v_ashrrev_i32_e32 v99, 31, v98
	v_lshlrev_b64 v[98:99], 13, v[98:99]
	v_lshl_add_u64 v[98:99], s[30:31], 0, v[98:99]
	v_lshl_add_u64 v[98:99], v[98:99], 0, v[162:163]
	s_mov_b64 s[30:31], 0x100000
	s_waitcnt vmcnt(0)
	v_fmamk_f32 v100, v100, 0x3a800000, v196
	v_cmp_gt_f32_e32 vcc, s5, v100
	v_mul_f32_e32 v101, 0x4b800000, v100
	s_nop 0
	v_cndmask_b32_e32 v100, v100, v101, vcc
	v_rsq_f32_e32 v100, v100
	s_nop 0
	v_mul_f32_e32 v101, 0x45800000, v100
	v_cndmask_b32_e32 v100, v100, v101, vcc
	v_pk_fma_f32 v[90:91], v[90:91], v[100:101], v[58:59] op_sel_hi:[1,0,1]
	v_pk_fma_f32 v[94:95], v[94:95], v[100:101], v[62:63] op_sel_hi:[1,0,1]
	v_pk_fma_f32 v[92:93], v[92:93], v[100:101], v[60:61] op_sel_hi:[1,0,1]
	v_max_f32_e32 v90, 0, v90
	v_pk_fma_f32 v[96:97], v[96:97], v[100:101], v[64:65] op_sel_hi:[1,0,1]
	v_mul_f32_e32 v101, v90, v90
	v_max_f32_e32 v90, 0, v95
	v_max_f32_e32 v91, 0, v91
	v_max_f32_e32 v92, 0, v92
	v_max_f32_e32 v94, 0, v94
	v_mul_f32_e32 v90, v90, v90
	v_mul_f32_e32 v95, v91, v91
	v_max_f32_e32 v91, 0, v96
	v_mul_f32_e32 v96, v92, v92
	v_max_f32_e32 v92, 0, v97
	v_max_f32_e32 v93, 0, v93
	v_pk_fma_f32 v[84:85], v[84:85], v[100:101], v[44:45] op_sel_hi:[1,0,1]
	v_pk_fma_f32 v[82:83], v[82:83], v[100:101], v[42:43] op_sel_hi:[1,0,1]
	v_mul_f32_e32 v94, v94, v94
	v_mul_f32_e32 v91, v91, v91
	v_mul_f32_e32 v92, v92, v92
	v_mul_f32_e32 v93, v93, v93
	v_cvt_pk_bf16_f32 v90, v94, v90
	v_pk_fma_f32 v[88:89], v[88:89], v[100:101], v[48:49] op_sel_hi:[1,0,1]
	v_pk_fma_f32 v[86:87], v[86:87], v[100:101], v[46:47] op_sel_hi:[1,0,1]
	v_max_f32_e32 v82, 0, v82
	v_max_f32_e32 v83, 0, v83
	v_max_f32_e32 v84, 0, v84
	v_cvt_pk_bf16_f32 v91, v91, v92
	v_cvt_pk_bf16_f32 v92, v101, v95
	v_cvt_pk_bf16_f32 v93, v96, v93
	global_store_dwordx4 v[98:99], v[90:93], off
	v_max_f32_e32 v85, 0, v85
	v_max_f32_e32 v86, 0, v86
	v_mul_f32_e32 v90, v82, v82
	v_max_f32_e32 v82, 0, v87
	v_mul_f32_e32 v87, v83, v83
	v_max_f32_e32 v83, 0, v88
	v_mul_f32_e32 v88, v84, v84
	v_max_f32_e32 v84, 0, v89
	v_mul_f32_e32 v82, v82, v82
	v_mul_f32_e32 v83, v83, v83
	v_mul_f32_e32 v84, v84, v84
	v_mul_f32_e32 v85, v85, v85
	v_mul_f32_e32 v86, v86, v86
	v_cvt_pk_bf16_f32 v82, v86, v82
	v_cvt_pk_bf16_f32 v83, v83, v84
	v_cvt_pk_bf16_f32 v84, v90, v87
	v_cvt_pk_bf16_f32 v85, v88, v85
	global_store_dwordx4 v[98:99], v[82:85], off offset:256
	global_load_dword v84, v[158:159], off offset:512
	s_nop 0
	v_lshl_add_u64 v[82:83], v[156:157], 0, s[30:31]
	s_mov_b64 s[30:31], 0x120000
	s_waitcnt vmcnt(0)
; DEVI unsigned cvt_pk_bf16(float lo, float hi) { unsigned r; asm volatile("v_cvt_pk_bf16_f32 %0, %1, %2" : "=v"(r) : "v"(lo), "v"(hi)); return r; }
;     DEVI void operator()(f32x4 (&acc)[2][2][4][2], const Unit& u, int wr, int wc, int fr, int fq) const {
;     ...
;             for (int m = 0; m < 4; ++m) { bf16_t* rowp = O + (size_t)(row0 + ai * HALF + m * 16) * ldc + col0;
;                 float rstd = 1.0f; if (RS) rstd = rsqrtf(ssq[row0 + ai * HALF + m * 16] * (1.0f / 1024.0f) + EPS);
; #pragma unroll
;                 for (int bj = 0; bj < 2; ++bj) { f32x4 v0 = acc[ai][bj][m][0], v1 = acc[ai][bj][m][1];
;                     if (RS) { v0 = v0 * rstd + sh[bj][0]; v1 = v1 * rstd + sh[bj][1]; }
;                     if (ACT == 1) {
; #pragma unroll
;                         for (int j = 0; j < 4; ++j) { const float a = fmaxf(v0[j], 0.f), b = fmaxf(v1[j], 0.f); v0[j] = a * a; v1[j] = b * b; } }
;                     if (ACT == 2) {
; #pragma unroll
;                         for (int j = 0; j < 4; ++j) { v0[j] = 1.0f + __expf(-fminf(fmaxf(v0[j], -30.f), 30.f)); v1[j] = 1.0f + __expf(-fminf(fmaxf(v1[j], -30.f), 30.f)); } }
;                     u32x4 w; w.x = cvt_pk_bf16(v0[0], v0[1]); w.y = cvt_pk_bf16(v0[2], v0[3]); w.z = cvt_pk_bf16(v1[0], v1[1]); w.w = cvt_pk_bf16(v1[2], v1[3]);
;                     *(u32x4*)(rowp + bj * HALF) = w; } }
	v_fmamk_f32 v84, v84, 0x3a800000, v196
	v_cmp_gt_f32_e32 vcc, s5, v84
	v_mul_f32_e32 v85, 0x4b800000, v84
	s_nop 0
	v_cndmask_b32_e32 v84, v84, v85, vcc
	v_rsq_f32_e32 v84, v84
	s_nop 0
	v_mul_f32_e32 v85, 0x45800000, v84
	v_cndmask_b32_e32 v84, v84, v85, vcc
	v_pk_fma_f32 v[74:75], v[74:75], v[84:85], v[58:59] op_sel_hi:[1,0,1]
	v_pk_fma_f32 v[78:79], v[78:79], v[84:85], v[62:63] op_sel_hi:[1,0,1]
	v_pk_fma_f32 v[76:77], v[76:77], v[84:85], v[60:61] op_sel_hi:[1,0,1]
	v_max_f32_e32 v74, 0, v74
	v_pk_fma_f32 v[80:81], v[80:81], v[84:85], v[64:65] op_sel_hi:[1,0,1]
	v_max_f32_e32 v78, 0, v78
	v_mul_f32_e32 v85, v74, v74
	v_max_f32_e32 v74, 0, v79
	v_max_f32_e32 v75, 0, v75
	v_max_f32_e32 v76, 0, v76
	v_mul_f32_e32 v78, v78, v78
	v_mul_f32_e32 v74, v74, v74
	v_mul_f32_e32 v79, v75, v75
	v_max_f32_e32 v75, 0, v80
	v_mul_f32_e32 v80, v76, v76
	v_max_f32_e32 v76, 0, v81
	v_mul_f32_e32 v75, v75, v75
	v_max_f32_e32 v77, 0, v77
	v_mul_f32_e32 v76, v76, v76
	v_cvt_pk_bf16_f32 v74, v78, v74
	v_add_co_u32_e32 v78, vcc, s3, v156
	v_pk_fma_f32 v[68:69], v[68:69], v[84:85], v[44:45] op_sel_hi:[1,0,1]
	v_pk_fma_f32 v[66:67], v[66:67], v[84:85], v[42:43] op_sel_hi:[1,0,1]
	v_mul_f32_e32 v77, v77, v77
	v_cvt_pk_bf16_f32 v75, v75, v76
	v_cvt_pk_bf16_f32 v76, v85, v79
	v_addc_co_u32_e32 v79, vcc, 0, v157, vcc
	v_pk_fma_f32 v[72:73], v[72:73], v[84:85], v[48:49] op_sel_hi:[1,0,1]
	v_pk_fma_f32 v[70:71], v[70:71], v[84:85], v[46:47] op_sel_hi:[1,0,1]
	v_max_f32_e32 v66, 0, v66
	v_max_f32_e32 v67, 0, v67
	v_max_f32_e32 v68, 0, v68
	v_cvt_pk_bf16_f32 v77, v80, v77
	global_store_dwordx4 v[78:79], v[74:77], off
	v_max_f32_e32 v69, 0, v69
	v_max_f32_e32 v70, 0, v70
	v_mul_f32_e32 v74, v66, v66
	v_max_f32_e32 v66, 0, v71
	v_mul_f32_e32 v71, v67, v67
	v_max_f32_e32 v67, 0, v72
	v_mul_f32_e32 v72, v68, v68
	v_max_f32_e32 v68, 0, v73
	v_mul_f32_e32 v66, v66, v66
	v_mul_f32_e32 v67, v67, v67
	v_mul_f32_e32 v68, v68, v68
	v_mul_f32_e32 v69, v69, v69
	v_mul_f32_e32 v70, v70, v70
	v_cvt_pk_bf16_f32 v66, v70, v66
	v_cvt_pk_bf16_f32 v67, v67, v68
	v_cvt_pk_bf16_f32 v68, v74, v71
	v_cvt_pk_bf16_f32 v69, v72, v69
	global_store_dwordx4 v[82:83], v[66:69], off offset:256
	global_load_dword v68, v[158:159], off offset:576
	s_mov_b32 s3, 0x120000
	v_lshl_add_u64 v[66:67], v[156:157], 0, s[30:31]
	s_mov_b64 s[30:31], 0x140000
	s_waitcnt vmcnt(0)
	v_fmamk_f32 v68, v68, 0x3a800000, v196
	v_cmp_gt_f32_e32 vcc, s5, v68
	v_mul_f32_e32 v69, 0x4b800000, v68
	s_nop 0
	v_cndmask_b32_e32 v68, v68, v69, vcc
	v_rsq_f32_e32 v68, v68
	s_nop 0
	v_mul_f32_e32 v69, 0x45800000, v68
	v_cndmask_b32_e32 v68, v68, v69, vcc
	v_pk_fma_f32 v[50:51], v[50:51], v[68:69], v[58:59] op_sel_hi:[1,0,1]
	v_pk_fma_f32 v[54:55], v[54:55], v[68:69], v[62:63] op_sel_hi:[1,0,1]
	v_pk_fma_f32 v[52:53], v[52:53], v[68:69], v[60:61] op_sel_hi:[1,0,1]
	v_max_f32_e32 v50, 0, v50
	v_pk_fma_f32 v[56:57], v[56:57], v[68:69], v[64:65] op_sel_hi:[1,0,1]
	v_max_f32_e32 v54, 0, v54
	v_mul_f32_e32 v69, v50, v50
	v_max_f32_e32 v50, 0, v55
	v_max_f32_e32 v51, 0, v51
	v_max_f32_e32 v52, 0, v52
	v_mul_f32_e32 v54, v54, v54
	v_mul_f32_e32 v50, v50, v50
	v_mul_f32_e32 v55, v51, v51
	v_max_f32_e32 v51, 0, v56
	v_mul_f32_e32 v56, v52, v52
	v_max_f32_e32 v52, 0, v57
	v_mul_f32_e32 v51, v51, v51
	v_max_f32_e32 v53, 0, v53
	v_mul_f32_e32 v52, v52, v52
	v_cvt_pk_bf16_f32 v50, v54, v50
	v_add_co_u32_e32 v54, vcc, s3, v156
	v_pk_fma_f32 v[36:37], v[36:37], v[68:69], v[44:45] op_sel_hi:[1,0,1]
	v_pk_fma_f32 v[34:35], v[34:35], v[68:69], v[42:43] op_sel_hi:[1,0,1]
	v_mul_f32_e32 v53, v53, v53
	v_cvt_pk_bf16_f32 v51, v51, v52
	v_cvt_pk_bf16_f32 v52, v69, v55
	v_addc_co_u32_e32 v55, vcc, 0, v157, vcc
	v_pk_fma_f32 v[40:41], v[40:41], v[68:69], v[48:49] op_sel_hi:[1,0,1]
	v_pk_fma_f32 v[38:39], v[38:39], v[68:69], v[46:47] op_sel_hi:[1,0,1]
	v_max_f32_e32 v34, 0, v34
	v_max_f32_e32 v35, 0, v35
	v_max_f32_e32 v36, 0, v36
	v_cvt_pk_bf16_f32 v53, v56, v53
	global_store_dwordx4 v[54:55], v[50:53], off
	v_max_f32_e32 v37, 0, v37
	v_max_f32_e32 v38, 0, v38
	v_mul_f32_e32 v50, v34, v34
	v_max_f32_e32 v34, 0, v39
	v_mul_f32_e32 v39, v35, v35
	v_max_f32_e32 v35, 0, v40
	v_mul_f32_e32 v40, v36, v36
	v_max_f32_e32 v36, 0, v41
	v_mul_f32_e32 v34, v34, v34
	v_mul_f32_e32 v35, v35, v35
	v_mul_f32_e32 v36, v36, v36
	v_mul_f32_e32 v37, v37, v37
	v_mul_f32_e32 v38, v38, v38
	v_cvt_pk_bf16_f32 v34, v38, v34
	v_cvt_pk_bf16_f32 v35, v35, v36
	v_cvt_pk_bf16_f32 v36, v50, v39
	v_cvt_pk_bf16_f32 v37, v40, v37
	global_store_dwordx4 v[66:67], v[34:37], off offset:256
	global_load_dword v36, v[158:159], off offset:640
	s_mov_b32 s3, 0x140000
	v_lshl_add_u64 v[34:35], v[156:157], 0, s[30:31]
	s_mov_b64 s[30:31], 0x160000
	s_waitcnt vmcnt(0)
; DEVI unsigned cvt_pk_bf16(float lo, float hi) { unsigned r; asm volatile("v_cvt_pk_bf16_f32 %0, %1, %2" : "=v"(r) : "v"(lo), "v"(hi)); return r; }
;     DEVI void operator()(f32x4 (&acc)[2][2][4][2], const Unit& u, int wr, int wc, int fr, int fq) const {
;     ...
;             for (int m = 0; m < 4; ++m) { bf16_t* rowp = O + (size_t)(row0 + ai * HALF + m * 16) * ldc + col0;
;                 float rstd = 1.0f; if (RS) rstd = rsqrtf(ssq[row0 + ai * HALF + m * 16] * (1.0f / 1024.0f) + EPS);
; #pragma unroll
;                 for (int bj = 0; bj < 2; ++bj) { f32x4 v0 = acc[ai][bj][m][0], v1 = acc[ai][bj][m][1];
;                     if (RS) { v0 = v0 * rstd + sh[bj][0]; v1 = v1 * rstd + sh[bj][1]; }
;                     if (ACT == 1) {
; #pragma unroll
;                         for (int j = 0; j < 4; ++j) { const float a = fmaxf(v0[j], 0.f), b = fmaxf(v1[j], 0.f); v0[j] = a * a; v1[j] = b * b; } }
;                     if (ACT == 2) {
; #pragma unroll
;                         for (int j = 0; j < 4; ++j) { v0[j] = 1.0f + __expf(-fminf(fmaxf(v0[j], -30.f), 30.f)); v1[j] = 1.0f + __expf(-fminf(fmaxf(v1[j], -30.f), 30.f)); } }
;                     u32x4 w; w.x = cvt_pk_bf16(v0[0], v0[1]); w.y = cvt_pk_bf16(v0[2], v0[3]); w.z = cvt_pk_bf16(v1[0], v1[1]); w.w = cvt_pk_bf16(v1[2], v1[3]);
;                     *(u32x4*)(rowp + bj * HALF) = w; } }
; template <class Epi>
; DEVI void gemm_phase(const int wv, LAS unsigned char* lds, const Gemm g, const Order& S, const Epi& E) {
;     ...
;         if (!has_next) break;
;         cur = nxt; cA = nA; cB = nB; ++ui;
	v_fmamk_f32 v36, v36, 0x3a800000, v196
	v_cmp_gt_f32_e32 vcc, s5, v36
	v_mul_f32_e32 v37, 0x4b800000, v36
	s_nop 0
	v_cndmask_b32_e32 v36, v36, v37, vcc
	v_rsq_f32_e32 v36, v36
	s_nop 0
	v_mul_f32_e32 v37, 0x45800000, v36
	v_cndmask_b32_e32 v36, v36, v37, vcc
	v_pk_fma_f32 v[26:27], v[26:27], v[36:37], v[58:59] op_sel_hi:[1,0,1]
	v_pk_fma_f32 v[30:31], v[30:31], v[36:37], v[62:63] op_sel_hi:[1,0,1]
	v_pk_fma_f32 v[28:29], v[28:29], v[36:37], v[60:61] op_sel_hi:[1,0,1]
	v_max_f32_e32 v26, 0, v26
	v_pk_fma_f32 v[32:33], v[32:33], v[36:37], v[64:65] op_sel_hi:[1,0,1]
	v_max_f32_e32 v30, 0, v30
	v_mul_f32_e32 v37, v26, v26
	v_max_f32_e32 v26, 0, v31
	v_max_f32_e32 v27, 0, v27
	v_max_f32_e32 v28, 0, v28
	v_mul_f32_e32 v30, v30, v30
	v_mul_f32_e32 v26, v26, v26
	v_mul_f32_e32 v31, v27, v27
	v_max_f32_e32 v27, 0, v32
	v_mul_f32_e32 v32, v28, v28
	v_max_f32_e32 v28, 0, v33
	v_mul_f32_e32 v27, v27, v27
	v_max_f32_e32 v29, 0, v29
	v_mul_f32_e32 v28, v28, v28
	v_cvt_pk_bf16_f32 v26, v30, v26
	v_add_co_u32_e32 v30, vcc, s3, v156
	v_pk_fma_f32 v[20:21], v[20:21], v[36:37], v[44:45] op_sel_hi:[1,0,1]
	v_pk_fma_f32 v[18:19], v[18:19], v[36:37], v[42:43] op_sel_hi:[1,0,1]
	v_mul_f32_e32 v29, v29, v29
	v_cvt_pk_bf16_f32 v27, v27, v28
	v_cvt_pk_bf16_f32 v28, v37, v31
	v_addc_co_u32_e32 v31, vcc, 0, v157, vcc
	v_pk_fma_f32 v[24:25], v[24:25], v[36:37], v[48:49] op_sel_hi:[1,0,1]
	v_pk_fma_f32 v[22:23], v[22:23], v[36:37], v[46:47] op_sel_hi:[1,0,1]
	v_max_f32_e32 v18, 0, v18
	v_max_f32_e32 v19, 0, v19
	v_max_f32_e32 v20, 0, v20
	v_cvt_pk_bf16_f32 v29, v32, v29
	global_store_dwordx4 v[30:31], v[26:29], off
	v_max_f32_e32 v21, 0, v21
	v_max_f32_e32 v22, 0, v22
	v_mul_f32_e32 v26, v18, v18
	v_max_f32_e32 v18, 0, v23
	v_mul_f32_e32 v23, v19, v19
	v_max_f32_e32 v19, 0, v24
	v_mul_f32_e32 v24, v20, v20
	v_max_f32_e32 v20, 0, v25
	v_mul_f32_e32 v18, v18, v18
	v_mul_f32_e32 v19, v19, v19
	v_mul_f32_e32 v20, v20, v20
	v_mul_f32_e32 v21, v21, v21
	v_mul_f32_e32 v22, v22, v22
	v_cvt_pk_bf16_f32 v18, v22, v18
	v_cvt_pk_bf16_f32 v19, v19, v20
	v_cvt_pk_bf16_f32 v20, v26, v23
	v_cvt_pk_bf16_f32 v21, v24, v21
	global_store_dwordx4 v[34:35], v[18:21], off offset:256
	global_load_dword v20, v[158:159], off offset:704
	s_mov_b32 s3, 0x160000
	v_lshl_add_u64 v[18:19], v[156:157], 0, s[30:31]
	s_mov_b64 s[30:31], s[6:7]
	s_waitcnt vmcnt(0)
	v_fmamk_f32 v20, v20, 0x3a800000, v196
	v_cmp_gt_f32_e32 vcc, s5, v20
	v_mul_f32_e32 v21, 0x4b800000, v20
	s_nop 0
	v_cndmask_b32_e32 v20, v20, v21, vcc
	v_rsq_f32_e32 v20, v20
	s_nop 0
	v_mul_f32_e32 v21, 0x45800000, v20
	v_cndmask_b32_e32 v20, v20, v21, vcc
	v_pk_fma_f32 v[10:11], v[10:11], v[20:21], v[58:59] op_sel_hi:[1,0,1]
	v_pk_fma_f32 v[14:15], v[14:15], v[20:21], v[62:63] op_sel_hi:[1,0,1]
	v_pk_fma_f32 v[12:13], v[12:13], v[20:21], v[60:61] op_sel_hi:[1,0,1]
	v_max_f32_e32 v10, 0, v10
	v_pk_fma_f32 v[16:17], v[16:17], v[20:21], v[64:65] op_sel_hi:[1,0,1]
	v_max_f32_e32 v14, 0, v14
	v_mul_f32_e32 v21, v10, v10
	v_max_f32_e32 v10, 0, v15
	v_max_f32_e32 v11, 0, v11
	v_max_f32_e32 v12, 0, v12
	v_mul_f32_e32 v14, v14, v14
	v_mul_f32_e32 v10, v10, v10
	v_mul_f32_e32 v15, v11, v11
	v_max_f32_e32 v11, 0, v16
	v_mul_f32_e32 v16, v12, v12
	v_max_f32_e32 v12, 0, v17
	v_mul_f32_e32 v11, v11, v11
	v_max_f32_e32 v13, 0, v13
	v_mul_f32_e32 v12, v12, v12
	v_cvt_pk_bf16_f32 v10, v14, v10
	v_add_co_u32_e32 v14, vcc, s3, v156
	v_pk_fma_f32 v[4:5], v[4:5], v[20:21], v[44:45] op_sel_hi:[1,0,1]
	v_pk_fma_f32 v[2:3], v[2:3], v[20:21], v[42:43] op_sel_hi:[1,0,1]
	v_mul_f32_e32 v13, v13, v13
	v_cvt_pk_bf16_f32 v11, v11, v12
	v_cvt_pk_bf16_f32 v12, v21, v15
	v_addc_co_u32_e32 v15, vcc, 0, v157, vcc
	v_pk_fma_f32 v[8:9], v[8:9], v[20:21], v[48:49] op_sel_hi:[1,0,1]
	v_pk_fma_f32 v[6:7], v[6:7], v[20:21], v[46:47] op_sel_hi:[1,0,1]
	v_max_f32_e32 v2, 0, v2
	v_max_f32_e32 v3, 0, v3
	v_max_f32_e32 v4, 0, v4
	v_cvt_pk_bf16_f32 v13, v16, v13
	global_store_dwordx4 v[14:15], v[10:13], off
	v_max_f32_e32 v5, 0, v5
	v_max_f32_e32 v6, 0, v6
	v_mul_f32_e32 v10, v2, v2
	v_max_f32_e32 v2, 0, v7
	v_mul_f32_e32 v7, v3, v3
	v_max_f32_e32 v3, 0, v8
	v_mul_f32_e32 v8, v4, v4
	v_max_f32_e32 v4, 0, v9
	v_mul_f32_e32 v2, v2, v2
	v_mul_f32_e32 v3, v3, v3
	v_mul_f32_e32 v4, v4, v4
	v_mul_f32_e32 v5, v5, v5
	s_and_b64 vcc, exec, s[10:11]
	v_mul_f32_e32 v6, v6, v6
	v_cvt_pk_bf16_f32 v2, v6, v2
	v_cvt_pk_bf16_f32 v3, v3, v4
	v_cvt_pk_bf16_f32 v4, v10, v7
	v_cvt_pk_bf16_f32 v5, v8, v5
	global_store_dwordx4 v[18:19], v[2:5], off offset:256
	s_cbranch_vccz .LBB0_1278
	s_branch .LBB0_1286

; #define PG8_STAGE(bufoff, gbase, voff) do { _Pragma("unroll") for (int _i = 0; _i < 2; ++_i) \
;         __builtin_amdgcn_global_load_lds((const unsigned*)((const char*)(gbase) + (voff)[_i]), (LAS unsigned*)(lds + (bufoff) + ldsw + _i * 8192), 16, 0, 0); } while (0)
; #define PG8_LDA(dst, b, h) do { _Pragma("unroll") for (int m = 0; m < 4; ++m) _Pragma("unroll") for (int k = 0; k < 2; ++k) dst[m][k] = *(const LAS bf16x8*)(lds + PG8_SA(b, h) + aoff + m * 2048 + k * 1024); } while (0)
; #define PG8_LDB(dst, b, h) do { _Pragma("unroll") for (int n = 0; n < 2; ++n) _Pragma("unroll") for (int k = 0; k < 2; ++k) dst[n][k] = *(const LAS bf16x8*)(lds + PG8_SB(b, h) + boff + n * 2048 + k * 1024); } while (0)
; #define PG8_MMA(ai, bj, At, Bt) do { __builtin_amdgcn_s_setprio(1); _Pragma("unroll") for (int m = 0; m < 4; ++m) _Pragma("unroll") for (int n = 0; n < 2; ++n) _Pragma("unroll") for (int k = 0; k < 2; ++k) \
;         acc[ai][bj][m][n] = __builtin_amdgcn_mfma_f32_16x16x32_bf16(Bt[n][k], At[m][k], acc[ai][bj][m][n], 0, 0, 0); __builtin_amdgcn_s_setprio(0); } while (0)
; template <class Epi>
; DEVI void gemm_phase(const int wv, LAS unsigned char* lds, const Gemm g, const Order& S, const Epi& E) {
;     ...
;     for (;;) {
;         const bool has_next = S.next(ui + 1, nxt);
;         const char* nA = has_next ? (const char*)g.A + (size_t)nxt.pb * g.a_bs + (size_t)nxt.pm * tstepA : cA;
;         const char* nB = has_next ? (const char*)g.Bt + (size_t)nxt.pb * g.b_bs + (size_t)nxt.pn * tstepB : cB;
;         for (int t = 0; t < nt; t += 2) {
;             const bool last = (t == nt - 2);
;             const char* a1 = cA + (size_t)(t + 1) * kstep;
;             const char* a2 = last ? nA : cA + (size_t)(t + 2) * kstep; const char* b2 = last ? nB : cB + (size_t)(t + 2) * kstep;
;             const char* a3 = a2 + kstep; const char* b3 = b2 + kstep;
;             PG8_LDB(B0, 0, 0); PG8_SCHED; PG8_LDA(At, 0, 0); PG8_STAGE(PG8_SA(1, 1), a1 + hstepA, voffA);
;             PG8_WAIT_L(8); PG8_BAR; PG8_WAIT_L(0); PG8_MMA(0, 0, At, B0); PG8_BAR; PG8_SCHED;
;             PG8_LDB(B1, 0, 1); PG8_STAGE(PG8_SB(0, 0), b2, voffB);
;             PG8_BAR; PG8_WAIT_L(0); PG8_MMA(0, 1, At, B1); PG8_BAR;
;             PG8_LDA(At, 0, 1); PG8_STAGE(PG8_SA(0, 0), a2, voffA);
;             PG8_BAR; PG8_WAIT_L(0); PG8_MMA(1, 0, At, B0); PG8_BAR; PG8_SCHED;
.LBB0_1352:
	s_ashr_i32 s5, s4, 31
	s_xor_b64 s[6:7], s[34:35], -1
	s_lshl_b64 s[8:9], s[4:5], 21
	v_readlane_b32 s10, v252, 51
	v_readlane_b32 s11, v252, 52
	s_add_u32 s8, s10, s8
	s_addc_u32 s9, s11, s9
	s_and_b64 s[10:11], s[34:35], exec
	s_cselect_b32 s1, s9, s29
	s_cselect_b32 s5, s8, s28
	s_ashr_i32 s3, s2, 31
	s_lshl_b64 s[10:11], s[2:3], 21
	v_readlane_b32 s54, v250, 31
	v_readlane_b32 s55, v250, 32
	s_add_u32 s10, s54, s10
	s_addc_u32 s11, s55, s11
	s_and_b64 s[34:35], s[34:35], exec
	s_cselect_b32 s3, s11, s31
	s_cselect_b32 s53, s10, s30
	s_add_u32 s28, s28, 0x100080
	s_addc_u32 s29, s29, 0
	s_add_u32 s54, s30, 0x100
	v_mov_b32_e32 v2, 0
	s_addc_u32 s55, s31, 0
	s_mov_b32 s56, -2
	s_add_u32 s30, s28, 0xfff00080
	s_addc_u32 s31, s29, -1
	s_add_i32 s57, 0, 0x10000
	v_add_u32_e32 v142, s57, v155
	ds_read_b128 v[130:133], v142
	ds_read_b128 v[134:137], v142 offset:1024
	ds_read_b128 v[138:141], v142 offset:2048
	ds_read_b128 v[142:145], v142 offset:3072
	s_cmp_eq_u32 s56, 60
	s_cselect_b32 s35, s1, s31
	s_cselect_b32 s34, s5, s30
	s_cselect_b32 s31, s3, s55
	s_cselect_b32 s30, s53, s54
	v_lshl_add_u64 v[152:153], s[28:29], 0, v[148:149]
	s_add_i32 m0, s13, 0xc000
	ds_read_b128 v[158:161], v157
	ds_read_b128 v[162:165], v157 offset:1024
	ds_read_b128 v[166:169], v157 offset:2048
	ds_read_b128 v[170:173], v157 offset:3072
	ds_read_b128 v[174:177], v157 offset:4096
	ds_read_b128 v[178:181], v157 offset:5120
	ds_read_b128 v[182:185], v157 offset:6144
	ds_read_b128 v[186:189], v157 offset:7168
	global_load_lds_dwordx4 v[152:153], off
	v_lshl_add_u64 v[152:153], s[28:29], 0, v[150:151]
	s_add_i32 m0, s13, 0xe000
	s_nop 0
	global_load_lds_dwordx4 v[152:153], off
	s_waitcnt lgkmcnt(8)
	s_barrier
	s_waitcnt lgkmcnt(0)
	s_setprio 1
	s_waitcnt lgkmcnt(0)
	v_mfma_f32_16x16x32_bf16 v[122:125], v[130:133], v[158:161], 0
	v_mfma_f32_16x16x32_bf16 v[126:129], v[138:141], v[158:161], 0
	v_mfma_f32_16x16x32_bf16 v[114:117], v[130:133], v[166:169], 0
	v_mfma_f32_16x16x32_bf16 v[118:121], v[138:141], v[166:169], 0
	v_mfma_f32_16x16x32_bf16 v[94:97], v[130:133], v[174:177], 0
	v_mfma_f32_16x16x32_bf16 v[90:93], v[138:141], v[174:177], 0
	v_mfma_f32_16x16x32_bf16 v[86:89], v[130:133], v[182:185], 0
	v_mfma_f32_16x16x32_bf16 v[82:85], v[138:141], v[182:185], 0
	v_mfma_f32_16x16x32_bf16 v[122:125], v[134:137], v[162:165], v[122:125]
	v_mfma_f32_16x16x32_bf16 v[126:129], v[142:145], v[162:165], v[126:129]
	v_mfma_f32_16x16x32_bf16 v[114:117], v[134:137], v[170:173], v[114:117]
	v_mfma_f32_16x16x32_bf16 v[118:121], v[142:145], v[170:173], v[118:121]
	v_mfma_f32_16x16x32_bf16 v[94:97], v[134:137], v[178:181], v[94:97]
	v_mfma_f32_16x16x32_bf16 v[90:93], v[142:145], v[178:181], v[90:93]
	v_mfma_f32_16x16x32_bf16 v[86:89], v[134:137], v[186:189], v[86:89]
	v_mfma_f32_16x16x32_bf16 v[82:85], v[142:145], v[186:189], v[82:85]
	s_setprio 0
	s_barrier
	s_add_i32 s60, 0, 0x14000
	v_add_u32_e32 v152, s60, v155
	s_add_i32 s57, s57, s95
	ds_read_b128 v[190:193], v152
	ds_read_b128 v[200:203], v152 offset:1024
	ds_read_b128 v[204:207], v152 offset:2048
	ds_read_b128 v[208:211], v152 offset:3072
	v_lshl_add_u64 v[152:153], s[30:31], 0, v[0:1]
	s_mov_b32 m0, s57
	v_lshl_add_u64 v[194:195], s[30:31], 0, v[146:147]
	global_load_lds_dwordx4 v[152:153], off
	s_add_i32 m0, s57, 0x2000
	s_nop 0
	global_load_lds_dwordx4 v[194:195], off
	s_barrier
	s_waitcnt lgkmcnt(0)
	s_setprio 1
	s_waitcnt lgkmcnt(0)
	v_mfma_f32_16x16x32_bf16 v[110:113], v[190:193], v[158:161], 0
	v_mfma_f32_16x16x32_bf16 v[102:105], v[204:207], v[158:161], 0
	v_mfma_f32_16x16x32_bf16 v[106:109], v[190:193], v[166:169], 0
	v_mfma_f32_16x16x32_bf16 v[98:101], v[204:207], v[166:169], 0
	v_mfma_f32_16x16x32_bf16 v[78:81], v[190:193], v[174:177], 0
	v_mfma_f32_16x16x32_bf16 v[74:77], v[204:207], v[174:177], 0
	v_mfma_f32_16x16x32_bf16 v[70:73], v[190:193], v[182:185], 0
	v_mfma_f32_16x16x32_bf16 v[66:69], v[204:207], v[182:185], 0
	v_mfma_f32_16x16x32_bf16 v[110:113], v[200:203], v[162:165], v[110:113]
	v_mfma_f32_16x16x32_bf16 v[102:105], v[208:211], v[162:165], v[102:105]
	v_mfma_f32_16x16x32_bf16 v[106:109], v[200:203], v[170:173], v[106:109]
	v_mfma_f32_16x16x32_bf16 v[98:101], v[208:211], v[170:173], v[98:101]
	v_mfma_f32_16x16x32_bf16 v[78:81], v[200:203], v[178:181], v[78:81]
	v_mfma_f32_16x16x32_bf16 v[74:77], v[208:211], v[178:181], v[74:77]
	v_mfma_f32_16x16x32_bf16 v[70:73], v[200:203], v[186:189], v[70:73]
	v_mfma_f32_16x16x32_bf16 v[66:69], v[208:211], v[186:189], v[66:69]
	s_setprio 0
	s_mov_b32 m0, s13
	v_lshl_add_u64 v[212:213], s[34:35], 0, v[0:1]
	s_barrier
	ds_read_b128 v[158:161], v157 offset:16384
	ds_read_b128 v[162:165], v157 offset:17408
	ds_read_b128 v[166:169], v157 offset:18432
	ds_read_b128 v[170:173], v157 offset:19456
	ds_read_b128 v[174:177], v157 offset:20480
	ds_read_b128 v[178:181], v157 offset:21504
	ds_read_b128 v[182:185], v157 offset:22528
	ds_read_b128 v[186:189], v157 offset:23552
	global_load_lds_dwordx4 v[212:213], off
	v_lshl_add_u64 v[214:215], s[34:35], 0, v[146:147]
	s_mov_b32 m0, s38
	s_nop 0
	global_load_lds_dwordx4 v[214:215], off
	s_barrier
; #define PG8_STAGE(bufoff, gbase, voff) do { _Pragma("unroll") for (int _i = 0; _i < 2; ++_i) \
;         __builtin_amdgcn_global_load_lds((const unsigned*)((const char*)(gbase) + (voff)[_i]), (LAS unsigned*)(lds + (bufoff) + ldsw + _i * 8192), 16, 0, 0); } while (0)
; #define PG8_LDA(dst, b, h) do { _Pragma("unroll") for (int m = 0; m < 4; ++m) _Pragma("unroll") for (int k = 0; k < 2; ++k) dst[m][k] = *(const LAS bf16x8*)(lds + PG8_SA(b, h) + aoff + m * 2048 + k * 1024); } while (0)
; #define PG8_LDB(dst, b, h) do { _Pragma("unroll") for (int n = 0; n < 2; ++n) _Pragma("unroll") for (int k = 0; k < 2; ++k) dst[n][k] = *(const LAS bf16x8*)(lds + PG8_SB(b, h) + boff + n * 2048 + k * 1024); } while (0)
; #define PG8_MMA(ai, bj, At, Bt) do { __builtin_amdgcn_s_setprio(1); _Pragma("unroll") for (int m = 0; m < 4; ++m) _Pragma("unroll") for (int n = 0; n < 2; ++n) _Pragma("unroll") for (int k = 0; k < 2; ++k) \
;         acc[ai][bj][m][n] = __builtin_amdgcn_mfma_f32_16x16x32_bf16(Bt[n][k], At[m][k], acc[ai][bj][m][n], 0, 0, 0); __builtin_amdgcn_s_setprio(0); } while (0)
; #define PG8_WAIT_V(n) asm volatile("s_waitcnt vmcnt(" #n ")" ::: "memory")
; #define PG8_WAIT_L(n) asm volatile("s_waitcnt lgkmcnt(" #n ")" ::: "memory")
; #define PG8_BAR __builtin_amdgcn_s_barrier()
; #define PG8_SCHED __builtin_amdgcn_sched_barrier(0)
; template <class Epi>
; DEVI void gemm_phase(const int wv, LAS unsigned char* lds, const Gemm g, const Order& S, const Epi& E) {
;     ...
;             PG8_STAGE(PG8_SB(0, 1), b2 + hstepB, voffB);
;             PG8_WAIT_V(6); PG8_BAR; PG8_MMA(1, 1, At, B1); PG8_BAR;
;             PG8_LDB(B0, 1, 0); PG8_SCHED; PG8_LDA(At, 1, 0); PG8_STAGE(PG8_SA(0, 1), a2 + hstepA, voffA);
;             PG8_WAIT_L(8); PG8_BAR; PG8_WAIT_L(0); PG8_MMA(0, 0, At, B0); PG8_BAR; PG8_SCHED;
;             PG8_LDB(B1, 1, 1); PG8_STAGE(PG8_SB(1, 0), b3, voffB);
;             PG8_BAR; PG8_WAIT_L(0); PG8_MMA(0, 1, At, B1); PG8_BAR;
;             PG8_LDA(At, 1, 1); PG8_STAGE(PG8_SA(1, 0), a3, voffA);
;             PG8_BAR; PG8_WAIT_L(0); PG8_MMA(1, 0, At, B0); PG8_BAR; PG8_SCHED;
	s_waitcnt lgkmcnt(0)
	s_setprio 1
	s_waitcnt lgkmcnt(0)
	v_mfma_f32_16x16x32_bf16 v[62:65], v[130:133], v[158:161], 0
	v_mfma_f32_16x16x32_bf16 v[58:61], v[138:141], v[158:161], 0
	v_mfma_f32_16x16x32_bf16 v[54:57], v[130:133], v[166:169], 0
	v_mfma_f32_16x16x32_bf16 v[50:53], v[138:141], v[166:169], 0
	v_mfma_f32_16x16x32_bf16 v[30:33], v[130:133], v[174:177], 0
	v_mfma_f32_16x16x32_bf16 v[26:29], v[138:141], v[174:177], 0
	v_mfma_f32_16x16x32_bf16 v[22:25], v[130:133], v[182:185], 0
	v_mfma_f32_16x16x32_bf16 v[18:21], v[138:141], v[182:185], 0
	v_mfma_f32_16x16x32_bf16 v[62:65], v[134:137], v[162:165], v[62:65]
	v_mfma_f32_16x16x32_bf16 v[58:61], v[142:145], v[162:165], v[58:61]
	v_mfma_f32_16x16x32_bf16 v[54:57], v[134:137], v[170:173], v[54:57]
	v_mfma_f32_16x16x32_bf16 v[50:53], v[142:145], v[170:173], v[50:53]
	v_mfma_f32_16x16x32_bf16 v[30:33], v[134:137], v[178:181], v[30:33]
	v_mfma_f32_16x16x32_bf16 v[26:29], v[142:145], v[178:181], v[26:29]
	v_mfma_f32_16x16x32_bf16 v[22:25], v[134:137], v[186:189], v[22:25]
	v_mfma_f32_16x16x32_bf16 v[18:21], v[142:145], v[186:189], v[18:21]
	s_setprio 0
	s_barrier
	s_add_u32 s58, s30, 0x100000
	s_addc_u32 s59, s31, 0
	s_add_i32 s57, s60, s95
	v_lshl_add_u64 v[130:131], s[58:59], 0, v[0:1]
	s_mov_b32 m0, s57
	s_nop 0
	global_load_lds_dwordx4 v[130:131], off
	v_lshl_add_u64 v[130:131], s[58:59], 0, v[146:147]
	s_add_i32 m0, s57, 0x2000
	s_nop 0
	global_load_lds_dwordx4 v[130:131], off
	s_waitcnt vmcnt(6)
	s_barrier
	s_setprio 1
	v_mfma_f32_16x16x32_bf16 v[46:49], v[190:193], v[158:161], 0
	v_mfma_f32_16x16x32_bf16 v[42:45], v[204:207], v[158:161], 0
	v_mfma_f32_16x16x32_bf16 v[38:41], v[190:193], v[166:169], 0
	v_mfma_f32_16x16x32_bf16 v[34:37], v[204:207], v[166:169], 0
	v_mfma_f32_16x16x32_bf16 v[14:17], v[190:193], v[174:177], 0
	v_mfma_f32_16x16x32_bf16 v[10:13], v[204:207], v[174:177], 0
	v_mfma_f32_16x16x32_bf16 v[6:9], v[190:193], v[182:185], 0
	v_mfma_f32_16x16x32_bf16 v[2:5], v[204:207], v[182:185], 0
	v_mfma_f32_16x16x32_bf16 v[46:49], v[200:203], v[162:165], v[46:49]
	v_mfma_f32_16x16x32_bf16 v[42:45], v[208:211], v[162:165], v[42:45]
	v_mfma_f32_16x16x32_bf16 v[38:41], v[200:203], v[170:173], v[38:41]
	v_mfma_f32_16x16x32_bf16 v[34:37], v[208:211], v[170:173], v[34:37]
	v_mfma_f32_16x16x32_bf16 v[14:17], v[200:203], v[178:181], v[14:17]
	v_mfma_f32_16x16x32_bf16 v[10:13], v[208:211], v[178:181], v[10:13]
	v_mfma_f32_16x16x32_bf16 v[6:9], v[200:203], v[186:189], v[6:9]
	v_mfma_f32_16x16x32_bf16 v[2:5], v[208:211], v[186:189], v[2:5]
	s_setprio 0
	s_add_i32 s57, 0, 0x18000
	v_add_u32_e32 v142, s57, v155
	s_barrier
	ds_read_b128 v[130:133], v142
	ds_read_b128 v[134:137], v142 offset:1024
	ds_read_b128 v[138:141], v142 offset:2048
	ds_read_b128 v[142:145], v142 offset:3072
	s_add_u32 s34, s34, 0x100000
	s_addc_u32 s35, s35, 0
	s_mov_b32 m0, s39
	v_lshl_add_u64 v[190:191], s[34:35], 0, v[0:1]
	ds_read_b128 v[158:161], v157 offset:32768
	ds_read_b128 v[162:165], v157 offset:33792
	ds_read_b128 v[166:169], v157 offset:34816
	ds_read_b128 v[170:173], v157 offset:35840
	ds_read_b128 v[174:177], v157 offset:36864
	ds_read_b128 v[178:181], v157 offset:37888
	ds_read_b128 v[182:185], v157 offset:38912
	ds_read_b128 v[186:189], v157 offset:39936
	global_load_lds_dwordx4 v[190:191], off
	v_lshl_add_u64 v[190:191], s[34:35], 0, v[146:147]
	s_mov_b32 m0, s40
	s_nop 0
	global_load_lds_dwordx4 v[190:191], off
	s_waitcnt lgkmcnt(8)
	s_barrier
	s_waitcnt lgkmcnt(0)
	s_setprio 1
	s_waitcnt lgkmcnt(0)
	v_mfma_f32_16x16x32_bf16 v[122:125], v[130:133], v[158:161], v[122:125]
	v_mfma_f32_16x16x32_bf16 v[126:129], v[138:141], v[158:161], v[126:129]
	v_mfma_f32_16x16x32_bf16 v[114:117], v[130:133], v[166:169], v[114:117]
	v_mfma_f32_16x16x32_bf16 v[118:121], v[138:141], v[166:169], v[118:121]
	v_mfma_f32_16x16x32_bf16 v[94:97], v[130:133], v[174:177], v[94:97]
	v_mfma_f32_16x16x32_bf16 v[90:93], v[138:141], v[174:177], v[90:93]
	v_mfma_f32_16x16x32_bf16 v[86:89], v[130:133], v[182:185], v[86:89]
	v_mfma_f32_16x16x32_bf16 v[82:85], v[138:141], v[182:185], v[82:85]
	v_mfma_f32_16x16x32_bf16 v[122:125], v[134:137], v[162:165], v[122:125]
	v_mfma_f32_16x16x32_bf16 v[126:129], v[142:145], v[162:165], v[126:129]
	v_mfma_f32_16x16x32_bf16 v[114:117], v[134:137], v[170:173], v[114:117]
	v_mfma_f32_16x16x32_bf16 v[118:121], v[142:145], v[170:173], v[118:121]
	v_mfma_f32_16x16x32_bf16 v[94:97], v[134:137], v[178:181], v[94:97]
	v_mfma_f32_16x16x32_bf16 v[90:93], v[142:145], v[178:181], v[90:93]
	v_mfma_f32_16x16x32_bf16 v[86:89], v[134:137], v[186:189], v[86:89]
	v_mfma_f32_16x16x32_bf16 v[82:85], v[142:145], v[186:189], v[82:85]
	s_setprio 0
	s_barrier
	s_add_i32 s34, 0, 0x1c000
	s_add_i32 s35, s57, s95
	v_add_u32_e32 v199, s34, v155
	v_lshl_add_u64 v[152:153], v[152:153], 0, s[92:93]
	s_mov_b32 m0, s35
	ds_read_b128 v[190:193], v199
	ds_read_b128 v[200:203], v199 offset:1024
	ds_read_b128 v[204:207], v199 offset:2048
	ds_read_b128 v[208:211], v199 offset:3072
	global_load_lds_dwordx4 v[152:153], off
	v_lshl_add_u64 v[152:153], v[194:195], 0, s[92:93]
	s_add_i32 m0, s35, 0x2000
	s_nop 0
	global_load_lds_dwordx4 v[152:153], off
	s_barrier
; #define PG8_STAGE(bufoff, gbase, voff) do { _Pragma("unroll") for (int _i = 0; _i < 2; ++_i) \
;         __builtin_amdgcn_global_load_lds((const unsigned*)((const char*)(gbase) + (voff)[_i]), (LAS unsigned*)(lds + (bufoff) + ldsw + _i * 8192), 16, 0, 0); } while (0)
; #define PG8_MMA(ai, bj, At, Bt) do { __builtin_amdgcn_s_setprio(1); _Pragma("unroll") for (int m = 0; m < 4; ++m) _Pragma("unroll") for (int n = 0; n < 2; ++n) _Pragma("unroll") for (int k = 0; k < 2; ++k) \
;         acc[ai][bj][m][n] = __builtin_amdgcn_mfma_f32_16x16x32_bf16(Bt[n][k], At[m][k], acc[ai][bj][m][n], 0, 0, 0); __builtin_amdgcn_s_setprio(0); } while (0)
; #define PG8_WAIT_V(n) asm volatile("s_waitcnt vmcnt(" #n ")" ::: "memory")
; #define PG8_WAIT_L(n) asm volatile("s_waitcnt lgkmcnt(" #n ")" ::: "memory")
; #define PG8_BAR __builtin_amdgcn_s_barrier()
; #define PG8_SCHED __builtin_amdgcn_sched_barrier(0)
; template <class Epi>
; DEVI void gemm_phase(const int wv, LAS unsigned char* lds, const Gemm g, const Order& S, const Epi& E) {
;     ...
;             PG8_BAR; PG8_WAIT_L(0); PG8_MMA(1, 0, At, B0); PG8_BAR; PG8_SCHED;
;             PG8_STAGE(PG8_SB(1, 1), b3 + hstepB, voffB);
;             PG8_WAIT_V(6); PG8_BAR; PG8_MMA(1, 1, At, B1); PG8_BAR;
;         }
	s_waitcnt lgkmcnt(0)
	s_setprio 1
	s_waitcnt lgkmcnt(0)
	v_mfma_f32_16x16x32_bf16 v[110:113], v[190:193], v[158:161], v[110:113]
	v_mfma_f32_16x16x32_bf16 v[102:105], v[204:207], v[158:161], v[102:105]
	v_mfma_f32_16x16x32_bf16 v[106:109], v[190:193], v[166:169], v[106:109]
	v_mfma_f32_16x16x32_bf16 v[98:101], v[204:207], v[166:169], v[98:101]
	v_mfma_f32_16x16x32_bf16 v[78:81], v[190:193], v[174:177], v[78:81]
	v_mfma_f32_16x16x32_bf16 v[74:77], v[204:207], v[174:177], v[74:77]
	v_mfma_f32_16x16x32_bf16 v[70:73], v[190:193], v[182:185], v[70:73]
	v_mfma_f32_16x16x32_bf16 v[66:69], v[204:207], v[182:185], v[66:69]
	v_mfma_f32_16x16x32_bf16 v[110:113], v[200:203], v[162:165], v[110:113]
	v_mfma_f32_16x16x32_bf16 v[102:105], v[208:211], v[162:165], v[102:105]
	v_mfma_f32_16x16x32_bf16 v[106:109], v[200:203], v[170:173], v[106:109]
	v_mfma_f32_16x16x32_bf16 v[98:101], v[208:211], v[170:173], v[98:101]
	v_mfma_f32_16x16x32_bf16 v[78:81], v[200:203], v[178:181], v[78:81]
	v_mfma_f32_16x16x32_bf16 v[74:77], v[208:211], v[178:181], v[74:77]
	v_mfma_f32_16x16x32_bf16 v[70:73], v[200:203], v[186:189], v[70:73]
	v_mfma_f32_16x16x32_bf16 v[66:69], v[208:211], v[186:189], v[66:69]
	s_setprio 0
	s_mov_b32 m0, s41
	v_lshl_add_u64 v[152:153], v[212:213], 0, s[92:93]
	s_barrier
	ds_read_b128 v[158:161], v157 offset:49152
	ds_read_b128 v[162:165], v157 offset:50176
	ds_read_b128 v[166:169], v157 offset:51200
	ds_read_b128 v[170:173], v157 offset:52224
	ds_read_b128 v[174:177], v157 offset:53248
	ds_read_b128 v[178:181], v157 offset:54272
	ds_read_b128 v[182:185], v157 offset:55296
	ds_read_b128 v[186:189], v157 offset:56320
	global_load_lds_dwordx4 v[152:153], off
	v_lshl_add_u64 v[152:153], v[214:215], 0, s[92:93]
	s_mov_b32 m0, s50
	s_nop 0
	global_load_lds_dwordx4 v[152:153], off
	s_barrier
	s_waitcnt lgkmcnt(0)
	s_setprio 1
	s_waitcnt lgkmcnt(0)
	v_mfma_f32_16x16x32_bf16 v[62:65], v[130:133], v[158:161], v[62:65]
	v_mfma_f32_16x16x32_bf16 v[58:61], v[138:141], v[158:161], v[58:61]
	v_mfma_f32_16x16x32_bf16 v[54:57], v[130:133], v[166:169], v[54:57]
	v_mfma_f32_16x16x32_bf16 v[50:53], v[138:141], v[166:169], v[50:53]
	v_mfma_f32_16x16x32_bf16 v[30:33], v[130:133], v[174:177], v[30:33]
	v_mfma_f32_16x16x32_bf16 v[26:29], v[138:141], v[174:177], v[26:29]
	v_mfma_f32_16x16x32_bf16 v[22:25], v[130:133], v[182:185], v[22:25]
	v_mfma_f32_16x16x32_bf16 v[18:21], v[138:141], v[182:185], v[18:21]
	v_mfma_f32_16x16x32_bf16 v[62:65], v[134:137], v[162:165], v[62:65]
	v_mfma_f32_16x16x32_bf16 v[58:61], v[142:145], v[162:165], v[58:61]
	v_mfma_f32_16x16x32_bf16 v[54:57], v[134:137], v[170:173], v[54:57]
	v_mfma_f32_16x16x32_bf16 v[50:53], v[142:145], v[170:173], v[50:53]
	v_mfma_f32_16x16x32_bf16 v[30:33], v[134:137], v[178:181], v[30:33]
	v_mfma_f32_16x16x32_bf16 v[26:29], v[142:145], v[178:181], v[26:29]
	v_mfma_f32_16x16x32_bf16 v[22:25], v[134:137], v[186:189], v[22:25]
	v_mfma_f32_16x16x32_bf16 v[18:21], v[142:145], v[186:189], v[18:21]
	s_setprio 0
	s_barrier
	s_add_u32 s30, s30, 0x100080
	s_addc_u32 s31, s31, 0
	s_add_i32 s34, s34, s95
	v_lshl_add_u64 v[130:131], s[30:31], 0, v[0:1]
	s_mov_b32 m0, s34
	s_nop 0
	global_load_lds_dwordx4 v[130:131], off
	v_lshl_add_u64 v[130:131], s[30:31], 0, v[146:147]
	s_add_i32 m0, s34, 0x2000
	s_nop 0
	global_load_lds_dwordx4 v[130:131], off
	s_waitcnt vmcnt(6)
	s_barrier
	s_setprio 1
	v_mfma_f32_16x16x32_bf16 v[46:49], v[190:193], v[158:161], v[46:49]
	v_mfma_f32_16x16x32_bf16 v[42:45], v[204:207], v[158:161], v[42:45]
	v_mfma_f32_16x16x32_bf16 v[38:41], v[190:193], v[166:169], v[38:41]
	v_mfma_f32_16x16x32_bf16 v[34:37], v[204:207], v[166:169], v[34:37]
	v_mfma_f32_16x16x32_bf16 v[14:17], v[190:193], v[174:177], v[14:17]
	v_mfma_f32_16x16x32_bf16 v[10:13], v[204:207], v[174:177], v[10:13]
	v_mfma_f32_16x16x32_bf16 v[6:9], v[190:193], v[182:185], v[6:9]
	v_mfma_f32_16x16x32_bf16 v[2:5], v[204:207], v[182:185], v[2:5]
	v_mfma_f32_16x16x32_bf16 v[46:49], v[200:203], v[162:165], v[46:49]
	v_mfma_f32_16x16x32_bf16 v[42:45], v[208:211], v[162:165], v[42:45]
	v_mfma_f32_16x16x32_bf16 v[38:41], v[200:203], v[170:173], v[38:41]
	v_mfma_f32_16x16x32_bf16 v[34:37], v[208:211], v[170:173], v[34:37]
	v_mfma_f32_16x16x32_bf16 v[14:17], v[200:203], v[178:181], v[14:17]
	v_mfma_f32_16x16x32_bf16 v[10:13], v[208:211], v[178:181], v[10:13]
	v_mfma_f32_16x16x32_bf16 v[6:9], v[200:203], v[186:189], v[6:9]
	v_mfma_f32_16x16x32_bf16 v[2:5], v[208:211], v[186:189], v[2:5]
	s_setprio 0
	s_add_i32 s56, s56, 2
	s_add_u32 s28, s28, 0x100
	s_addc_u32 s29, s29, 0
	s_add_u32 s54, s54, 0x100
	s_addc_u32 s55, s55, 0
	s_cmp_gt_u32 s56, 61
	s_barrier
	s_cbranch_scc0 .LBB0_1353
	s_branch .Lzp_epi_4

; DEVI const float* modrow(const Params& p, int l, int row) { const int bi = row < NLAT ? (row >> 11) : 16; return (const float*)(p.ws + OFF_MOD) + (size_t)(l * 17 + bi) * 6144; }
;     DEVI void operator()(f32x4 (&acc)[2][2][4][2], const Unit& u, int wr, int wc, int fr, int fq) const {
;         const int row0 = u.pm * BM + wr * 64 + fr, col0 = u.pn * BM + wc * 32 + 4 * fq;
;         const float* gr = modrow(p, l, u.pm * BM) + goff + col0;
;         f32x4 gv[2][2];
; #pragma unroll
;         for (int bj = 0; bj < 2; ++bj)
; #pragma unroll
;             for (int n = 0; n < 2; ++n) gv[bj][n] = *(const f32x4*)(gr + bj * HALF + n * 16);
;         f32x4 av[2][2];
;         if (emit) { const int bi = u.pm * BM < NLAT ? (u.pm * BM) >> 11 : 16; const float* ar = (const float*)(p.ws + OFF_A2) + (size_t)(l * 17 + bi) * 1024 + col0;
; #pragma unroll
;             for (int bj = 0; bj < 2; ++bj)
; #pragma unroll
;                 for (int n = 0; n < 2; ++n) av[bj][n] = *(const f32x4*)(ar + bj * HALF + n * 16); }
; #pragma unroll
;         for (int am = 0; am < 4; ++am) {
;             const int ai = am >> 1, mb = (am & 1) * 2;
;             f32x4 xv[2][2][2];
; #pragma unroll
;             for (int mm = 0; mm < 2; ++mm) { const int r = row0 + ai * HALF + (mb + mm) * 16;
;                 const float* xi = (in_is_stream ? (const float*)xrow_out(p, r) : xrow_in(p, l, r)) + col0;
; #pragma unroll
;                 for (int bj = 0; bj < 2; ++bj)
; #pragma unroll
;                     for (int n = 0; n < 2; ++n) xv[mm][bj][n] = *(const f32x4*)(xi + bj * HALF + n * 16); }
; #pragma unroll
;             for (int mm = 0; mm < 2; ++mm) { const int m = mb + mm; const int r = row0 + ai * HALF + m * 16; float* xo = xrow_out(p, r) + col0;
;                 float ssp = 0.f;
; #pragma unroll
;                 for (int bj = 0; bj < 2; ++bj)
; #pragma unroll
;                     for (int n = 0; n < 2; ++n) { const f32x4 xn = xv[mm][bj][n] + gv[bj][n] * acc[ai][bj][m][n]; *(f32x4*)(xo + bj * HALF + n * 16) = xn;
.Lzp_epi_4:
	s_lshl_b32 s3, s12, 8
	v_lshl_or_b32 v130, s0, 8, v156
	s_min_i32 s0, s3, 0x8000
	s_ashr_i32 s0, s0, 11
	s_add_i32 s0, s0, s51
	s_mul_hi_i32 s1, s0, 0x6000
	s_mulk_i32 s0, 0x6000
	s_add_u32 s0, s24, s0
	v_ashrrev_i32_e32 v131, 31, v130
	s_addc_u32 s1, s25, s1
	v_lshlrev_b64 v[152:153], 2, v[130:131]
	v_lshl_add_u64 v[138:139], s[0:1], 0, v[152:153]
	s_mov_b64 s[0:1], 0x1e085000
	v_lshl_add_u64 v[140:141], v[138:139], 0, s[0:1]
	s_mov_b32 s0, 0x1e085000
	v_add_u32_e32 v161, s3, v154
	s_mov_b32 s3, 0x8000
	v_add_co_u32_e32 v138, vcc, s0, v138
	v_add_u32_e32 v142, 0xffff8000, v161
	v_ashrrev_i32_e32 v143, 31, v161
	v_cmp_gt_i32_e64 s[0:1], s3, v161
	v_mov_b32_e32 v160, s17
	v_mov_b32_e32 v162, s23
	v_cndmask_b32_e64 v143, 0, v143, s[0:1]
	v_cndmask_b32_e64 v142, v142, v161, s[0:1]
	v_mov_b32_e32 v158, s16
	v_mov_b32_e32 v159, s22
	v_cndmask_b32_e64 v145, v160, v162, s[0:1]
	v_cndmask_b32_e64 v144, v158, v159, s[0:1]
	v_lshlrev_b64 v[142:143], 12, v[142:143]
	v_lshl_add_u64 v[142:143], v[144:145], 0, v[142:143]
	v_lshl_add_u64 v[200:201], v[142:143], 0, v[152:153]
	v_or_b32_e32 v142, 16, v161
	v_add_u32_e32 v144, 0xffff8010, v161
	v_ashrrev_i32_e32 v143, 31, v142
	v_cmp_gt_i32_e64 s[0:1], s3, v142
	v_addc_co_u32_e32 v139, vcc, 0, v139, vcc
	s_nop 0
	v_cndmask_b32_e64 v143, 0, v143, s[0:1]
	v_cndmask_b32_e64 v142, v144, v142, s[0:1]
	v_cndmask_b32_e64 v145, v160, v162, s[0:1]
	v_cndmask_b32_e64 v144, v158, v159, s[0:1]
	v_lshlrev_b64 v[142:143], 12, v[142:143]
	v_lshl_add_u64 v[142:143], v[144:145], 0, v[142:143]
	v_lshl_add_u64 v[202:203], v[142:143], 0, v[152:153]
	global_load_dwordx4 v[134:137], v[140:141], off offset:64
	global_load_dwordx4 v[130:133], v[140:141], off offset:512
	global_load_dwordx4 v[164:167], v[200:201], off
	global_load_dwordx4 v[168:171], v[200:201], off offset:64
	global_load_dwordx4 v[172:175], v[200:201], off offset:512
	global_load_dwordx4 v[176:179], v[202:203], off offset:64
	global_load_dwordx4 v[180:183], v[202:203], off offset:512
	global_load_dwordx4 v[142:145], v[138:139], off
	s_nop 0
	global_load_dwordx4 v[138:141], v[140:141], off offset:576
	s_nop 0
	global_load_dwordx4 v[184:187], v[200:201], off offset:576
	global_load_dwordx4 v[188:191], v[202:203], off
	global_load_dwordx4 v[192:195], v[202:203], off offset:576
	v_or_b32_e32 v163, 32, v161
	v_add_u32_e32 v199, 0xffff8020, v161
	v_ashrrev_i32_e32 v204, 31, v163
	v_cmp_gt_i32_e32 vcc, s3, v163
	s_movk_i32 s0, 0x7f80
	s_mov_b32 s12, s4
	v_cndmask_b32_e32 v205, 0, v204, vcc
	v_cndmask_b32_e32 v204, v199, v163, vcc
	v_cndmask_b32_e32 v207, v160, v162, vcc
	v_cndmask_b32_e32 v206, v158, v159, vcc
	v_lshlrev_b64 v[204:205], 12, v[204:205]
	v_lshl_add_u64 v[204:205], v[206:207], 0, v[204:205]
	v_lshl_add_u64 v[204:205], v[204:205], 0, v[152:153]
	v_add_u32_e32 v163, 0xffff8080, v161
	s_mov_b64 s[30:31], s[10:11]
	s_mov_b64 s[28:29], s[8:9]
	s_movk_i32 s55, 0xc00
	s_waitcnt vmcnt(0)
	v_pk_fma_f32 v[124:125], v[124:125], v[144:145], v[166:167]
	v_pk_fma_f32 v[128:129], v[128:129], v[136:137], v[170:171]
	v_pk_fma_f32 v[126:127], v[126:127], v[134:135], v[168:169]
	v_pk_fma_f32 v[112:113], v[112:113], v[132:133], v[174:175]
	v_pk_fma_f32 v[110:111], v[110:111], v[130:131], v[172:173]
	v_pk_fma_f32 v[122:123], v[122:123], v[142:143], v[164:165]
	v_pk_fma_f32 v[98:99], v[98:99], v[138:139], v[192:193]
	v_pk_fma_f32 v[120:121], v[120:121], v[136:137], v[178:179]
	v_pk_fma_f32 v[118:119], v[118:119], v[134:135], v[176:177]
	v_pk_fma_f32 v[108:109], v[108:109], v[132:133], v[182:183]
	v_pk_fma_f32 v[106:107], v[106:107], v[130:131], v[180:181]
	global_store_dwordx4 v[200:201], v[126:129], off offset:64
	global_store_dwordx4 v[200:201], v[110:113], off offset:512
	v_pk_fma_f32 v[104:105], v[104:105], v[140:141], v[186:187]
	v_pk_fma_f32 v[102:103], v[102:103], v[138:139], v[184:185]
	v_pk_fma_f32 v[112:113], v[116:117], v[144:145], v[190:191]
	v_pk_fma_f32 v[110:111], v[114:115], v[142:143], v[188:189]
	v_pk_fma_f32 v[100:101], v[100:101], v[140:141], v[194:195]
	global_store_dwordx4 v[200:201], v[122:125], off
	global_store_dwordx4 v[200:201], v[102:105], off offset:576
	global_store_dwordx4 v[202:203], v[110:113], off
	global_store_dwordx4 v[202:203], v[118:121], off offset:64
	global_store_dwordx4 v[202:203], v[106:109], off offset:512
	global_store_dwordx4 v[202:203], v[98:101], off offset:576
	v_add_u32_e32 v116, 0xffff8030, v161
	global_load_dwordx4 v[100:103], v[204:205], off
	global_load_dwordx4 v[104:107], v[204:205], off offset:64
	global_load_dwordx4 v[108:111], v[204:205], off offset:512
	global_load_dwordx4 v[112:115], v[204:205], off offset:576
	v_or_b32_e32 v98, 48, v161
	v_ashrrev_i32_e32 v99, 31, v98
	v_cmp_gt_i32_e32 vcc, s3, v98
	v_add_u32_e32 v170, 0x90, v161
	v_add_u32_e32 v172, 0xffff8090, v161
	v_cndmask_b32_e32 v99, 0, v99, vcc
	v_cndmask_b32_e32 v98, v116, v98, vcc
	v_cndmask_b32_e32 v117, v160, v162, vcc
	v_cndmask_b32_e32 v116, v158, v159, vcc
	v_lshlrev_b64 v[98:99], 12, v[98:99]
	v_lshl_add_u64 v[98:99], v[116:117], 0, v[98:99]
	v_lshl_add_u64 v[128:129], v[98:99], 0, v[152:153]
	global_load_dwordx4 v[116:119], v[128:129], off
	global_load_dwordx4 v[120:123], v[128:129], off offset:64
	global_load_dwordx4 v[124:127], v[128:129], off offset:512
	global_load_dwordx4 v[164:167], v[128:129], off offset:576
	v_add_u32_e32 v98, 0x80, v161
	v_ashrrev_i32_e32 v99, 31, v98
	v_cmp_gt_i32_e32 vcc, s0, v161
	s_movk_i32 s0, 0x7f70
	v_ashrrev_i32_e32 v171, 31, v170
	v_cndmask_b32_e32 v99, 0, v99, vcc
	v_cndmask_b32_e32 v98, v163, v98, vcc
	v_cndmask_b32_e32 v169, v160, v162, vcc
	v_cndmask_b32_e32 v168, v158, v159, vcc
	v_cmp_gt_i32_e32 vcc, s0, v161
	v_lshlrev_b64 v[98:99], 12, v[98:99]
	v_lshl_add_u64 v[98:99], v[168:169], 0, v[98:99]
	v_cndmask_b32_e32 v171, 0, v171, vcc
	v_cndmask_b32_e32 v170, v172, v170, vcc
	v_cndmask_b32_e32 v173, v160, v162, vcc
	v_cndmask_b32_e32 v172, v158, v159, vcc
	v_lshl_add_u64 v[98:99], v[98:99], 0, v[152:153]
	s_movk_i32 s0, 0x7f60
	v_cmp_gt_i32_e32 vcc, s0, v161
	s_movk_i32 s0, 0x7f50
	s_waitcnt vmcnt(0)
;     DEVI void operator()(f32x4 (&acc)[2][2][4][2], const Unit& u, int wr, int wc, int fr, int fq) const {
;     ...
;         for (int am = 0; am < 4; ++am) {
;             const int ai = am >> 1, mb = (am & 1) * 2;
;             f32x4 xv[2][2][2];
; #pragma unroll
;             for (int mm = 0; mm < 2; ++mm) { const int r = row0 + ai * HALF + (mb + mm) * 16;
;                 const float* xi = (in_is_stream ? (const float*)xrow_out(p, r) : xrow_in(p, l, r)) + col0;
; #pragma unroll
;                 for (int bj = 0; bj < 2; ++bj)
; #pragma unroll
;                     for (int n = 0; n < 2; ++n) xv[mm][bj][n] = *(const f32x4*)(xi + bj * HALF + n * 16); }
; #pragma unroll
;             for (int mm = 0; mm < 2; ++mm) { const int m = mb + mm; const int r = row0 + ai * HALF + m * 16; float* xo = xrow_out(p, r) + col0;
;                 float ssp = 0.f;
; #pragma unroll
;                 for (int bj = 0; bj < 2; ++bj)
; #pragma unroll
;                     for (int n = 0; n < 2; ++n) { const f32x4 xn = xv[mm][bj][n] + gv[bj][n] * acc[ai][bj][m][n]; *(f32x4*)(xo + bj * HALF + n * 16) = xn;
; template <class Epi>
; DEVI void gemm_phase(const int wv, LAS unsigned char* lds, const Gemm g, const Order& S, const Epi& E) {
;     ...
;         if (!has_next) break;
;         cur = nxt; cA = nA; cB = nB; ++ui;
	v_pk_fma_f32 v[96:97], v[96:97], v[144:145], v[102:103]
	v_pk_fma_f32 v[94:95], v[94:95], v[142:143], v[100:101]
	v_pk_fma_f32 v[78:79], v[78:79], v[130:131], v[108:109]
	v_pk_fma_f32 v[92:93], v[92:93], v[136:137], v[106:107]
	v_pk_fma_f32 v[90:91], v[90:91], v[134:135], v[104:105]
	v_pk_fma_f32 v[80:81], v[80:81], v[132:133], v[110:111]
	v_pk_fma_f32 v[76:77], v[76:77], v[140:141], v[114:115]
	v_pk_fma_f32 v[74:75], v[74:75], v[138:139], v[112:113]
	v_add_u32_e32 v102, 0xa0, v161
	v_add_u32_e32 v104, 0xffff80a0, v161
	v_add_u32_e32 v106, 0xb0, v161
	v_ashrrev_i32_e32 v103, 31, v102
	v_add_u32_e32 v108, 0xffff80b0, v161
	v_pk_fma_f32 v[88:89], v[88:89], v[144:145], v[118:119]
	v_pk_fma_f32 v[86:87], v[86:87], v[142:143], v[116:117]
	v_pk_fma_f32 v[84:85], v[84:85], v[136:137], v[122:123]
	v_pk_fma_f32 v[82:83], v[82:83], v[134:135], v[120:121]
	v_pk_fma_f32 v[72:73], v[72:73], v[132:133], v[126:127]
	v_pk_fma_f32 v[70:71], v[70:71], v[130:131], v[124:125]
	v_pk_fma_f32 v[68:69], v[68:69], v[140:141], v[166:167]
	v_pk_fma_f32 v[66:67], v[66:67], v[138:139], v[164:165]
	global_store_dwordx4 v[204:205], v[94:97], off
	global_store_dwordx4 v[204:205], v[90:93], off offset:64
	global_store_dwordx4 v[204:205], v[78:81], off offset:512
	global_store_dwordx4 v[204:205], v[74:77], off offset:576
	global_store_dwordx4 v[128:129], v[86:89], off
	global_store_dwordx4 v[128:129], v[82:85], off offset:64
	global_store_dwordx4 v[128:129], v[70:73], off offset:512
	global_store_dwordx4 v[128:129], v[66:69], off offset:576
	v_lshlrev_b64 v[78:79], 12, v[170:171]
	v_lshl_add_u64 v[82:83], v[172:173], 0, v[78:79]
	global_load_dwordx4 v[66:69], v[98:99], off
	global_load_dwordx4 v[70:73], v[98:99], off offset:64
	global_load_dwordx4 v[74:77], v[98:99], off offset:512
	global_load_dwordx4 v[78:81], v[98:99], off offset:576
	v_lshl_add_u64 v[100:101], v[82:83], 0, v[152:153]
	global_load_dwordx4 v[82:85], v[100:101], off
	global_load_dwordx4 v[86:89], v[100:101], off offset:64
	global_load_dwordx4 v[90:93], v[100:101], off offset:512
	global_load_dwordx4 v[94:97], v[100:101], off offset:576
	v_ashrrev_i32_e32 v107, 31, v106
	v_cndmask_b32_e32 v103, 0, v103, vcc
	v_cndmask_b32_e32 v102, v104, v102, vcc
	v_cndmask_b32_e32 v105, v160, v162, vcc
	v_cndmask_b32_e32 v104, v158, v159, vcc
	v_cmp_gt_i32_e32 vcc, s0, v161
	v_lshlrev_b64 v[102:103], 12, v[102:103]
	v_lshl_add_u64 v[102:103], v[104:105], 0, v[102:103]
	v_cndmask_b32_e32 v107, 0, v107, vcc
	v_cndmask_b32_e32 v106, v108, v106, vcc
	v_cndmask_b32_e32 v109, v160, v162, vcc
	v_cndmask_b32_e32 v108, v158, v159, vcc
	v_lshl_add_u64 v[102:103], v[102:103], 0, v[152:153]
	s_mov_b32 s0, s2
	s_and_b64 vcc, exec, s[6:7]
	s_waitcnt vmcnt(0)
	v_pk_fma_f32 v[64:65], v[64:65], v[144:145], v[68:69]
	v_pk_fma_f32 v[62:63], v[62:63], v[142:143], v[66:67]
	v_pk_fma_f32 v[46:47], v[46:47], v[130:131], v[74:75]
	v_pk_fma_f32 v[60:61], v[60:61], v[136:137], v[72:73]
	v_pk_fma_f32 v[58:59], v[58:59], v[134:135], v[70:71]
	v_pk_fma_f32 v[48:49], v[48:49], v[132:133], v[76:77]
	v_pk_fma_f32 v[44:45], v[44:45], v[140:141], v[80:81]
	v_pk_fma_f32 v[42:43], v[42:43], v[138:139], v[78:79]
	v_pk_fma_f32 v[56:57], v[56:57], v[144:145], v[84:85]
	v_pk_fma_f32 v[54:55], v[54:55], v[142:143], v[82:83]
	v_pk_fma_f32 v[52:53], v[52:53], v[136:137], v[88:89]
	v_pk_fma_f32 v[50:51], v[50:51], v[134:135], v[86:87]
	v_pk_fma_f32 v[40:41], v[40:41], v[132:133], v[92:93]
	v_pk_fma_f32 v[38:39], v[38:39], v[130:131], v[90:91]
	v_pk_fma_f32 v[36:37], v[36:37], v[140:141], v[96:97]
	v_pk_fma_f32 v[34:35], v[34:35], v[138:139], v[94:95]
	global_store_dwordx4 v[98:99], v[62:65], off
	global_store_dwordx4 v[98:99], v[58:61], off offset:64
	global_store_dwordx4 v[98:99], v[46:49], off offset:512
	global_store_dwordx4 v[98:99], v[42:45], off offset:576
	global_store_dwordx4 v[100:101], v[54:57], off
	global_store_dwordx4 v[100:101], v[50:53], off offset:64
	global_store_dwordx4 v[100:101], v[38:41], off offset:512
	global_store_dwordx4 v[100:101], v[34:37], off offset:576
	v_lshlrev_b64 v[46:47], 12, v[106:107]
	v_lshl_add_u64 v[50:51], v[108:109], 0, v[46:47]
	global_load_dwordx4 v[34:37], v[102:103], off
	global_load_dwordx4 v[38:41], v[102:103], off offset:64
	v_lshl_add_u64 v[66:67], v[50:51], 0, v[152:153]
	global_load_dwordx4 v[42:45], v[102:103], off offset:512
	global_load_dwordx4 v[46:49], v[102:103], off offset:576
	global_load_dwordx4 v[50:53], v[66:67], off
	global_load_dwordx4 v[54:57], v[66:67], off offset:64
	global_load_dwordx4 v[58:61], v[66:67], off offset:512
	global_load_dwordx4 v[62:65], v[66:67], off offset:576
	s_waitcnt vmcnt(0)
	v_pk_fma_f32 v[32:33], v[32:33], v[144:145], v[36:37]
	v_pk_fma_f32 v[30:31], v[30:31], v[142:143], v[34:35]
	v_pk_fma_f32 v[28:29], v[28:29], v[136:137], v[40:41]
	v_pk_fma_f32 v[26:27], v[26:27], v[134:135], v[38:39]
	v_pk_fma_f32 v[16:17], v[16:17], v[132:133], v[44:45]
	v_pk_fma_f32 v[14:15], v[14:15], v[130:131], v[42:43]
	v_pk_fma_f32 v[12:13], v[12:13], v[140:141], v[48:49]
	v_pk_fma_f32 v[10:11], v[10:11], v[138:139], v[46:47]
	v_pk_fma_f32 v[24:25], v[24:25], v[144:145], v[52:53]
	v_pk_fma_f32 v[22:23], v[22:23], v[142:143], v[50:51]
	v_pk_fma_f32 v[20:21], v[20:21], v[136:137], v[56:57]
	v_pk_fma_f32 v[18:19], v[18:19], v[134:135], v[54:55]
	v_pk_fma_f32 v[8:9], v[8:9], v[132:133], v[60:61]
	v_pk_fma_f32 v[6:7], v[6:7], v[130:131], v[58:59]
	v_pk_fma_f32 v[4:5], v[4:5], v[140:141], v[64:65]
	v_pk_fma_f32 v[2:3], v[2:3], v[138:139], v[62:63]
	global_store_dwordx4 v[102:103], v[30:33], off
	global_store_dwordx4 v[102:103], v[26:29], off offset:64
	global_store_dwordx4 v[102:103], v[14:17], off offset:512
	global_store_dwordx4 v[102:103], v[10:13], off offset:576
	global_store_dwordx4 v[66:67], v[22:25], off
	global_store_dwordx4 v[66:67], v[18:21], off offset:64
	global_store_dwordx4 v[66:67], v[6:9], off offset:512
	global_store_dwordx4 v[66:67], v[2:5], off offset:576
	s_cbranch_vccz .LBB0_1348
	s_branch .LBB0_1356
